# GEMM K-loops: s_setprio 1 moved ahead of the pre-MMA s_barrier so the MMA wave is already prioritised at barrier release
# speedup vs baseline: 1.0050x; 1.0007x over previous
; #define PG8_STAGE(bufoff, gbase, voff) do { _Pragma("unroll") for (int _i = 0; _i < 2; ++_i) \
;         __builtin_amdgcn_global_load_lds((const unsigned*)((const char*)(gbase) + (voff)[_i]), (PG8_LAS unsigned*)(lds + (bufoff) + ldsw + _i * 8192), 16, 0, 0); } while (0)
; #define PG8_LDA(dst, b, h) do { _Pragma("unroll") for (int m = 0; m < 4; ++m) _Pragma("unroll") for (int k = 0; k < 2; ++k) dst[m][k] = *(const PG8_LAS bf16x8*)(lds + PG8_SA(b, h) + aoff + m * 2048 + k * 1024); } while (0)
; #define PG8_WAIT_V(n) asm volatile("s_waitcnt vmcnt(" #n ")" ::: "memory")
; #define PG8_WAIT_L(n) asm volatile("s_waitcnt lgkmcnt(" #n ")" ::: "memory")
; #define PG8_BAR __builtin_amdgcn_s_barrier()
; template <class Epi, class Sched, bool ALIGN_EPI = false, bool SP2 = false>
; __device__ __forceinline__ void gemm_phase(PG8_LAS unsigned char* lds, const Gemm g, const Sched& S, const Epi& E, const int wave0) {
;     ...
;         for (int t = 0; t < nt; t += 2) {
;             const bool last = (t == nt - 2);
;             const char* a1 = cA + (size_t)(t + 1) * kstep;
;             const char* a2 = last ? nA : cA + (size_t)(t + 2) * kstep; const char* b2 = last ? nB : cB + (size_t)(t + 2) * kstep;
;             const char* a3 = a2 + kstep; const char* b3 = b2 + kstep;
;             if (last && has_next) S.a_ready(nxt);
;             if constexpr (SP2) {
;             PG8_LDB(B0, 0, 0); PG8_LDB(B1, 0, 1); PG8_SCHED; PG8_LDA(At, 0, 0); PG8_STAGE(PG8_SA(1, 1), a1 + hstepA, voffA);
;             PG8_WAIT_V(8); PG8_WAIT_L(0); PG8_BAR; PG8_MMA(0, 0, At, B0); PG8_MMA(0, 1, At, B1); PG8_BAR; PG8_SCHED;
;             PG8_LDA(At, 0, 1); PG8_STAGE(PG8_SB(0, 0), b2, voffB); PG8_STAGE(PG8_SB(0, 1), b2 + hstepB, voffB); PG8_STAGE(PG8_SA(0, 0), a2, voffA);
;             PG8_WAIT_V(8); PG8_WAIT_L(0); PG8_BAR; PG8_MMA(1, 0, At, B0); PG8_MMA(1, 1, At, B1); PG8_BAR; PG8_SCHED;
;             PG8_LDB(B0, 1, 0); PG8_LDB(B1, 1, 1); PG8_SCHED; PG8_LDA(At, 1, 0); PG8_STAGE(PG8_SA(0, 1), a2 + hstepA, voffA);
;             PG8_WAIT_V(8); PG8_WAIT_L(0); PG8_BAR; PG8_MMA(0, 0, At, B0); PG8_MMA(0, 1, At, B1); PG8_BAR; PG8_SCHED;
;             PG8_LDA(At, 1, 1); PG8_STAGE(PG8_SB(1, 0), b3, voffB); PG8_STAGE(PG8_SB(1, 1), b3 + hstepB, voffB); PG8_STAGE(PG8_SA(1, 0), a3, voffA);
;             PG8_WAIT_V(8); PG8_WAIT_L(0); PG8_BAR; PG8_MMA(1, 0, At, B0); PG8_MMA(1, 1, At, B1); PG8_BAR; PG8_SCHED;
.LBB0_316:
	s_add_u32 s16, s0, 0xfff80080
	s_addc_u32 s17, s1, -1
	s_add_i32 s38, 0, 0x10000
	s_cmp_eq_u32 s37, 28
	s_cselect_b32 s19, s11, s17
	s_cselect_b32 s18, s33, s16
	s_cselect_b32 s17, s9, s36
	s_cselect_b32 s16, s34, s35
	s_add_i32 s40, 0, 0x14000
	ds_read_b128 v[144:147], v252
	ds_read_b128 v[148:151], v252 offset:1024
	ds_read_b128 v[152:155], v252 offset:2048
	ds_read_b128 v[156:159], v252 offset:3072
	ds_read_b128 v[178:181], v253
	ds_read_b128 v[182:185], v253 offset:1024
	ds_read_b128 v[186:189], v253 offset:2048
	ds_read_b128 v[190:193], v253 offset:3072
	s_add_i32 m0, s23, 0xc000
	ds_read_b128 v[194:197], v143
	ds_read_b128 v[208:211], v143 offset:1024
	ds_read_b128 v[212:215], v143 offset:2048
	ds_read_b128 v[216:219], v143 offset:3072
	ds_read_b128 v[220:223], v143 offset:4096
	ds_read_b128 v[224:227], v143 offset:5120
	ds_read_b128 v[228:231], v143 offset:6144
	ds_read_b128 v[232:235], v143 offset:7168
	global_load_lds_dwordx4 v136, s[0:1]
	s_add_i32 m0, s23, 0xe000
	s_nop 0
	global_load_lds_dwordx4 v138, s[0:1]
	s_waitcnt vmcnt(8)
	s_waitcnt lgkmcnt(0)
	s_setprio 1
	s_barrier
	s_waitcnt lgkmcnt(0)
	v_mfma_f32_16x16x32_bf16 v[126:129], v[144:147], v[194:197], v[126:129]
	v_mfma_f32_16x16x32_bf16 v[122:125], v[152:155], v[194:197], v[122:125]
	v_mfma_f32_16x16x32_bf16 v[118:121], v[144:147], v[212:215], v[118:121]
	v_mfma_f32_16x16x32_bf16 v[114:117], v[152:155], v[212:215], v[114:117]
	v_mfma_f32_16x16x32_bf16 v[102:105], v[144:147], v[220:223], v[102:105]
	v_mfma_f32_16x16x32_bf16 v[98:101], v[152:155], v[220:223], v[98:101]
	v_mfma_f32_16x16x32_bf16 v[86:89], v[144:147], v[228:231], v[86:89]
	v_mfma_f32_16x16x32_bf16 v[82:85], v[152:155], v[228:231], v[82:85]
	s_setprio 0
	s_setprio 1
	v_mfma_f32_16x16x32_bf16 v[126:129], v[148:151], v[208:211], v[126:129]
	v_mfma_f32_16x16x32_bf16 v[122:125], v[156:159], v[208:211], v[122:125]
	v_mfma_f32_16x16x32_bf16 v[118:121], v[148:151], v[216:219], v[118:121]
	v_mfma_f32_16x16x32_bf16 v[114:117], v[156:159], v[216:219], v[114:117]
	v_mfma_f32_16x16x32_bf16 v[102:105], v[148:151], v[224:227], v[102:105]
	v_mfma_f32_16x16x32_bf16 v[98:101], v[156:159], v[224:227], v[98:101]
	v_mfma_f32_16x16x32_bf16 v[86:89], v[148:151], v[232:235], v[86:89]
	v_mfma_f32_16x16x32_bf16 v[82:85], v[156:159], v[232:235], v[82:85]
	s_setprio 0
	s_setprio 1
	v_mfma_f32_16x16x32_bf16 v[110:113], v[178:181], v[194:197], v[110:113]
	v_mfma_f32_16x16x32_bf16 v[106:109], v[186:189], v[194:197], v[106:109]
	v_mfma_f32_16x16x32_bf16 v[94:97], v[178:181], v[212:215], v[94:97]
	v_mfma_f32_16x16x32_bf16 v[90:93], v[186:189], v[212:215], v[90:93]
	v_mfma_f32_16x16x32_bf16 v[78:81], v[178:181], v[220:223], v[78:81]
	v_mfma_f32_16x16x32_bf16 v[74:77], v[186:189], v[220:223], v[74:77]
	v_mfma_f32_16x16x32_bf16 v[70:73], v[178:181], v[228:231], v[70:73]
	v_mfma_f32_16x16x32_bf16 v[66:69], v[186:189], v[228:231], v[66:69]
	s_setprio 0
	s_setprio 1
	v_mfma_f32_16x16x32_bf16 v[110:113], v[182:185], v[208:211], v[110:113]
	v_mfma_f32_16x16x32_bf16 v[106:109], v[190:193], v[208:211], v[106:109]
	v_mfma_f32_16x16x32_bf16 v[94:97], v[182:185], v[216:219], v[94:97]
	v_mfma_f32_16x16x32_bf16 v[90:93], v[190:193], v[216:219], v[90:93]
	v_mfma_f32_16x16x32_bf16 v[78:81], v[182:185], v[224:227], v[78:81]
	v_mfma_f32_16x16x32_bf16 v[74:77], v[190:193], v[224:227], v[74:77]
	v_mfma_f32_16x16x32_bf16 v[70:73], v[182:185], v[232:235], v[70:73]
	v_mfma_f32_16x16x32_bf16 v[66:69], v[190:193], v[232:235], v[66:69]
	s_setprio 0
	s_barrier
	s_add_i32 s38, s38, s22
	s_mov_b32 m0, s38
	ds_read_b128 v[194:197], v143 offset:16384
	ds_read_b128 v[208:211], v143 offset:17408
	ds_read_b128 v[212:215], v143 offset:18432
	ds_read_b128 v[216:219], v143 offset:19456
	ds_read_b128 v[220:223], v143 offset:20480
	ds_read_b128 v[224:227], v143 offset:21504
	ds_read_b128 v[228:231], v143 offset:22528
	ds_read_b128 v[232:235], v143 offset:23552
	global_load_lds_dwordx4 v64, s[16:17]
	s_add_i32 m0, s38, 0x2000
	s_add_u32 s38, s16, 0x80000
	s_addc_u32 s39, s17, 0
	s_add_i32 s40, s40, s22
	global_load_lds_dwordx4 v130, s[16:17]
	s_mov_b32 m0, s40
	s_mov_b64 s[100:101], s[18:19]
	global_load_lds_dwordx4 v64, s[38:39]
	s_add_i32 m0, s40, 0x2000
	s_nop 0
	global_load_lds_dwordx4 v130, s[38:39]
	s_mov_b32 m0, s23
	s_nop 0
	global_load_lds_dwordx4 v134, s[18:19]
	s_mov_b32 m0, s24
	s_nop 0
	global_load_lds_dwordx4 v132, s[18:19]
	s_waitcnt vmcnt(8)
	s_waitcnt lgkmcnt(0)
	s_setprio 1
	s_barrier
	s_waitcnt lgkmcnt(0)
	v_mfma_f32_16x16x32_bf16 v[60:63], v[144:147], v[194:197], v[60:63]
	v_mfma_f32_16x16x32_bf16 v[56:59], v[152:155], v[194:197], v[56:59]
	v_mfma_f32_16x16x32_bf16 v[52:55], v[144:147], v[212:215], v[52:55]
	v_mfma_f32_16x16x32_bf16 v[48:51], v[152:155], v[212:215], v[48:51]
	v_mfma_f32_16x16x32_bf16 v[36:39], v[144:147], v[220:223], v[36:39]
	v_mfma_f32_16x16x32_bf16 v[32:35], v[152:155], v[220:223], v[32:35]
	v_mfma_f32_16x16x32_bf16 v[20:23], v[144:147], v[228:231], v[20:23]
	v_mfma_f32_16x16x32_bf16 v[16:19], v[152:155], v[228:231], v[16:19]
	s_setprio 0
	s_setprio 1
	v_mfma_f32_16x16x32_bf16 v[60:63], v[148:151], v[208:211], v[60:63]
	v_mfma_f32_16x16x32_bf16 v[56:59], v[156:159], v[208:211], v[56:59]
	v_mfma_f32_16x16x32_bf16 v[52:55], v[148:151], v[216:219], v[52:55]
	v_mfma_f32_16x16x32_bf16 v[48:51], v[156:159], v[216:219], v[48:51]
	v_mfma_f32_16x16x32_bf16 v[36:39], v[148:151], v[224:227], v[36:39]
	v_mfma_f32_16x16x32_bf16 v[32:35], v[156:159], v[224:227], v[32:35]
	v_mfma_f32_16x16x32_bf16 v[20:23], v[148:151], v[232:235], v[20:23]
	v_mfma_f32_16x16x32_bf16 v[16:19], v[156:159], v[232:235], v[16:19]
	s_setprio 0
	s_setprio 1
	v_mfma_f32_16x16x32_bf16 v[44:47], v[178:181], v[194:197], v[44:47]
	v_mfma_f32_16x16x32_bf16 v[40:43], v[186:189], v[194:197], v[40:43]
	v_mfma_f32_16x16x32_bf16 v[28:31], v[178:181], v[212:215], v[28:31]
	v_mfma_f32_16x16x32_bf16 v[24:27], v[186:189], v[212:215], v[24:27]
	v_mfma_f32_16x16x32_bf16 v[12:15], v[178:181], v[220:223], v[12:15]
	v_mfma_f32_16x16x32_bf16 v[8:11], v[186:189], v[220:223], v[8:11]
	v_mfma_f32_16x16x32_bf16 v[4:7], v[178:181], v[228:231], v[4:7]
	v_mfma_f32_16x16x32_bf16 v[0:3], v[186:189], v[228:231], v[0:3]
	s_setprio 0
	s_setprio 1
	v_mfma_f32_16x16x32_bf16 v[44:47], v[182:185], v[208:211], v[44:47]
	v_mfma_f32_16x16x32_bf16 v[40:43], v[190:193], v[208:211], v[40:43]
	v_mfma_f32_16x16x32_bf16 v[28:31], v[182:185], v[216:219], v[28:31]
	v_mfma_f32_16x16x32_bf16 v[24:27], v[190:193], v[216:219], v[24:27]
	v_mfma_f32_16x16x32_bf16 v[12:15], v[182:185], v[224:227], v[12:15]
	v_mfma_f32_16x16x32_bf16 v[8:11], v[190:193], v[224:227], v[8:11]
	v_mfma_f32_16x16x32_bf16 v[4:7], v[182:185], v[232:235], v[4:7]
	v_mfma_f32_16x16x32_bf16 v[0:3], v[190:193], v[232:235], v[0:3]
	s_setprio 0
	s_barrier
; #define PG8_STAGE(bufoff, gbase, voff) do { _Pragma("unroll") for (int _i = 0; _i < 2; ++_i) \
;         __builtin_amdgcn_global_load_lds((const unsigned*)((const char*)(gbase) + (voff)[_i]), (PG8_LAS unsigned*)(lds + (bufoff) + ldsw + _i * 8192), 16, 0, 0); } while (0)
; #define PG8_LDA(dst, b, h) do { _Pragma("unroll") for (int m = 0; m < 4; ++m) _Pragma("unroll") for (int k = 0; k < 2; ++k) dst[m][k] = *(const PG8_LAS bf16x8*)(lds + PG8_SA(b, h) + aoff + m * 2048 + k * 1024); } while (0)
; #define PG8_WAIT_V(n) asm volatile("s_waitcnt vmcnt(" #n ")" ::: "memory")
; #define PG8_WAIT_L(n) asm volatile("s_waitcnt lgkmcnt(" #n ")" ::: "memory")
; #define PG8_BAR __builtin_amdgcn_s_barrier()
; template <class Epi, class Sched, bool ALIGN_EPI = false, bool SP2 = false>
; __device__ __forceinline__ void gemm_phase(PG8_LAS unsigned char* lds, const Gemm g, const Sched& S, const Epi& E, const int wave0) {
;     ...
;         for (int t = 0; t < nt; t += 2) {
;             const bool last = (t == nt - 2);
;             const char* a1 = cA + (size_t)(t + 1) * kstep;
;             const char* a2 = last ? nA : cA + (size_t)(t + 2) * kstep; const char* b2 = last ? nB : cB + (size_t)(t + 2) * kstep;
;             const char* a3 = a2 + kstep; const char* b3 = b2 + kstep;
;             if (last && has_next) S.a_ready(nxt);
;             if constexpr (SP2) {
;             PG8_LDB(B0, 0, 0); PG8_LDB(B1, 0, 1); PG8_SCHED; PG8_LDA(At, 0, 0); PG8_STAGE(PG8_SA(1, 1), a1 + hstepA, voffA);
;             PG8_WAIT_V(8); PG8_WAIT_L(0); PG8_BAR; PG8_MMA(0, 0, At, B0); PG8_MMA(0, 1, At, B1); PG8_BAR; PG8_SCHED;
;             PG8_LDA(At, 0, 1); PG8_STAGE(PG8_SB(0, 0), b2, voffB); PG8_STAGE(PG8_SB(0, 1), b2 + hstepB, voffB); PG8_STAGE(PG8_SA(0, 0), a2, voffA);
;             PG8_WAIT_V(8); PG8_WAIT_L(0); PG8_BAR; PG8_MMA(1, 0, At, B0); PG8_MMA(1, 1, At, B1); PG8_BAR; PG8_SCHED;
;             PG8_LDB(B0, 1, 0); PG8_LDB(B1, 1, 1); PG8_SCHED; PG8_LDA(At, 1, 0); PG8_STAGE(PG8_SA(0, 1), a2 + hstepA, voffA);
;             PG8_WAIT_V(8); PG8_WAIT_L(0); PG8_BAR; PG8_MMA(0, 0, At, B0); PG8_MMA(0, 1, At, B1); PG8_BAR; PG8_SCHED;
;             PG8_LDA(At, 1, 1); PG8_STAGE(PG8_SB(1, 0), b3, voffB); PG8_STAGE(PG8_SB(1, 1), b3 + hstepB, voffB); PG8_STAGE(PG8_SA(1, 0), a3, voffA);
;             PG8_WAIT_V(8); PG8_WAIT_L(0); PG8_BAR; PG8_MMA(1, 0, At, B0); PG8_MMA(1, 1, At, B1); PG8_BAR; PG8_SCHED;
	s_add_i32 s38, 0, 0x18000
	s_add_i32 s39, 0, 0x1c000
	ds_read_b128 v[144:147], v254
	ds_read_b128 v[148:151], v254 offset:1024
	ds_read_b128 v[152:155], v254 offset:2048
	ds_read_b128 v[156:159], v254 offset:3072
	ds_read_b128 v[178:181], v255
	ds_read_b128 v[182:185], v255 offset:1024
	ds_read_b128 v[186:189], v255 offset:2048
	ds_read_b128 v[190:193], v255 offset:3072
	s_add_u32 s18, s18, 0x80000
	s_addc_u32 s19, s19, 0
	s_mov_b32 m0, s25
	ds_read_b128 v[194:197], v143 offset:32768
	ds_read_b128 v[208:211], v143 offset:33792
	ds_read_b128 v[212:215], v143 offset:34816
	ds_read_b128 v[216:219], v143 offset:35840
	ds_read_b128 v[220:223], v143 offset:36864
	ds_read_b128 v[224:227], v143 offset:37888
	ds_read_b128 v[228:231], v143 offset:38912
	ds_read_b128 v[232:235], v143 offset:39936
	global_load_lds_dwordx4 v134, s[18:19]
	s_mov_b32 m0, s26
	s_nop 0
	global_load_lds_dwordx4 v132, s[18:19]
	s_waitcnt vmcnt(8)
	s_waitcnt lgkmcnt(0)
	s_setprio 1
	s_barrier
	s_waitcnt lgkmcnt(0)
	v_mfma_f32_16x16x32_bf16 v[126:129], v[144:147], v[194:197], v[126:129]
	v_mfma_f32_16x16x32_bf16 v[122:125], v[152:155], v[194:197], v[122:125]
	v_mfma_f32_16x16x32_bf16 v[118:121], v[144:147], v[212:215], v[118:121]
	v_mfma_f32_16x16x32_bf16 v[114:117], v[152:155], v[212:215], v[114:117]
	v_mfma_f32_16x16x32_bf16 v[102:105], v[144:147], v[220:223], v[102:105]
	v_mfma_f32_16x16x32_bf16 v[98:101], v[152:155], v[220:223], v[98:101]
	v_mfma_f32_16x16x32_bf16 v[86:89], v[144:147], v[228:231], v[86:89]
	v_mfma_f32_16x16x32_bf16 v[82:85], v[152:155], v[228:231], v[82:85]
	s_setprio 0
	s_setprio 1
	v_mfma_f32_16x16x32_bf16 v[126:129], v[148:151], v[208:211], v[126:129]
	v_mfma_f32_16x16x32_bf16 v[122:125], v[156:159], v[208:211], v[122:125]
	v_mfma_f32_16x16x32_bf16 v[118:121], v[148:151], v[216:219], v[118:121]
	v_mfma_f32_16x16x32_bf16 v[114:117], v[156:159], v[216:219], v[114:117]
	v_mfma_f32_16x16x32_bf16 v[102:105], v[148:151], v[224:227], v[102:105]
	v_mfma_f32_16x16x32_bf16 v[98:101], v[156:159], v[224:227], v[98:101]
	v_mfma_f32_16x16x32_bf16 v[86:89], v[148:151], v[232:235], v[86:89]
	v_mfma_f32_16x16x32_bf16 v[82:85], v[156:159], v[232:235], v[82:85]
	s_setprio 0
	s_setprio 1
	v_mfma_f32_16x16x32_bf16 v[110:113], v[178:181], v[194:197], v[110:113]
	v_mfma_f32_16x16x32_bf16 v[106:109], v[186:189], v[194:197], v[106:109]
	v_mfma_f32_16x16x32_bf16 v[94:97], v[178:181], v[212:215], v[94:97]
	v_mfma_f32_16x16x32_bf16 v[90:93], v[186:189], v[212:215], v[90:93]
	v_mfma_f32_16x16x32_bf16 v[78:81], v[178:181], v[220:223], v[78:81]
	v_mfma_f32_16x16x32_bf16 v[74:77], v[186:189], v[220:223], v[74:77]
	v_mfma_f32_16x16x32_bf16 v[70:73], v[178:181], v[228:231], v[70:73]
	v_mfma_f32_16x16x32_bf16 v[66:69], v[186:189], v[228:231], v[66:69]
	s_setprio 0
	s_setprio 1
	v_mfma_f32_16x16x32_bf16 v[110:113], v[182:185], v[208:211], v[110:113]
	v_mfma_f32_16x16x32_bf16 v[106:109], v[190:193], v[208:211], v[106:109]
	v_mfma_f32_16x16x32_bf16 v[94:97], v[182:185], v[216:219], v[94:97]
	v_mfma_f32_16x16x32_bf16 v[90:93], v[190:193], v[216:219], v[90:93]
	v_mfma_f32_16x16x32_bf16 v[78:81], v[182:185], v[224:227], v[78:81]
	v_mfma_f32_16x16x32_bf16 v[74:77], v[190:193], v[224:227], v[74:77]
	v_mfma_f32_16x16x32_bf16 v[70:73], v[182:185], v[232:235], v[70:73]
	v_mfma_f32_16x16x32_bf16 v[66:69], v[190:193], v[232:235], v[66:69]
	s_setprio 0
	s_barrier
	s_add_i32 s18, s38, s22
	s_add_u32 s42, s16, 0x80
	s_addc_u32 s43, s17, 0
	s_mov_b32 m0, s18
	ds_read_b128 v[194:197], v143 offset:49152
	ds_read_b128 v[208:211], v143 offset:50176
	ds_read_b128 v[212:215], v143 offset:51200
	ds_read_b128 v[216:219], v143 offset:52224
	ds_read_b128 v[220:223], v143 offset:53248
	ds_read_b128 v[224:227], v143 offset:54272
	ds_read_b128 v[228:231], v143 offset:55296
	ds_read_b128 v[232:235], v143 offset:56320
	global_load_lds_dwordx4 v64, s[42:43]
	s_add_i32 m0, s18, 0x2000
	s_add_u32 s16, s16, 0x80080
	s_addc_u32 s17, s17, 0
	s_add_i32 s18, s39, s22
	global_load_lds_dwordx4 v130, s[42:43]
	s_mov_b32 m0, s18
	s_nop 0
	global_load_lds_dwordx4 v64, s[16:17]
	s_add_i32 m0, s18, 0x2000
	s_nop 0
	global_load_lds_dwordx4 v130, s[16:17]
	s_add_u32 s100, s100, 0x80
	s_addc_u32 s101, s101, 0
	s_mov_b32 m0, s27
	s_nop 0
	global_load_lds_dwordx4 v134, s[100:101]
	s_mov_b32 m0, s28
	s_nop 0
	global_load_lds_dwordx4 v132, s[100:101]
	s_waitcnt vmcnt(8)
	s_waitcnt lgkmcnt(0)
	s_setprio 1
	s_barrier
	s_waitcnt lgkmcnt(0)
	v_mfma_f32_16x16x32_bf16 v[60:63], v[144:147], v[194:197], v[60:63]
	v_mfma_f32_16x16x32_bf16 v[56:59], v[152:155], v[194:197], v[56:59]
	v_mfma_f32_16x16x32_bf16 v[52:55], v[144:147], v[212:215], v[52:55]
	v_mfma_f32_16x16x32_bf16 v[48:51], v[152:155], v[212:215], v[48:51]
	v_mfma_f32_16x16x32_bf16 v[36:39], v[144:147], v[220:223], v[36:39]
	v_mfma_f32_16x16x32_bf16 v[32:35], v[152:155], v[220:223], v[32:35]
	v_mfma_f32_16x16x32_bf16 v[20:23], v[144:147], v[228:231], v[20:23]
	v_mfma_f32_16x16x32_bf16 v[16:19], v[152:155], v[228:231], v[16:19]
	s_setprio 0
	s_setprio 1
	v_mfma_f32_16x16x32_bf16 v[60:63], v[148:151], v[208:211], v[60:63]
	v_mfma_f32_16x16x32_bf16 v[56:59], v[156:159], v[208:211], v[56:59]
	v_mfma_f32_16x16x32_bf16 v[52:55], v[148:151], v[216:219], v[52:55]
	v_mfma_f32_16x16x32_bf16 v[48:51], v[156:159], v[216:219], v[48:51]
	v_mfma_f32_16x16x32_bf16 v[36:39], v[148:151], v[224:227], v[36:39]
	v_mfma_f32_16x16x32_bf16 v[32:35], v[156:159], v[224:227], v[32:35]
	v_mfma_f32_16x16x32_bf16 v[20:23], v[148:151], v[232:235], v[20:23]
	v_mfma_f32_16x16x32_bf16 v[16:19], v[156:159], v[232:235], v[16:19]
	s_setprio 0
	s_setprio 1
	v_mfma_f32_16x16x32_bf16 v[44:47], v[178:181], v[194:197], v[44:47]
	v_mfma_f32_16x16x32_bf16 v[40:43], v[186:189], v[194:197], v[40:43]
	v_mfma_f32_16x16x32_bf16 v[28:31], v[178:181], v[212:215], v[28:31]
	v_mfma_f32_16x16x32_bf16 v[24:27], v[186:189], v[212:215], v[24:27]
	v_mfma_f32_16x16x32_bf16 v[12:15], v[178:181], v[220:223], v[12:15]
	v_mfma_f32_16x16x32_bf16 v[8:11], v[186:189], v[220:223], v[8:11]
	v_mfma_f32_16x16x32_bf16 v[4:7], v[178:181], v[228:231], v[4:7]
	v_mfma_f32_16x16x32_bf16 v[0:3], v[186:189], v[228:231], v[0:3]
	s_setprio 0
	s_setprio 1
	v_mfma_f32_16x16x32_bf16 v[44:47], v[182:185], v[208:211], v[44:47]
	v_mfma_f32_16x16x32_bf16 v[40:43], v[190:193], v[208:211], v[40:43]
	v_mfma_f32_16x16x32_bf16 v[28:31], v[182:185], v[216:219], v[28:31]
	v_mfma_f32_16x16x32_bf16 v[24:27], v[190:193], v[216:219], v[24:27]
	v_mfma_f32_16x16x32_bf16 v[12:15], v[182:185], v[224:227], v[12:15]
	v_mfma_f32_16x16x32_bf16 v[8:11], v[190:193], v[224:227], v[8:11]
	v_mfma_f32_16x16x32_bf16 v[4:7], v[182:185], v[232:235], v[4:7]
	v_mfma_f32_16x16x32_bf16 v[0:3], v[190:193], v[232:235], v[0:3]
	s_setprio 0
	s_barrier
	s_add_i32 s37, s37, 2
	s_add_u32 s0, s0, 0x100
	s_addc_u32 s1, s1, 0
	s_add_u32 s35, s35, 0x100
	s_addc_u32 s36, s36, 0
	s_cmp_gt_u32 s37, 29
	s_cbranch_scc0 .LBB0_316
	s_mov_b64 s[42:43], 0x80
	s_and_b64 vcc, exec, s[6:7]
	s_mov_b64 s[34:35], 0x45000
	s_cbranch_vccz .LBB0_319
	s_barrier

; #define PG8_STAGE(bufoff, gbase, voff) do { _Pragma("unroll") for (int _i = 0; _i < 2; ++_i) \
;         __builtin_amdgcn_global_load_lds((const unsigned*)((const char*)(gbase) + (voff)[_i]), (PG8_LAS unsigned*)(lds + (bufoff) + ldsw + _i * 8192), 16, 0, 0); } while (0)
; #define PG8_LDA(dst, b, h) do { _Pragma("unroll") for (int m = 0; m < 4; ++m) _Pragma("unroll") for (int k = 0; k < 2; ++k) dst[m][k] = *(const PG8_LAS bf16x8*)(lds + PG8_SA(b, h) + aoff + m * 2048 + k * 1024); } while (0)
; #define PG8_WAIT_V(n) asm volatile("s_waitcnt vmcnt(" #n ")" ::: "memory")
; #define PG8_WAIT_L(n) asm volatile("s_waitcnt lgkmcnt(" #n ")" ::: "memory")
; #define PG8_BAR __builtin_amdgcn_s_barrier()
; template <class Epi, class Sched, bool ALIGN_EPI = false, bool SP2 = false>
; __device__ __forceinline__ void gemm_phase(PG8_LAS unsigned char* lds, const Gemm g, const Sched& S, const Epi& E, const int wave0) {
;     ...
;         for (int t = 0; t < nt; t += 2) {
;             const bool last = (t == nt - 2);
;             const char* a1 = cA + (size_t)(t + 1) * kstep;
;             const char* a2 = last ? nA : cA + (size_t)(t + 2) * kstep; const char* b2 = last ? nB : cB + (size_t)(t + 2) * kstep;
;             const char* a3 = a2 + kstep; const char* b3 = b2 + kstep;
;             if (last && has_next) S.a_ready(nxt);
;             if constexpr (SP2) {
;             PG8_LDB(B0, 0, 0); PG8_LDB(B1, 0, 1); PG8_SCHED; PG8_LDA(At, 0, 0); PG8_STAGE(PG8_SA(1, 1), a1 + hstepA, voffA);
;             PG8_WAIT_V(8); PG8_WAIT_L(0); PG8_BAR; PG8_MMA(0, 0, At, B0); PG8_MMA(0, 1, At, B1); PG8_BAR; PG8_SCHED;
;             PG8_LDA(At, 0, 1); PG8_STAGE(PG8_SB(0, 0), b2, voffB); PG8_STAGE(PG8_SB(0, 1), b2 + hstepB, voffB); PG8_STAGE(PG8_SA(0, 0), a2, voffA);
;             PG8_WAIT_V(8); PG8_WAIT_L(0); PG8_BAR; PG8_MMA(1, 0, At, B0); PG8_MMA(1, 1, At, B1); PG8_BAR; PG8_SCHED;
;             PG8_LDB(B0, 1, 0); PG8_LDB(B1, 1, 1); PG8_SCHED; PG8_LDA(At, 1, 0); PG8_STAGE(PG8_SA(0, 1), a2 + hstepA, voffA);
;             PG8_WAIT_V(8); PG8_WAIT_L(0); PG8_BAR; PG8_MMA(0, 0, At, B0); PG8_MMA(0, 1, At, B1); PG8_BAR; PG8_SCHED;
;             PG8_LDA(At, 1, 1); PG8_STAGE(PG8_SB(1, 0), b3, voffB); PG8_STAGE(PG8_SB(1, 1), b3 + hstepB, voffB); PG8_STAGE(PG8_SA(1, 0), a3, voffA);
;             PG8_WAIT_V(8); PG8_WAIT_L(0); PG8_BAR; PG8_MMA(1, 0, At, B0); PG8_MMA(1, 1, At, B1); PG8_BAR; PG8_SCHED;
.LBB0_1178:
	s_add_u32 s2, s0, 0xfffc0080
	s_addc_u32 s3, s1, -1
	s_add_i32 s31, 0, 0x10000
	s_cmp_eq_u32 s19, 12
	s_cselect_b32 s17, s45, s3
	s_cselect_b32 s16, s44, s2
	s_cselect_b32 s3, s9, s18
	s_cselect_b32 s2, s11, s13
	s_add_i32 s33, 0, 0x14000
	ds_read_b128 v[130:133], v252
	ds_read_b128 v[134:137], v252 offset:1024
	ds_read_b128 v[148:151], v252 offset:2048
	ds_read_b128 v[152:155], v252 offset:3072
	ds_read_b128 v[178:181], v253
	ds_read_b128 v[182:185], v253 offset:1024
	ds_read_b128 v[186:189], v253 offset:2048
	ds_read_b128 v[190:193], v253 offset:3072
	s_add_i32 m0, s23, 0xc000
	ds_read_b128 v[194:197], v159
	ds_read_b128 v[208:211], v159 offset:1024
	ds_read_b128 v[212:215], v159 offset:2048
	ds_read_b128 v[216:219], v159 offset:3072
	ds_read_b128 v[220:223], v159 offset:4096
	ds_read_b128 v[224:227], v159 offset:5120
	ds_read_b128 v[228:231], v159 offset:6144
	ds_read_b128 v[232:235], v159 offset:7168
	global_load_lds_dwordx4 v144, s[0:1]
	s_add_i32 m0, s23, 0xe000
	s_nop 0
	global_load_lds_dwordx4 v146, s[0:1]
	s_waitcnt vmcnt(8)
	s_waitcnt lgkmcnt(0)
	s_setprio 1
	s_barrier
	s_waitcnt lgkmcnt(0)
	v_mfma_f32_16x16x32_bf16 v[126:129], v[130:133], v[194:197], v[126:129]
	v_mfma_f32_16x16x32_bf16 v[122:125], v[148:151], v[194:197], v[122:125]
	v_mfma_f32_16x16x32_bf16 v[110:113], v[130:133], v[212:215], v[110:113]
	v_mfma_f32_16x16x32_bf16 v[106:109], v[148:151], v[212:215], v[106:109]
	v_mfma_f32_16x16x32_bf16 v[94:97], v[130:133], v[220:223], v[94:97]
	v_mfma_f32_16x16x32_bf16 v[90:93], v[148:151], v[220:223], v[90:93]
	v_mfma_f32_16x16x32_bf16 v[78:81], v[130:133], v[228:231], v[78:81]
	v_mfma_f32_16x16x32_bf16 v[74:77], v[148:151], v[228:231], v[74:77]
	s_setprio 0
	s_setprio 1
	v_mfma_f32_16x16x32_bf16 v[126:129], v[134:137], v[208:211], v[126:129]
	v_mfma_f32_16x16x32_bf16 v[122:125], v[152:155], v[208:211], v[122:125]
	v_mfma_f32_16x16x32_bf16 v[110:113], v[134:137], v[216:219], v[110:113]
	v_mfma_f32_16x16x32_bf16 v[106:109], v[152:155], v[216:219], v[106:109]
	v_mfma_f32_16x16x32_bf16 v[94:97], v[134:137], v[224:227], v[94:97]
	v_mfma_f32_16x16x32_bf16 v[90:93], v[152:155], v[224:227], v[90:93]
	v_mfma_f32_16x16x32_bf16 v[78:81], v[134:137], v[232:235], v[78:81]
	v_mfma_f32_16x16x32_bf16 v[74:77], v[152:155], v[232:235], v[74:77]
	s_setprio 0
	s_setprio 1
	v_mfma_f32_16x16x32_bf16 v[118:121], v[178:181], v[194:197], v[118:121]
	v_mfma_f32_16x16x32_bf16 v[114:117], v[186:189], v[194:197], v[114:117]
	v_mfma_f32_16x16x32_bf16 v[102:105], v[178:181], v[212:215], v[102:105]
	v_mfma_f32_16x16x32_bf16 v[98:101], v[186:189], v[212:215], v[98:101]
	v_mfma_f32_16x16x32_bf16 v[86:89], v[178:181], v[220:223], v[86:89]
	v_mfma_f32_16x16x32_bf16 v[82:85], v[186:189], v[220:223], v[82:85]
	v_mfma_f32_16x16x32_bf16 v[70:73], v[178:181], v[228:231], v[70:73]
	v_mfma_f32_16x16x32_bf16 v[66:69], v[186:189], v[228:231], v[66:69]
	s_setprio 0
	s_setprio 1
	v_mfma_f32_16x16x32_bf16 v[118:121], v[182:185], v[208:211], v[118:121]
	v_mfma_f32_16x16x32_bf16 v[114:117], v[190:193], v[208:211], v[114:117]
	v_mfma_f32_16x16x32_bf16 v[102:105], v[182:185], v[216:219], v[102:105]
	v_mfma_f32_16x16x32_bf16 v[98:101], v[190:193], v[216:219], v[98:101]
	v_mfma_f32_16x16x32_bf16 v[86:89], v[182:185], v[224:227], v[86:89]
	v_mfma_f32_16x16x32_bf16 v[82:85], v[190:193], v[224:227], v[82:85]
	v_mfma_f32_16x16x32_bf16 v[70:73], v[182:185], v[232:235], v[70:73]
	v_mfma_f32_16x16x32_bf16 v[66:69], v[190:193], v[232:235], v[66:69]
	s_setprio 0
	s_barrier
	s_add_i32 s31, s31, s22
	s_mov_b32 m0, s31
	ds_read_b128 v[194:197], v159 offset:16384
	ds_read_b128 v[208:211], v159 offset:17408
	ds_read_b128 v[212:215], v159 offset:18432
	ds_read_b128 v[216:219], v159 offset:19456
	ds_read_b128 v[220:223], v159 offset:20480
	ds_read_b128 v[224:227], v159 offset:21504
	ds_read_b128 v[228:231], v159 offset:22528
	ds_read_b128 v[232:235], v159 offset:23552
	global_load_lds_dwordx4 v64, s[2:3]
	s_add_i32 m0, s31, 0x2000
	s_add_u32 s34, s2, 0x40000
	s_addc_u32 s35, s3, 0
	s_add_i32 s31, s33, s22
	global_load_lds_dwordx4 v138, s[2:3]
	s_mov_b32 m0, s31
	s_mov_b64 s[100:101], s[16:17]
	global_load_lds_dwordx4 v64, s[34:35]
	s_add_i32 m0, s31, 0x2000
	s_nop 0
	global_load_lds_dwordx4 v138, s[34:35]
	s_mov_b32 m0, s23
	s_nop 0
	global_load_lds_dwordx4 v142, s[16:17]
	s_mov_b32 m0, s24
	s_nop 0
	global_load_lds_dwordx4 v140, s[16:17]
	s_waitcnt vmcnt(8)
	s_waitcnt lgkmcnt(0)
	s_setprio 1
	s_barrier
	s_waitcnt lgkmcnt(0)
	v_mfma_f32_16x16x32_bf16 v[60:63], v[130:133], v[194:197], v[60:63]
	v_mfma_f32_16x16x32_bf16 v[56:59], v[148:151], v[194:197], v[56:59]
	v_mfma_f32_16x16x32_bf16 v[44:47], v[130:133], v[212:215], v[44:47]
	v_mfma_f32_16x16x32_bf16 v[40:43], v[148:151], v[212:215], v[40:43]
	v_mfma_f32_16x16x32_bf16 v[28:31], v[130:133], v[220:223], v[28:31]
	v_mfma_f32_16x16x32_bf16 v[24:27], v[148:151], v[220:223], v[24:27]
	v_mfma_f32_16x16x32_bf16 v[12:15], v[130:133], v[228:231], v[12:15]
	v_mfma_f32_16x16x32_bf16 v[8:11], v[148:151], v[228:231], v[8:11]
	s_setprio 0
	s_setprio 1
	v_mfma_f32_16x16x32_bf16 v[60:63], v[134:137], v[208:211], v[60:63]
	v_mfma_f32_16x16x32_bf16 v[56:59], v[152:155], v[208:211], v[56:59]
	v_mfma_f32_16x16x32_bf16 v[44:47], v[134:137], v[216:219], v[44:47]
	v_mfma_f32_16x16x32_bf16 v[40:43], v[152:155], v[216:219], v[40:43]
	v_mfma_f32_16x16x32_bf16 v[28:31], v[134:137], v[224:227], v[28:31]
	v_mfma_f32_16x16x32_bf16 v[24:27], v[152:155], v[224:227], v[24:27]
	v_mfma_f32_16x16x32_bf16 v[12:15], v[134:137], v[232:235], v[12:15]
	v_mfma_f32_16x16x32_bf16 v[8:11], v[152:155], v[232:235], v[8:11]
	s_setprio 0
	s_setprio 1
	v_mfma_f32_16x16x32_bf16 v[52:55], v[178:181], v[194:197], v[52:55]
	v_mfma_f32_16x16x32_bf16 v[48:51], v[186:189], v[194:197], v[48:51]
	v_mfma_f32_16x16x32_bf16 v[36:39], v[178:181], v[212:215], v[36:39]
	v_mfma_f32_16x16x32_bf16 v[32:35], v[186:189], v[212:215], v[32:35]
	v_mfma_f32_16x16x32_bf16 v[20:23], v[178:181], v[220:223], v[20:23]
	v_mfma_f32_16x16x32_bf16 v[16:19], v[186:189], v[220:223], v[16:19]
	v_mfma_f32_16x16x32_bf16 v[4:7], v[178:181], v[228:231], v[4:7]
	v_mfma_f32_16x16x32_bf16 v[0:3], v[186:189], v[228:231], v[0:3]
	s_setprio 0
	s_setprio 1
	v_mfma_f32_16x16x32_bf16 v[52:55], v[182:185], v[208:211], v[52:55]
	v_mfma_f32_16x16x32_bf16 v[48:51], v[190:193], v[208:211], v[48:51]
	v_mfma_f32_16x16x32_bf16 v[36:39], v[182:185], v[216:219], v[36:39]
	v_mfma_f32_16x16x32_bf16 v[32:35], v[190:193], v[216:219], v[32:35]
	v_mfma_f32_16x16x32_bf16 v[20:23], v[182:185], v[224:227], v[20:23]
	v_mfma_f32_16x16x32_bf16 v[16:19], v[190:193], v[224:227], v[16:19]
	v_mfma_f32_16x16x32_bf16 v[4:7], v[182:185], v[232:235], v[4:7]
	v_mfma_f32_16x16x32_bf16 v[0:3], v[190:193], v[232:235], v[0:3]
	s_setprio 0
	s_barrier
; #define PG8_STAGE(bufoff, gbase, voff) do { _Pragma("unroll") for (int _i = 0; _i < 2; ++_i) \
;         __builtin_amdgcn_global_load_lds((const unsigned*)((const char*)(gbase) + (voff)[_i]), (PG8_LAS unsigned*)(lds + (bufoff) + ldsw + _i * 8192), 16, 0, 0); } while (0)
; #define PG8_LDA(dst, b, h) do { _Pragma("unroll") for (int m = 0; m < 4; ++m) _Pragma("unroll") for (int k = 0; k < 2; ++k) dst[m][k] = *(const PG8_LAS bf16x8*)(lds + PG8_SA(b, h) + aoff + m * 2048 + k * 1024); } while (0)
; #define PG8_WAIT_V(n) asm volatile("s_waitcnt vmcnt(" #n ")" ::: "memory")
; #define PG8_WAIT_L(n) asm volatile("s_waitcnt lgkmcnt(" #n ")" ::: "memory")
; #define PG8_BAR __builtin_amdgcn_s_barrier()
; template <class Epi, class Sched, bool ALIGN_EPI = false, bool SP2 = false>
; __device__ __forceinline__ void gemm_phase(PG8_LAS unsigned char* lds, const Gemm g, const Sched& S, const Epi& E, const int wave0) {
;     ...
;         for (int t = 0; t < nt; t += 2) {
;             const bool last = (t == nt - 2);
;             const char* a1 = cA + (size_t)(t + 1) * kstep;
;             const char* a2 = last ? nA : cA + (size_t)(t + 2) * kstep; const char* b2 = last ? nB : cB + (size_t)(t + 2) * kstep;
;             const char* a3 = a2 + kstep; const char* b3 = b2 + kstep;
;             if (last && has_next) S.a_ready(nxt);
;             if constexpr (SP2) {
;             PG8_LDB(B0, 0, 0); PG8_LDB(B1, 0, 1); PG8_SCHED; PG8_LDA(At, 0, 0); PG8_STAGE(PG8_SA(1, 1), a1 + hstepA, voffA);
;             PG8_WAIT_V(8); PG8_WAIT_L(0); PG8_BAR; PG8_MMA(0, 0, At, B0); PG8_MMA(0, 1, At, B1); PG8_BAR; PG8_SCHED;
;             PG8_LDA(At, 0, 1); PG8_STAGE(PG8_SB(0, 0), b2, voffB); PG8_STAGE(PG8_SB(0, 1), b2 + hstepB, voffB); PG8_STAGE(PG8_SA(0, 0), a2, voffA);
;             PG8_WAIT_V(8); PG8_WAIT_L(0); PG8_BAR; PG8_MMA(1, 0, At, B0); PG8_MMA(1, 1, At, B1); PG8_BAR; PG8_SCHED;
;             PG8_LDB(B0, 1, 0); PG8_LDB(B1, 1, 1); PG8_SCHED; PG8_LDA(At, 1, 0); PG8_STAGE(PG8_SA(0, 1), a2 + hstepA, voffA);
;             PG8_WAIT_V(8); PG8_WAIT_L(0); PG8_BAR; PG8_MMA(0, 0, At, B0); PG8_MMA(0, 1, At, B1); PG8_BAR; PG8_SCHED;
;             PG8_LDA(At, 1, 1); PG8_STAGE(PG8_SB(1, 0), b3, voffB); PG8_STAGE(PG8_SB(1, 1), b3 + hstepB, voffB); PG8_STAGE(PG8_SA(1, 0), a3, voffA);
;             PG8_WAIT_V(8); PG8_WAIT_L(0); PG8_BAR; PG8_MMA(1, 0, At, B0); PG8_MMA(1, 1, At, B1); PG8_BAR; PG8_SCHED;
	s_add_i32 s31, 0, 0x18000
	s_add_i32 s33, 0, 0x1c000
	ds_read_b128 v[130:133], v254
	ds_read_b128 v[134:137], v254 offset:1024
	ds_read_b128 v[148:151], v254 offset:2048
	ds_read_b128 v[152:155], v254 offset:3072
	ds_read_b128 v[178:181], v255
	ds_read_b128 v[182:185], v255 offset:1024
	ds_read_b128 v[186:189], v255 offset:2048
	ds_read_b128 v[190:193], v255 offset:3072
	s_add_u32 s16, s16, 0x40000
	s_addc_u32 s17, s17, 0
	s_mov_b32 m0, s25
	ds_read_b128 v[194:197], v159 offset:32768
	ds_read_b128 v[208:211], v159 offset:33792
	ds_read_b128 v[212:215], v159 offset:34816
	ds_read_b128 v[216:219], v159 offset:35840
	ds_read_b128 v[220:223], v159 offset:36864
	ds_read_b128 v[224:227], v159 offset:37888
	ds_read_b128 v[228:231], v159 offset:38912
	ds_read_b128 v[232:235], v159 offset:39936
	global_load_lds_dwordx4 v142, s[16:17]
	s_mov_b32 m0, s26
	s_nop 0
	global_load_lds_dwordx4 v140, s[16:17]
	s_waitcnt vmcnt(8)
	s_waitcnt lgkmcnt(0)
	s_setprio 1
	s_barrier
	s_waitcnt lgkmcnt(0)
	v_mfma_f32_16x16x32_bf16 v[126:129], v[130:133], v[194:197], v[126:129]
	v_mfma_f32_16x16x32_bf16 v[122:125], v[148:151], v[194:197], v[122:125]
	v_mfma_f32_16x16x32_bf16 v[110:113], v[130:133], v[212:215], v[110:113]
	v_mfma_f32_16x16x32_bf16 v[106:109], v[148:151], v[212:215], v[106:109]
	v_mfma_f32_16x16x32_bf16 v[94:97], v[130:133], v[220:223], v[94:97]
	v_mfma_f32_16x16x32_bf16 v[90:93], v[148:151], v[220:223], v[90:93]
	v_mfma_f32_16x16x32_bf16 v[78:81], v[130:133], v[228:231], v[78:81]
	v_mfma_f32_16x16x32_bf16 v[74:77], v[148:151], v[228:231], v[74:77]
	s_setprio 0
	s_setprio 1
	v_mfma_f32_16x16x32_bf16 v[126:129], v[134:137], v[208:211], v[126:129]
	v_mfma_f32_16x16x32_bf16 v[122:125], v[152:155], v[208:211], v[122:125]
	v_mfma_f32_16x16x32_bf16 v[110:113], v[134:137], v[216:219], v[110:113]
	v_mfma_f32_16x16x32_bf16 v[106:109], v[152:155], v[216:219], v[106:109]
	v_mfma_f32_16x16x32_bf16 v[94:97], v[134:137], v[224:227], v[94:97]
	v_mfma_f32_16x16x32_bf16 v[90:93], v[152:155], v[224:227], v[90:93]
	v_mfma_f32_16x16x32_bf16 v[78:81], v[134:137], v[232:235], v[78:81]
	v_mfma_f32_16x16x32_bf16 v[74:77], v[152:155], v[232:235], v[74:77]
	s_setprio 0
	s_setprio 1
	v_mfma_f32_16x16x32_bf16 v[118:121], v[178:181], v[194:197], v[118:121]
	v_mfma_f32_16x16x32_bf16 v[114:117], v[186:189], v[194:197], v[114:117]
	v_mfma_f32_16x16x32_bf16 v[102:105], v[178:181], v[212:215], v[102:105]
	v_mfma_f32_16x16x32_bf16 v[98:101], v[186:189], v[212:215], v[98:101]
	v_mfma_f32_16x16x32_bf16 v[86:89], v[178:181], v[220:223], v[86:89]
	v_mfma_f32_16x16x32_bf16 v[82:85], v[186:189], v[220:223], v[82:85]
	v_mfma_f32_16x16x32_bf16 v[70:73], v[178:181], v[228:231], v[70:73]
	v_mfma_f32_16x16x32_bf16 v[66:69], v[186:189], v[228:231], v[66:69]
	s_setprio 0
	s_setprio 1
	v_mfma_f32_16x16x32_bf16 v[118:121], v[182:185], v[208:211], v[118:121]
	v_mfma_f32_16x16x32_bf16 v[114:117], v[190:193], v[208:211], v[114:117]
	v_mfma_f32_16x16x32_bf16 v[102:105], v[182:185], v[216:219], v[102:105]
	v_mfma_f32_16x16x32_bf16 v[98:101], v[190:193], v[216:219], v[98:101]
	v_mfma_f32_16x16x32_bf16 v[86:89], v[182:185], v[224:227], v[86:89]
	v_mfma_f32_16x16x32_bf16 v[82:85], v[190:193], v[224:227], v[82:85]
	v_mfma_f32_16x16x32_bf16 v[70:73], v[182:185], v[232:235], v[70:73]
	v_mfma_f32_16x16x32_bf16 v[66:69], v[190:193], v[232:235], v[66:69]
	s_setprio 0
	s_barrier
	s_add_i32 s16, s31, s22
	s_add_u32 s36, s2, 0x80
	s_addc_u32 s37, s3, 0
	s_mov_b32 m0, s16
	ds_read_b128 v[194:197], v159 offset:49152
	ds_read_b128 v[208:211], v159 offset:50176
	ds_read_b128 v[212:215], v159 offset:51200
	ds_read_b128 v[216:219], v159 offset:52224
	ds_read_b128 v[220:223], v159 offset:53248
	ds_read_b128 v[224:227], v159 offset:54272
	ds_read_b128 v[228:231], v159 offset:55296
	ds_read_b128 v[232:235], v159 offset:56320
	global_load_lds_dwordx4 v64, s[36:37]
	s_add_i32 m0, s16, 0x2000
	s_add_u32 s2, s2, 0x40080
	s_addc_u32 s3, s3, 0
	s_add_i32 s16, s33, s22
	global_load_lds_dwordx4 v138, s[36:37]
	s_mov_b32 m0, s16
	s_nop 0
	global_load_lds_dwordx4 v64, s[2:3]
	s_add_i32 m0, s16, 0x2000
	s_nop 0
	global_load_lds_dwordx4 v138, s[2:3]
	s_add_u32 s100, s100, 0x80
	s_addc_u32 s101, s101, 0
	s_mov_b32 m0, s27
	s_nop 0
	global_load_lds_dwordx4 v142, s[100:101]
	s_mov_b32 m0, s28
	s_nop 0
	global_load_lds_dwordx4 v140, s[100:101]
	s_waitcnt vmcnt(8)
	s_waitcnt lgkmcnt(0)
	s_setprio 1
	s_barrier
	s_waitcnt lgkmcnt(0)
	v_mfma_f32_16x16x32_bf16 v[60:63], v[130:133], v[194:197], v[60:63]
	v_mfma_f32_16x16x32_bf16 v[56:59], v[148:151], v[194:197], v[56:59]
	v_mfma_f32_16x16x32_bf16 v[44:47], v[130:133], v[212:215], v[44:47]
	v_mfma_f32_16x16x32_bf16 v[40:43], v[148:151], v[212:215], v[40:43]
	v_mfma_f32_16x16x32_bf16 v[28:31], v[130:133], v[220:223], v[28:31]
	v_mfma_f32_16x16x32_bf16 v[24:27], v[148:151], v[220:223], v[24:27]
	v_mfma_f32_16x16x32_bf16 v[12:15], v[130:133], v[228:231], v[12:15]
	v_mfma_f32_16x16x32_bf16 v[8:11], v[148:151], v[228:231], v[8:11]
	s_setprio 0
	s_setprio 1
	v_mfma_f32_16x16x32_bf16 v[60:63], v[134:137], v[208:211], v[60:63]
	v_mfma_f32_16x16x32_bf16 v[56:59], v[152:155], v[208:211], v[56:59]
	v_mfma_f32_16x16x32_bf16 v[44:47], v[134:137], v[216:219], v[44:47]
	v_mfma_f32_16x16x32_bf16 v[40:43], v[152:155], v[216:219], v[40:43]
	v_mfma_f32_16x16x32_bf16 v[28:31], v[134:137], v[224:227], v[28:31]
	v_mfma_f32_16x16x32_bf16 v[24:27], v[152:155], v[224:227], v[24:27]
	v_mfma_f32_16x16x32_bf16 v[12:15], v[134:137], v[232:235], v[12:15]
	v_mfma_f32_16x16x32_bf16 v[8:11], v[152:155], v[232:235], v[8:11]
	s_setprio 0
	s_setprio 1
	v_mfma_f32_16x16x32_bf16 v[52:55], v[178:181], v[194:197], v[52:55]
	v_mfma_f32_16x16x32_bf16 v[48:51], v[186:189], v[194:197], v[48:51]
	v_mfma_f32_16x16x32_bf16 v[36:39], v[178:181], v[212:215], v[36:39]
	v_mfma_f32_16x16x32_bf16 v[32:35], v[186:189], v[212:215], v[32:35]
	v_mfma_f32_16x16x32_bf16 v[20:23], v[178:181], v[220:223], v[20:23]
	v_mfma_f32_16x16x32_bf16 v[16:19], v[186:189], v[220:223], v[16:19]
	v_mfma_f32_16x16x32_bf16 v[4:7], v[178:181], v[228:231], v[4:7]
	v_mfma_f32_16x16x32_bf16 v[0:3], v[186:189], v[228:231], v[0:3]
	s_setprio 0
	s_setprio 1
	v_mfma_f32_16x16x32_bf16 v[52:55], v[182:185], v[208:211], v[52:55]
	v_mfma_f32_16x16x32_bf16 v[48:51], v[190:193], v[208:211], v[48:51]
	v_mfma_f32_16x16x32_bf16 v[36:39], v[182:185], v[216:219], v[36:39]
	v_mfma_f32_16x16x32_bf16 v[32:35], v[190:193], v[216:219], v[32:35]
	v_mfma_f32_16x16x32_bf16 v[20:23], v[182:185], v[224:227], v[20:23]
	v_mfma_f32_16x16x32_bf16 v[16:19], v[190:193], v[224:227], v[16:19]
	v_mfma_f32_16x16x32_bf16 v[4:7], v[182:185], v[232:235], v[4:7]
	v_mfma_f32_16x16x32_bf16 v[0:3], v[190:193], v[232:235], v[0:3]
	s_setprio 0
	s_barrier
	s_add_i32 s19, s19, 2
	s_add_u32 s0, s0, 0x100
	s_addc_u32 s1, s1, 0
	s_add_u32 s13, s13, 0x100
	s_addc_u32 s18, s18, 0
	s_cmp_gt_u32 s19, 13
	s_cbranch_scc0 .LBB0_1178
	s_mov_b64 s[36:37], 0x80
	s_and_b64 vcc, exec, s[6:7]
	s_cbranch_vccz .LBB0_1181
	s_barrier

; #define PG8_STAGE(bufoff, gbase, voff) do { _Pragma("unroll") for (int _i = 0; _i < 2; ++_i) \
;         __builtin_amdgcn_global_load_lds((const unsigned*)((const char*)(gbase) + (voff)[_i]), (PG8_LAS unsigned*)(lds + (bufoff) + ldsw + _i * 8192), 16, 0, 0); } while (0)
; #define PG8_LDA(dst, b, h) do { _Pragma("unroll") for (int m = 0; m < 4; ++m) _Pragma("unroll") for (int k = 0; k < 2; ++k) dst[m][k] = *(const PG8_LAS bf16x8*)(lds + PG8_SA(b, h) + aoff + m * 2048 + k * 1024); } while (0)
; #define PG8_WAIT_V(n) asm volatile("s_waitcnt vmcnt(" #n ")" ::: "memory")
; #define PG8_WAIT_L(n) asm volatile("s_waitcnt lgkmcnt(" #n ")" ::: "memory")
; #define PG8_BAR __builtin_amdgcn_s_barrier()
; template <class Epi, class Sched, bool ALIGN_EPI = false, bool SP2 = false>
; __device__ __forceinline__ void gemm_phase(PG8_LAS unsigned char* lds, const Gemm g, const Sched& S, const Epi& E, const int wave0) {
;     ...
;         for (int t = 0; t < nt; t += 2) {
;             const bool last = (t == nt - 2);
;             const char* a1 = cA + (size_t)(t + 1) * kstep;
;             const char* a2 = last ? nA : cA + (size_t)(t + 2) * kstep; const char* b2 = last ? nB : cB + (size_t)(t + 2) * kstep;
;             const char* a3 = a2 + kstep; const char* b3 = b2 + kstep;
;             if (last && has_next) S.a_ready(nxt);
;             if constexpr (SP2) {
;             PG8_LDB(B0, 0, 0); PG8_LDB(B1, 0, 1); PG8_SCHED; PG8_LDA(At, 0, 0); PG8_STAGE(PG8_SA(1, 1), a1 + hstepA, voffA);
;             PG8_WAIT_V(8); PG8_WAIT_L(0); PG8_BAR; PG8_MMA(0, 0, At, B0); PG8_MMA(0, 1, At, B1); PG8_BAR; PG8_SCHED;
;             PG8_LDA(At, 0, 1); PG8_STAGE(PG8_SB(0, 0), b2, voffB); PG8_STAGE(PG8_SB(0, 1), b2 + hstepB, voffB); PG8_STAGE(PG8_SA(0, 0), a2, voffA);
;             PG8_WAIT_V(8); PG8_WAIT_L(0); PG8_BAR; PG8_MMA(1, 0, At, B0); PG8_MMA(1, 1, At, B1); PG8_BAR; PG8_SCHED;
;             PG8_LDB(B0, 1, 0); PG8_LDB(B1, 1, 1); PG8_SCHED; PG8_LDA(At, 1, 0); PG8_STAGE(PG8_SA(0, 1), a2 + hstepA, voffA);
;             PG8_WAIT_V(8); PG8_WAIT_L(0); PG8_BAR; PG8_MMA(0, 0, At, B0); PG8_MMA(0, 1, At, B1); PG8_BAR; PG8_SCHED;
;             PG8_LDA(At, 1, 1); PG8_STAGE(PG8_SB(1, 0), b3, voffB); PG8_STAGE(PG8_SB(1, 1), b3 + hstepB, voffB); PG8_STAGE(PG8_SA(1, 0), a3, voffA);
;             PG8_WAIT_V(8); PG8_WAIT_L(0); PG8_BAR; PG8_MMA(1, 0, At, B0); PG8_MMA(1, 1, At, B1); PG8_BAR; PG8_SCHED;
.LBB0_1231:
	s_add_u32 s2, s0, 0xfffc0080
	s_addc_u32 s3, s1, -1
	s_add_i32 s31, 0, 0x10000
	s_cmp_eq_u32 s19, 12
	s_cselect_b32 s17, s43, s3
	s_cselect_b32 s16, s42, s2
	s_cselect_b32 s3, s9, s18
	s_cselect_b32 s2, s11, s13
	s_add_i32 s33, 0, 0x14000
	ds_read_b128 v[140:143], v252
	ds_read_b128 v[144:147], v252 offset:1024
	ds_read_b128 v[154:157], v252 offset:2048
	ds_read_b128 v[158:161], v252 offset:3072
	ds_read_b128 v[178:181], v253
	ds_read_b128 v[182:185], v253 offset:1024
	ds_read_b128 v[186:189], v253 offset:2048
	ds_read_b128 v[190:193], v253 offset:3072
	s_add_i32 m0, s23, 0xc000
	ds_read_b128 v[194:197], v153
	ds_read_b128 v[208:211], v153 offset:1024
	ds_read_b128 v[212:215], v153 offset:2048
	ds_read_b128 v[216:219], v153 offset:3072
	ds_read_b128 v[220:223], v153 offset:4096
	ds_read_b128 v[224:227], v153 offset:5120
	ds_read_b128 v[228:231], v153 offset:6144
	ds_read_b128 v[232:235], v153 offset:7168
	global_load_lds_dwordx4 v136, s[0:1]
	s_add_i32 m0, s23, 0xe000
	s_nop 0
	global_load_lds_dwordx4 v138, s[0:1]
	s_waitcnt vmcnt(8)
	s_waitcnt lgkmcnt(0)
	s_setprio 1
	s_barrier
	s_waitcnt lgkmcnt(0)
	v_mfma_f32_16x16x32_bf16 v[126:129], v[140:143], v[194:197], v[126:129]
	v_mfma_f32_16x16x32_bf16 v[122:125], v[154:157], v[194:197], v[122:125]
	v_mfma_f32_16x16x32_bf16 v[110:113], v[140:143], v[212:215], v[110:113]
	v_mfma_f32_16x16x32_bf16 v[106:109], v[154:157], v[212:215], v[106:109]
	v_mfma_f32_16x16x32_bf16 v[94:97], v[140:143], v[220:223], v[94:97]
	v_mfma_f32_16x16x32_bf16 v[90:93], v[154:157], v[220:223], v[90:93]
	v_mfma_f32_16x16x32_bf16 v[78:81], v[140:143], v[228:231], v[78:81]
	v_mfma_f32_16x16x32_bf16 v[74:77], v[154:157], v[228:231], v[74:77]
	s_setprio 0
	s_setprio 1
	v_mfma_f32_16x16x32_bf16 v[126:129], v[144:147], v[208:211], v[126:129]
	v_mfma_f32_16x16x32_bf16 v[122:125], v[158:161], v[208:211], v[122:125]
	v_mfma_f32_16x16x32_bf16 v[110:113], v[144:147], v[216:219], v[110:113]
	v_mfma_f32_16x16x32_bf16 v[106:109], v[158:161], v[216:219], v[106:109]
	v_mfma_f32_16x16x32_bf16 v[94:97], v[144:147], v[224:227], v[94:97]
	v_mfma_f32_16x16x32_bf16 v[90:93], v[158:161], v[224:227], v[90:93]
	v_mfma_f32_16x16x32_bf16 v[78:81], v[144:147], v[232:235], v[78:81]
	v_mfma_f32_16x16x32_bf16 v[74:77], v[158:161], v[232:235], v[74:77]
	s_setprio 0
	s_setprio 1
	v_mfma_f32_16x16x32_bf16 v[118:121], v[178:181], v[194:197], v[118:121]
	v_mfma_f32_16x16x32_bf16 v[114:117], v[186:189], v[194:197], v[114:117]
	v_mfma_f32_16x16x32_bf16 v[102:105], v[178:181], v[212:215], v[102:105]
	v_mfma_f32_16x16x32_bf16 v[98:101], v[186:189], v[212:215], v[98:101]
	v_mfma_f32_16x16x32_bf16 v[86:89], v[178:181], v[220:223], v[86:89]
	v_mfma_f32_16x16x32_bf16 v[82:85], v[186:189], v[220:223], v[82:85]
	v_mfma_f32_16x16x32_bf16 v[70:73], v[178:181], v[228:231], v[70:73]
	v_mfma_f32_16x16x32_bf16 v[66:69], v[186:189], v[228:231], v[66:69]
	s_setprio 0
	s_setprio 1
	v_mfma_f32_16x16x32_bf16 v[118:121], v[182:185], v[208:211], v[118:121]
	v_mfma_f32_16x16x32_bf16 v[114:117], v[190:193], v[208:211], v[114:117]
	v_mfma_f32_16x16x32_bf16 v[102:105], v[182:185], v[216:219], v[102:105]
	v_mfma_f32_16x16x32_bf16 v[98:101], v[190:193], v[216:219], v[98:101]
	v_mfma_f32_16x16x32_bf16 v[86:89], v[182:185], v[224:227], v[86:89]
	v_mfma_f32_16x16x32_bf16 v[82:85], v[190:193], v[224:227], v[82:85]
	v_mfma_f32_16x16x32_bf16 v[70:73], v[182:185], v[232:235], v[70:73]
	v_mfma_f32_16x16x32_bf16 v[66:69], v[190:193], v[232:235], v[66:69]
	s_setprio 0
	s_barrier
	s_add_i32 s31, s31, s22
	s_mov_b32 m0, s31
	ds_read_b128 v[194:197], v153 offset:16384
	ds_read_b128 v[208:211], v153 offset:17408
	ds_read_b128 v[212:215], v153 offset:18432
	ds_read_b128 v[216:219], v153 offset:19456
	ds_read_b128 v[220:223], v153 offset:20480
	ds_read_b128 v[224:227], v153 offset:21504
	ds_read_b128 v[228:231], v153 offset:22528
	ds_read_b128 v[232:235], v153 offset:23552
	global_load_lds_dwordx4 v64, s[2:3]
	s_add_i32 m0, s31, 0x2000
	s_add_u32 s34, s2, 0x40000
	s_addc_u32 s35, s3, 0
	s_add_i32 s31, s33, s22
	global_load_lds_dwordx4 v130, s[2:3]
	s_mov_b32 m0, s31
	s_mov_b64 s[100:101], s[16:17]
	global_load_lds_dwordx4 v64, s[34:35]
	s_add_i32 m0, s31, 0x2000
	s_nop 0
	global_load_lds_dwordx4 v130, s[34:35]
	s_mov_b32 m0, s23
	s_nop 0
	global_load_lds_dwordx4 v134, s[16:17]
	s_mov_b32 m0, s24
	s_nop 0
	global_load_lds_dwordx4 v132, s[16:17]
	s_waitcnt vmcnt(8)
	s_waitcnt lgkmcnt(0)
	s_setprio 1
	s_barrier
	s_waitcnt lgkmcnt(0)
	v_mfma_f32_16x16x32_bf16 v[60:63], v[140:143], v[194:197], v[60:63]
	v_mfma_f32_16x16x32_bf16 v[56:59], v[154:157], v[194:197], v[56:59]
	v_mfma_f32_16x16x32_bf16 v[44:47], v[140:143], v[212:215], v[44:47]
	v_mfma_f32_16x16x32_bf16 v[40:43], v[154:157], v[212:215], v[40:43]
	v_mfma_f32_16x16x32_bf16 v[28:31], v[140:143], v[220:223], v[28:31]
	v_mfma_f32_16x16x32_bf16 v[24:27], v[154:157], v[220:223], v[24:27]
	v_mfma_f32_16x16x32_bf16 v[12:15], v[140:143], v[228:231], v[12:15]
	v_mfma_f32_16x16x32_bf16 v[8:11], v[154:157], v[228:231], v[8:11]
	s_setprio 0
	s_setprio 1
	v_mfma_f32_16x16x32_bf16 v[60:63], v[144:147], v[208:211], v[60:63]
	v_mfma_f32_16x16x32_bf16 v[56:59], v[158:161], v[208:211], v[56:59]
	v_mfma_f32_16x16x32_bf16 v[44:47], v[144:147], v[216:219], v[44:47]
	v_mfma_f32_16x16x32_bf16 v[40:43], v[158:161], v[216:219], v[40:43]
	v_mfma_f32_16x16x32_bf16 v[28:31], v[144:147], v[224:227], v[28:31]
	v_mfma_f32_16x16x32_bf16 v[24:27], v[158:161], v[224:227], v[24:27]
	v_mfma_f32_16x16x32_bf16 v[12:15], v[144:147], v[232:235], v[12:15]
	v_mfma_f32_16x16x32_bf16 v[8:11], v[158:161], v[232:235], v[8:11]
	s_setprio 0
	s_setprio 1
	v_mfma_f32_16x16x32_bf16 v[52:55], v[178:181], v[194:197], v[52:55]
	v_mfma_f32_16x16x32_bf16 v[48:51], v[186:189], v[194:197], v[48:51]
	v_mfma_f32_16x16x32_bf16 v[36:39], v[178:181], v[212:215], v[36:39]
	v_mfma_f32_16x16x32_bf16 v[32:35], v[186:189], v[212:215], v[32:35]
	v_mfma_f32_16x16x32_bf16 v[20:23], v[178:181], v[220:223], v[20:23]
	v_mfma_f32_16x16x32_bf16 v[16:19], v[186:189], v[220:223], v[16:19]
	v_mfma_f32_16x16x32_bf16 v[4:7], v[178:181], v[228:231], v[4:7]
	v_mfma_f32_16x16x32_bf16 v[0:3], v[186:189], v[228:231], v[0:3]
	s_setprio 0
	s_setprio 1
	v_mfma_f32_16x16x32_bf16 v[52:55], v[182:185], v[208:211], v[52:55]
	v_mfma_f32_16x16x32_bf16 v[48:51], v[190:193], v[208:211], v[48:51]
	v_mfma_f32_16x16x32_bf16 v[36:39], v[182:185], v[216:219], v[36:39]
	v_mfma_f32_16x16x32_bf16 v[32:35], v[190:193], v[216:219], v[32:35]
	v_mfma_f32_16x16x32_bf16 v[20:23], v[182:185], v[224:227], v[20:23]
	v_mfma_f32_16x16x32_bf16 v[16:19], v[190:193], v[224:227], v[16:19]
	v_mfma_f32_16x16x32_bf16 v[4:7], v[182:185], v[232:235], v[4:7]
	v_mfma_f32_16x16x32_bf16 v[0:3], v[190:193], v[232:235], v[0:3]
	s_setprio 0
	s_barrier
; #define PG8_STAGE(bufoff, gbase, voff) do { _Pragma("unroll") for (int _i = 0; _i < 2; ++_i) \
;         __builtin_amdgcn_global_load_lds((const unsigned*)((const char*)(gbase) + (voff)[_i]), (PG8_LAS unsigned*)(lds + (bufoff) + ldsw + _i * 8192), 16, 0, 0); } while (0)
; #define PG8_LDA(dst, b, h) do { _Pragma("unroll") for (int m = 0; m < 4; ++m) _Pragma("unroll") for (int k = 0; k < 2; ++k) dst[m][k] = *(const PG8_LAS bf16x8*)(lds + PG8_SA(b, h) + aoff + m * 2048 + k * 1024); } while (0)
; #define PG8_WAIT_V(n) asm volatile("s_waitcnt vmcnt(" #n ")" ::: "memory")
; #define PG8_WAIT_L(n) asm volatile("s_waitcnt lgkmcnt(" #n ")" ::: "memory")
; #define PG8_BAR __builtin_amdgcn_s_barrier()
; template <class Epi, class Sched, bool ALIGN_EPI = false, bool SP2 = false>
; __device__ __forceinline__ void gemm_phase(PG8_LAS unsigned char* lds, const Gemm g, const Sched& S, const Epi& E, const int wave0) {
;     ...
;         for (int t = 0; t < nt; t += 2) {
;             const bool last = (t == nt - 2);
;             const char* a1 = cA + (size_t)(t + 1) * kstep;
;             const char* a2 = last ? nA : cA + (size_t)(t + 2) * kstep; const char* b2 = last ? nB : cB + (size_t)(t + 2) * kstep;
;             const char* a3 = a2 + kstep; const char* b3 = b2 + kstep;
;             if (last && has_next) S.a_ready(nxt);
;             if constexpr (SP2) {
;             PG8_LDB(B0, 0, 0); PG8_LDB(B1, 0, 1); PG8_SCHED; PG8_LDA(At, 0, 0); PG8_STAGE(PG8_SA(1, 1), a1 + hstepA, voffA);
;             PG8_WAIT_V(8); PG8_WAIT_L(0); PG8_BAR; PG8_MMA(0, 0, At, B0); PG8_MMA(0, 1, At, B1); PG8_BAR; PG8_SCHED;
;             PG8_LDA(At, 0, 1); PG8_STAGE(PG8_SB(0, 0), b2, voffB); PG8_STAGE(PG8_SB(0, 1), b2 + hstepB, voffB); PG8_STAGE(PG8_SA(0, 0), a2, voffA);
;             PG8_WAIT_V(8); PG8_WAIT_L(0); PG8_BAR; PG8_MMA(1, 0, At, B0); PG8_MMA(1, 1, At, B1); PG8_BAR; PG8_SCHED;
;             PG8_LDB(B0, 1, 0); PG8_LDB(B1, 1, 1); PG8_SCHED; PG8_LDA(At, 1, 0); PG8_STAGE(PG8_SA(0, 1), a2 + hstepA, voffA);
;             PG8_WAIT_V(8); PG8_WAIT_L(0); PG8_BAR; PG8_MMA(0, 0, At, B0); PG8_MMA(0, 1, At, B1); PG8_BAR; PG8_SCHED;
;             PG8_LDA(At, 1, 1); PG8_STAGE(PG8_SB(1, 0), b3, voffB); PG8_STAGE(PG8_SB(1, 1), b3 + hstepB, voffB); PG8_STAGE(PG8_SA(1, 0), a3, voffA);
;             PG8_WAIT_V(8); PG8_WAIT_L(0); PG8_BAR; PG8_MMA(1, 0, At, B0); PG8_MMA(1, 1, At, B1); PG8_BAR; PG8_SCHED;
	s_add_i32 s31, 0, 0x18000
	s_add_i32 s33, 0, 0x1c000
	ds_read_b128 v[140:143], v254
	ds_read_b128 v[144:147], v254 offset:1024
	ds_read_b128 v[154:157], v254 offset:2048
	ds_read_b128 v[158:161], v254 offset:3072
	ds_read_b128 v[178:181], v255
	ds_read_b128 v[182:185], v255 offset:1024
	ds_read_b128 v[186:189], v255 offset:2048
	ds_read_b128 v[190:193], v255 offset:3072
	s_add_u32 s16, s16, 0x40000
	s_addc_u32 s17, s17, 0
	s_mov_b32 m0, s25
	ds_read_b128 v[194:197], v153 offset:32768
	ds_read_b128 v[208:211], v153 offset:33792
	ds_read_b128 v[212:215], v153 offset:34816
	ds_read_b128 v[216:219], v153 offset:35840
	ds_read_b128 v[220:223], v153 offset:36864
	ds_read_b128 v[224:227], v153 offset:37888
	ds_read_b128 v[228:231], v153 offset:38912
	ds_read_b128 v[232:235], v153 offset:39936
	global_load_lds_dwordx4 v134, s[16:17]
	s_mov_b32 m0, s26
	s_nop 0
	global_load_lds_dwordx4 v132, s[16:17]
	s_waitcnt vmcnt(8)
	s_waitcnt lgkmcnt(0)
	s_setprio 1
	s_barrier
	s_waitcnt lgkmcnt(0)
	v_mfma_f32_16x16x32_bf16 v[126:129], v[140:143], v[194:197], v[126:129]
	v_mfma_f32_16x16x32_bf16 v[122:125], v[154:157], v[194:197], v[122:125]
	v_mfma_f32_16x16x32_bf16 v[110:113], v[140:143], v[212:215], v[110:113]
	v_mfma_f32_16x16x32_bf16 v[106:109], v[154:157], v[212:215], v[106:109]
	v_mfma_f32_16x16x32_bf16 v[94:97], v[140:143], v[220:223], v[94:97]
	v_mfma_f32_16x16x32_bf16 v[90:93], v[154:157], v[220:223], v[90:93]
	v_mfma_f32_16x16x32_bf16 v[78:81], v[140:143], v[228:231], v[78:81]
	v_mfma_f32_16x16x32_bf16 v[74:77], v[154:157], v[228:231], v[74:77]
	s_setprio 0
	s_setprio 1
	v_mfma_f32_16x16x32_bf16 v[126:129], v[144:147], v[208:211], v[126:129]
	v_mfma_f32_16x16x32_bf16 v[122:125], v[158:161], v[208:211], v[122:125]
	v_mfma_f32_16x16x32_bf16 v[110:113], v[144:147], v[216:219], v[110:113]
	v_mfma_f32_16x16x32_bf16 v[106:109], v[158:161], v[216:219], v[106:109]
	v_mfma_f32_16x16x32_bf16 v[94:97], v[144:147], v[224:227], v[94:97]
	v_mfma_f32_16x16x32_bf16 v[90:93], v[158:161], v[224:227], v[90:93]
	v_mfma_f32_16x16x32_bf16 v[78:81], v[144:147], v[232:235], v[78:81]
	v_mfma_f32_16x16x32_bf16 v[74:77], v[158:161], v[232:235], v[74:77]
	s_setprio 0
	s_setprio 1
	v_mfma_f32_16x16x32_bf16 v[118:121], v[178:181], v[194:197], v[118:121]
	v_mfma_f32_16x16x32_bf16 v[114:117], v[186:189], v[194:197], v[114:117]
	v_mfma_f32_16x16x32_bf16 v[102:105], v[178:181], v[212:215], v[102:105]
	v_mfma_f32_16x16x32_bf16 v[98:101], v[186:189], v[212:215], v[98:101]
	v_mfma_f32_16x16x32_bf16 v[86:89], v[178:181], v[220:223], v[86:89]
	v_mfma_f32_16x16x32_bf16 v[82:85], v[186:189], v[220:223], v[82:85]
	v_mfma_f32_16x16x32_bf16 v[70:73], v[178:181], v[228:231], v[70:73]
	v_mfma_f32_16x16x32_bf16 v[66:69], v[186:189], v[228:231], v[66:69]
	s_setprio 0
	s_setprio 1
	v_mfma_f32_16x16x32_bf16 v[118:121], v[182:185], v[208:211], v[118:121]
	v_mfma_f32_16x16x32_bf16 v[114:117], v[190:193], v[208:211], v[114:117]
	v_mfma_f32_16x16x32_bf16 v[102:105], v[182:185], v[216:219], v[102:105]
	v_mfma_f32_16x16x32_bf16 v[98:101], v[190:193], v[216:219], v[98:101]
	v_mfma_f32_16x16x32_bf16 v[86:89], v[182:185], v[224:227], v[86:89]
	v_mfma_f32_16x16x32_bf16 v[82:85], v[190:193], v[224:227], v[82:85]
	v_mfma_f32_16x16x32_bf16 v[70:73], v[182:185], v[232:235], v[70:73]
	v_mfma_f32_16x16x32_bf16 v[66:69], v[190:193], v[232:235], v[66:69]
	s_setprio 0
	s_barrier
	s_add_i32 s16, s31, s22
	s_add_u32 s36, s2, 0x80
	s_addc_u32 s37, s3, 0
	s_mov_b32 m0, s16
	ds_read_b128 v[194:197], v153 offset:49152
	ds_read_b128 v[208:211], v153 offset:50176
	ds_read_b128 v[212:215], v153 offset:51200
	ds_read_b128 v[216:219], v153 offset:52224
	ds_read_b128 v[220:223], v153 offset:53248
	ds_read_b128 v[224:227], v153 offset:54272
	ds_read_b128 v[228:231], v153 offset:55296
	ds_read_b128 v[232:235], v153 offset:56320
	global_load_lds_dwordx4 v64, s[36:37]
	s_add_i32 m0, s16, 0x2000
	s_add_u32 s2, s2, 0x40080
	s_addc_u32 s3, s3, 0
	s_add_i32 s16, s33, s22
	global_load_lds_dwordx4 v130, s[36:37]
	s_mov_b32 m0, s16
	s_nop 0
	global_load_lds_dwordx4 v64, s[2:3]
	s_add_i32 m0, s16, 0x2000
	s_nop 0
	global_load_lds_dwordx4 v130, s[2:3]
	s_add_u32 s100, s100, 0x80
	s_addc_u32 s101, s101, 0
	s_mov_b32 m0, s27
	s_nop 0
	global_load_lds_dwordx4 v134, s[100:101]
	s_mov_b32 m0, s28
	s_nop 0
	global_load_lds_dwordx4 v132, s[100:101]
	s_waitcnt vmcnt(8)
	s_waitcnt lgkmcnt(0)
	s_setprio 1
	s_barrier
	s_waitcnt lgkmcnt(0)
	v_mfma_f32_16x16x32_bf16 v[60:63], v[140:143], v[194:197], v[60:63]
	v_mfma_f32_16x16x32_bf16 v[56:59], v[154:157], v[194:197], v[56:59]
	v_mfma_f32_16x16x32_bf16 v[44:47], v[140:143], v[212:215], v[44:47]
	v_mfma_f32_16x16x32_bf16 v[40:43], v[154:157], v[212:215], v[40:43]
	v_mfma_f32_16x16x32_bf16 v[28:31], v[140:143], v[220:223], v[28:31]
	v_mfma_f32_16x16x32_bf16 v[24:27], v[154:157], v[220:223], v[24:27]
	v_mfma_f32_16x16x32_bf16 v[12:15], v[140:143], v[228:231], v[12:15]
	v_mfma_f32_16x16x32_bf16 v[8:11], v[154:157], v[228:231], v[8:11]
	s_setprio 0
	s_setprio 1
	v_mfma_f32_16x16x32_bf16 v[60:63], v[144:147], v[208:211], v[60:63]
	v_mfma_f32_16x16x32_bf16 v[56:59], v[158:161], v[208:211], v[56:59]
	v_mfma_f32_16x16x32_bf16 v[44:47], v[144:147], v[216:219], v[44:47]
	v_mfma_f32_16x16x32_bf16 v[40:43], v[158:161], v[216:219], v[40:43]
	v_mfma_f32_16x16x32_bf16 v[28:31], v[144:147], v[224:227], v[28:31]
	v_mfma_f32_16x16x32_bf16 v[24:27], v[158:161], v[224:227], v[24:27]
	v_mfma_f32_16x16x32_bf16 v[12:15], v[144:147], v[232:235], v[12:15]
	v_mfma_f32_16x16x32_bf16 v[8:11], v[158:161], v[232:235], v[8:11]
	s_setprio 0
	s_setprio 1
	v_mfma_f32_16x16x32_bf16 v[52:55], v[178:181], v[194:197], v[52:55]
	v_mfma_f32_16x16x32_bf16 v[48:51], v[186:189], v[194:197], v[48:51]
	v_mfma_f32_16x16x32_bf16 v[36:39], v[178:181], v[212:215], v[36:39]
	v_mfma_f32_16x16x32_bf16 v[32:35], v[186:189], v[212:215], v[32:35]
	v_mfma_f32_16x16x32_bf16 v[20:23], v[178:181], v[220:223], v[20:23]
	v_mfma_f32_16x16x32_bf16 v[16:19], v[186:189], v[220:223], v[16:19]
	v_mfma_f32_16x16x32_bf16 v[4:7], v[178:181], v[228:231], v[4:7]
	v_mfma_f32_16x16x32_bf16 v[0:3], v[186:189], v[228:231], v[0:3]
	s_setprio 0
	s_setprio 1
	v_mfma_f32_16x16x32_bf16 v[52:55], v[182:185], v[208:211], v[52:55]
	v_mfma_f32_16x16x32_bf16 v[48:51], v[190:193], v[208:211], v[48:51]
	v_mfma_f32_16x16x32_bf16 v[36:39], v[182:185], v[216:219], v[36:39]
	v_mfma_f32_16x16x32_bf16 v[32:35], v[190:193], v[216:219], v[32:35]
	v_mfma_f32_16x16x32_bf16 v[20:23], v[182:185], v[224:227], v[20:23]
	v_mfma_f32_16x16x32_bf16 v[16:19], v[190:193], v[224:227], v[16:19]
	v_mfma_f32_16x16x32_bf16 v[4:7], v[182:185], v[232:235], v[4:7]
	v_mfma_f32_16x16x32_bf16 v[0:3], v[190:193], v[232:235], v[0:3]
	s_setprio 0
	s_barrier
	s_add_i32 s19, s19, 2
	s_add_u32 s0, s0, 0x100
	s_addc_u32 s1, s1, 0
	s_add_u32 s13, s13, 0x100
	s_addc_u32 s18, s18, 0
	s_cmp_gt_u32 s19, 13
	s_cbranch_scc0 .LBB0_1231
	s_mov_b64 s[36:37], 0x80
	s_and_b64 vcc, exec, s[6:7]
	s_cbranch_vccz .LBB0_1234
	s_barrier

; #define PG8_STAGE(bufoff, gbase, voff) do { _Pragma("unroll") for (int _i = 0; _i < 2; ++_i) \
;         __builtin_amdgcn_global_load_lds((const unsigned*)((const char*)(gbase) + (voff)[_i]), (PG8_LAS unsigned*)(lds + (bufoff) + ldsw + _i * 8192), 16, 0, 0); } while (0)
; #define PG8_LDA(dst, b, h) do { _Pragma("unroll") for (int m = 0; m < 4; ++m) _Pragma("unroll") for (int k = 0; k < 2; ++k) dst[m][k] = *(const PG8_LAS bf16x8*)(lds + PG8_SA(b, h) + aoff + m * 2048 + k * 1024); } while (0)
; #define PG8_WAIT_V(n) asm volatile("s_waitcnt vmcnt(" #n ")" ::: "memory")
; #define PG8_WAIT_L(n) asm volatile("s_waitcnt lgkmcnt(" #n ")" ::: "memory")
; #define PG8_BAR __builtin_amdgcn_s_barrier()
; template <class Epi, class Sched, bool ALIGN_EPI = false, bool SP2 = false>
; __device__ __forceinline__ void gemm_phase(PG8_LAS unsigned char* lds, const Gemm g, const Sched& S, const Epi& E, const int wave0) {
;     ...
;         for (int t = 0; t < nt; t += 2) {
;             const bool last = (t == nt - 2);
;             const char* a1 = cA + (size_t)(t + 1) * kstep;
;             const char* a2 = last ? nA : cA + (size_t)(t + 2) * kstep; const char* b2 = last ? nB : cB + (size_t)(t + 2) * kstep;
;             const char* a3 = a2 + kstep; const char* b3 = b2 + kstep;
;             if (last && has_next) S.a_ready(nxt);
;             if constexpr (SP2) {
;             PG8_LDB(B0, 0, 0); PG8_LDB(B1, 0, 1); PG8_SCHED; PG8_LDA(At, 0, 0); PG8_STAGE(PG8_SA(1, 1), a1 + hstepA, voffA);
;             PG8_WAIT_V(8); PG8_WAIT_L(0); PG8_BAR; PG8_MMA(0, 0, At, B0); PG8_MMA(0, 1, At, B1); PG8_BAR; PG8_SCHED;
;             PG8_LDA(At, 0, 1); PG8_STAGE(PG8_SB(0, 0), b2, voffB); PG8_STAGE(PG8_SB(0, 1), b2 + hstepB, voffB); PG8_STAGE(PG8_SA(0, 0), a2, voffA);
;             PG8_WAIT_V(8); PG8_WAIT_L(0); PG8_BAR; PG8_MMA(1, 0, At, B0); PG8_MMA(1, 1, At, B1); PG8_BAR; PG8_SCHED;
;             PG8_LDB(B0, 1, 0); PG8_LDB(B1, 1, 1); PG8_SCHED; PG8_LDA(At, 1, 0); PG8_STAGE(PG8_SA(0, 1), a2 + hstepA, voffA);
;             PG8_WAIT_V(8); PG8_WAIT_L(0); PG8_BAR; PG8_MMA(0, 0, At, B0); PG8_MMA(0, 1, At, B1); PG8_BAR; PG8_SCHED;
;             PG8_LDA(At, 1, 1); PG8_STAGE(PG8_SB(1, 0), b3, voffB); PG8_STAGE(PG8_SB(1, 1), b3 + hstepB, voffB); PG8_STAGE(PG8_SA(1, 0), a3, voffA);
;             PG8_WAIT_V(8); PG8_WAIT_L(0); PG8_BAR; PG8_MMA(1, 0, At, B0); PG8_MMA(1, 1, At, B1); PG8_BAR; PG8_SCHED;
.LBB0_1341:
	s_add_u32 s16, s0, 0xfff80080
	s_addc_u32 s17, s1, -1
	s_add_i32 s40, 0, 0x10000
	s_cmp_eq_u32 s37, 28
	s_cselect_b32 s19, s11, s17
	s_cselect_b32 s18, s33, s16
	s_cselect_b32 s17, s9, s36
	s_cselect_b32 s16, s34, s35
	s_add_i32 s42, 0, 0x14000
	ds_read_b128 v[144:147], v252
	ds_read_b128 v[148:151], v252 offset:1024
	ds_read_b128 v[152:155], v252 offset:2048
	ds_read_b128 v[156:159], v252 offset:3072
	ds_read_b128 v[178:181], v253
	ds_read_b128 v[182:185], v253 offset:1024
	ds_read_b128 v[186:189], v253 offset:2048
	ds_read_b128 v[190:193], v253 offset:3072
	s_add_i32 m0, s23, 0xc000
	ds_read_b128 v[194:197], v143
	ds_read_b128 v[208:211], v143 offset:1024
	ds_read_b128 v[212:215], v143 offset:2048
	ds_read_b128 v[216:219], v143 offset:3072
	ds_read_b128 v[220:223], v143 offset:4096
	ds_read_b128 v[224:227], v143 offset:5120
	ds_read_b128 v[228:231], v143 offset:6144
	ds_read_b128 v[232:235], v143 offset:7168
	global_load_lds_dwordx4 v136, s[0:1]
	s_add_i32 m0, s23, 0xe000
	s_nop 0
	global_load_lds_dwordx4 v138, s[0:1]
	s_waitcnt vmcnt(8)
	s_waitcnt lgkmcnt(0)
	s_setprio 1
	s_barrier
	s_waitcnt lgkmcnt(0)
	v_mfma_f32_16x16x32_bf16 v[126:129], v[144:147], v[194:197], v[126:129]
	v_mfma_f32_16x16x32_bf16 v[122:125], v[152:155], v[194:197], v[122:125]
	v_mfma_f32_16x16x32_bf16 v[118:121], v[144:147], v[212:215], v[118:121]
	v_mfma_f32_16x16x32_bf16 v[114:117], v[152:155], v[212:215], v[114:117]
	v_mfma_f32_16x16x32_bf16 v[102:105], v[144:147], v[220:223], v[102:105]
	v_mfma_f32_16x16x32_bf16 v[98:101], v[152:155], v[220:223], v[98:101]
	v_mfma_f32_16x16x32_bf16 v[86:89], v[144:147], v[228:231], v[86:89]
	v_mfma_f32_16x16x32_bf16 v[82:85], v[152:155], v[228:231], v[82:85]
	s_setprio 0
	s_setprio 1
	v_mfma_f32_16x16x32_bf16 v[126:129], v[148:151], v[208:211], v[126:129]
	v_mfma_f32_16x16x32_bf16 v[122:125], v[156:159], v[208:211], v[122:125]
	v_mfma_f32_16x16x32_bf16 v[118:121], v[148:151], v[216:219], v[118:121]
	v_mfma_f32_16x16x32_bf16 v[114:117], v[156:159], v[216:219], v[114:117]
	v_mfma_f32_16x16x32_bf16 v[102:105], v[148:151], v[224:227], v[102:105]
	v_mfma_f32_16x16x32_bf16 v[98:101], v[156:159], v[224:227], v[98:101]
	v_mfma_f32_16x16x32_bf16 v[86:89], v[148:151], v[232:235], v[86:89]
	v_mfma_f32_16x16x32_bf16 v[82:85], v[156:159], v[232:235], v[82:85]
	s_setprio 0
	s_setprio 1
	v_mfma_f32_16x16x32_bf16 v[110:113], v[178:181], v[194:197], v[110:113]
	v_mfma_f32_16x16x32_bf16 v[106:109], v[186:189], v[194:197], v[106:109]
	v_mfma_f32_16x16x32_bf16 v[94:97], v[178:181], v[212:215], v[94:97]
	v_mfma_f32_16x16x32_bf16 v[90:93], v[186:189], v[212:215], v[90:93]
	v_mfma_f32_16x16x32_bf16 v[78:81], v[178:181], v[220:223], v[78:81]
	v_mfma_f32_16x16x32_bf16 v[74:77], v[186:189], v[220:223], v[74:77]
	v_mfma_f32_16x16x32_bf16 v[70:73], v[178:181], v[228:231], v[70:73]
	v_mfma_f32_16x16x32_bf16 v[66:69], v[186:189], v[228:231], v[66:69]
	s_setprio 0
	s_setprio 1
	v_mfma_f32_16x16x32_bf16 v[110:113], v[182:185], v[208:211], v[110:113]
	v_mfma_f32_16x16x32_bf16 v[106:109], v[190:193], v[208:211], v[106:109]
	v_mfma_f32_16x16x32_bf16 v[94:97], v[182:185], v[216:219], v[94:97]
	v_mfma_f32_16x16x32_bf16 v[90:93], v[190:193], v[216:219], v[90:93]
	v_mfma_f32_16x16x32_bf16 v[78:81], v[182:185], v[224:227], v[78:81]
	v_mfma_f32_16x16x32_bf16 v[74:77], v[190:193], v[224:227], v[74:77]
	v_mfma_f32_16x16x32_bf16 v[70:73], v[182:185], v[232:235], v[70:73]
	v_mfma_f32_16x16x32_bf16 v[66:69], v[190:193], v[232:235], v[66:69]
	s_setprio 0
	s_barrier
	s_add_i32 s40, s40, s22
	s_mov_b32 m0, s40
	ds_read_b128 v[194:197], v143 offset:16384
	ds_read_b128 v[208:211], v143 offset:17408
	ds_read_b128 v[212:215], v143 offset:18432
	ds_read_b128 v[216:219], v143 offset:19456
	ds_read_b128 v[220:223], v143 offset:20480
	ds_read_b128 v[224:227], v143 offset:21504
	ds_read_b128 v[228:231], v143 offset:22528
	ds_read_b128 v[232:235], v143 offset:23552
	global_load_lds_dwordx4 v64, s[16:17]
	s_add_i32 m0, s40, 0x2000
	s_add_u32 s40, s16, 0x80000
	s_addc_u32 s41, s17, 0
	s_add_i32 s42, s42, s22
	global_load_lds_dwordx4 v130, s[16:17]
	s_mov_b32 m0, s42
	s_mov_b64 s[100:101], s[18:19]
	global_load_lds_dwordx4 v64, s[40:41]
	s_add_i32 m0, s42, 0x2000
	s_nop 0
	global_load_lds_dwordx4 v130, s[40:41]
	s_mov_b32 m0, s23
	s_nop 0
	global_load_lds_dwordx4 v134, s[18:19]
	s_mov_b32 m0, s24
	s_nop 0
	global_load_lds_dwordx4 v132, s[18:19]
	s_waitcnt vmcnt(8)
	s_waitcnt lgkmcnt(0)
	s_setprio 1
	s_barrier
	s_waitcnt lgkmcnt(0)
	v_mfma_f32_16x16x32_bf16 v[60:63], v[144:147], v[194:197], v[60:63]
	v_mfma_f32_16x16x32_bf16 v[56:59], v[152:155], v[194:197], v[56:59]
	v_mfma_f32_16x16x32_bf16 v[52:55], v[144:147], v[212:215], v[52:55]
	v_mfma_f32_16x16x32_bf16 v[48:51], v[152:155], v[212:215], v[48:51]
	v_mfma_f32_16x16x32_bf16 v[36:39], v[144:147], v[220:223], v[36:39]
	v_mfma_f32_16x16x32_bf16 v[32:35], v[152:155], v[220:223], v[32:35]
	v_mfma_f32_16x16x32_bf16 v[20:23], v[144:147], v[228:231], v[20:23]
	v_mfma_f32_16x16x32_bf16 v[16:19], v[152:155], v[228:231], v[16:19]
	s_setprio 0
	s_setprio 1
	v_mfma_f32_16x16x32_bf16 v[60:63], v[148:151], v[208:211], v[60:63]
	v_mfma_f32_16x16x32_bf16 v[56:59], v[156:159], v[208:211], v[56:59]
	v_mfma_f32_16x16x32_bf16 v[52:55], v[148:151], v[216:219], v[52:55]
	v_mfma_f32_16x16x32_bf16 v[48:51], v[156:159], v[216:219], v[48:51]
	v_mfma_f32_16x16x32_bf16 v[36:39], v[148:151], v[224:227], v[36:39]
	v_mfma_f32_16x16x32_bf16 v[32:35], v[156:159], v[224:227], v[32:35]
	v_mfma_f32_16x16x32_bf16 v[20:23], v[148:151], v[232:235], v[20:23]
	v_mfma_f32_16x16x32_bf16 v[16:19], v[156:159], v[232:235], v[16:19]
	s_setprio 0
	s_setprio 1
	v_mfma_f32_16x16x32_bf16 v[44:47], v[178:181], v[194:197], v[44:47]
	v_mfma_f32_16x16x32_bf16 v[40:43], v[186:189], v[194:197], v[40:43]
	v_mfma_f32_16x16x32_bf16 v[28:31], v[178:181], v[212:215], v[28:31]
	v_mfma_f32_16x16x32_bf16 v[24:27], v[186:189], v[212:215], v[24:27]
	v_mfma_f32_16x16x32_bf16 v[12:15], v[178:181], v[220:223], v[12:15]
	v_mfma_f32_16x16x32_bf16 v[8:11], v[186:189], v[220:223], v[8:11]
	v_mfma_f32_16x16x32_bf16 v[4:7], v[178:181], v[228:231], v[4:7]
	v_mfma_f32_16x16x32_bf16 v[0:3], v[186:189], v[228:231], v[0:3]
	s_setprio 0
	s_setprio 1
	v_mfma_f32_16x16x32_bf16 v[44:47], v[182:185], v[208:211], v[44:47]
	v_mfma_f32_16x16x32_bf16 v[40:43], v[190:193], v[208:211], v[40:43]
	v_mfma_f32_16x16x32_bf16 v[28:31], v[182:185], v[216:219], v[28:31]
	v_mfma_f32_16x16x32_bf16 v[24:27], v[190:193], v[216:219], v[24:27]
	v_mfma_f32_16x16x32_bf16 v[12:15], v[182:185], v[224:227], v[12:15]
	v_mfma_f32_16x16x32_bf16 v[8:11], v[190:193], v[224:227], v[8:11]
	v_mfma_f32_16x16x32_bf16 v[4:7], v[182:185], v[232:235], v[4:7]
	v_mfma_f32_16x16x32_bf16 v[0:3], v[190:193], v[232:235], v[0:3]
	s_setprio 0
	s_barrier
; #define PG8_STAGE(bufoff, gbase, voff) do { _Pragma("unroll") for (int _i = 0; _i < 2; ++_i) \
;         __builtin_amdgcn_global_load_lds((const unsigned*)((const char*)(gbase) + (voff)[_i]), (PG8_LAS unsigned*)(lds + (bufoff) + ldsw + _i * 8192), 16, 0, 0); } while (0)
; #define PG8_LDA(dst, b, h) do { _Pragma("unroll") for (int m = 0; m < 4; ++m) _Pragma("unroll") for (int k = 0; k < 2; ++k) dst[m][k] = *(const PG8_LAS bf16x8*)(lds + PG8_SA(b, h) + aoff + m * 2048 + k * 1024); } while (0)
; #define PG8_WAIT_V(n) asm volatile("s_waitcnt vmcnt(" #n ")" ::: "memory")
; #define PG8_WAIT_L(n) asm volatile("s_waitcnt lgkmcnt(" #n ")" ::: "memory")
; #define PG8_BAR __builtin_amdgcn_s_barrier()
; template <class Epi, class Sched, bool ALIGN_EPI = false, bool SP2 = false>
; __device__ __forceinline__ void gemm_phase(PG8_LAS unsigned char* lds, const Gemm g, const Sched& S, const Epi& E, const int wave0) {
;     ...
;         for (int t = 0; t < nt; t += 2) {
;             const bool last = (t == nt - 2);
;             const char* a1 = cA + (size_t)(t + 1) * kstep;
;             const char* a2 = last ? nA : cA + (size_t)(t + 2) * kstep; const char* b2 = last ? nB : cB + (size_t)(t + 2) * kstep;
;             const char* a3 = a2 + kstep; const char* b3 = b2 + kstep;
;             if (last && has_next) S.a_ready(nxt);
;             if constexpr (SP2) {
;             PG8_LDB(B0, 0, 0); PG8_LDB(B1, 0, 1); PG8_SCHED; PG8_LDA(At, 0, 0); PG8_STAGE(PG8_SA(1, 1), a1 + hstepA, voffA);
;             PG8_WAIT_V(8); PG8_WAIT_L(0); PG8_BAR; PG8_MMA(0, 0, At, B0); PG8_MMA(0, 1, At, B1); PG8_BAR; PG8_SCHED;
;             PG8_LDA(At, 0, 1); PG8_STAGE(PG8_SB(0, 0), b2, voffB); PG8_STAGE(PG8_SB(0, 1), b2 + hstepB, voffB); PG8_STAGE(PG8_SA(0, 0), a2, voffA);
;             PG8_WAIT_V(8); PG8_WAIT_L(0); PG8_BAR; PG8_MMA(1, 0, At, B0); PG8_MMA(1, 1, At, B1); PG8_BAR; PG8_SCHED;
;             PG8_LDB(B0, 1, 0); PG8_LDB(B1, 1, 1); PG8_SCHED; PG8_LDA(At, 1, 0); PG8_STAGE(PG8_SA(0, 1), a2 + hstepA, voffA);
;             PG8_WAIT_V(8); PG8_WAIT_L(0); PG8_BAR; PG8_MMA(0, 0, At, B0); PG8_MMA(0, 1, At, B1); PG8_BAR; PG8_SCHED;
;             PG8_LDA(At, 1, 1); PG8_STAGE(PG8_SB(1, 0), b3, voffB); PG8_STAGE(PG8_SB(1, 1), b3 + hstepB, voffB); PG8_STAGE(PG8_SA(1, 0), a3, voffA);
;             PG8_WAIT_V(8); PG8_WAIT_L(0); PG8_BAR; PG8_MMA(1, 0, At, B0); PG8_MMA(1, 1, At, B1); PG8_BAR; PG8_SCHED;
	s_add_i32 s40, 0, 0x18000
	s_add_i32 s41, 0, 0x1c000
	ds_read_b128 v[144:147], v254
	ds_read_b128 v[148:151], v254 offset:1024
	ds_read_b128 v[152:155], v254 offset:2048
	ds_read_b128 v[156:159], v254 offset:3072
	ds_read_b128 v[178:181], v255
	ds_read_b128 v[182:185], v255 offset:1024
	ds_read_b128 v[186:189], v255 offset:2048
	ds_read_b128 v[190:193], v255 offset:3072
	s_add_u32 s18, s18, 0x80000
	s_addc_u32 s19, s19, 0
	s_mov_b32 m0, s25
	ds_read_b128 v[194:197], v143 offset:32768
	ds_read_b128 v[208:211], v143 offset:33792
	ds_read_b128 v[212:215], v143 offset:34816
	ds_read_b128 v[216:219], v143 offset:35840
	ds_read_b128 v[220:223], v143 offset:36864
	ds_read_b128 v[224:227], v143 offset:37888
	ds_read_b128 v[228:231], v143 offset:38912
	ds_read_b128 v[232:235], v143 offset:39936
	global_load_lds_dwordx4 v134, s[18:19]
	s_mov_b32 m0, s26
	s_nop 0
	global_load_lds_dwordx4 v132, s[18:19]
	s_waitcnt vmcnt(8)
	s_waitcnt lgkmcnt(0)
	s_setprio 1
	s_barrier
	s_waitcnt lgkmcnt(0)
	v_mfma_f32_16x16x32_bf16 v[126:129], v[144:147], v[194:197], v[126:129]
	v_mfma_f32_16x16x32_bf16 v[122:125], v[152:155], v[194:197], v[122:125]
	v_mfma_f32_16x16x32_bf16 v[118:121], v[144:147], v[212:215], v[118:121]
	v_mfma_f32_16x16x32_bf16 v[114:117], v[152:155], v[212:215], v[114:117]
	v_mfma_f32_16x16x32_bf16 v[102:105], v[144:147], v[220:223], v[102:105]
	v_mfma_f32_16x16x32_bf16 v[98:101], v[152:155], v[220:223], v[98:101]
	v_mfma_f32_16x16x32_bf16 v[86:89], v[144:147], v[228:231], v[86:89]
	v_mfma_f32_16x16x32_bf16 v[82:85], v[152:155], v[228:231], v[82:85]
	s_setprio 0
	s_setprio 1
	v_mfma_f32_16x16x32_bf16 v[126:129], v[148:151], v[208:211], v[126:129]
	v_mfma_f32_16x16x32_bf16 v[122:125], v[156:159], v[208:211], v[122:125]
	v_mfma_f32_16x16x32_bf16 v[118:121], v[148:151], v[216:219], v[118:121]
	v_mfma_f32_16x16x32_bf16 v[114:117], v[156:159], v[216:219], v[114:117]
	v_mfma_f32_16x16x32_bf16 v[102:105], v[148:151], v[224:227], v[102:105]
	v_mfma_f32_16x16x32_bf16 v[98:101], v[156:159], v[224:227], v[98:101]
	v_mfma_f32_16x16x32_bf16 v[86:89], v[148:151], v[232:235], v[86:89]
	v_mfma_f32_16x16x32_bf16 v[82:85], v[156:159], v[232:235], v[82:85]
	s_setprio 0
	s_setprio 1
	v_mfma_f32_16x16x32_bf16 v[110:113], v[178:181], v[194:197], v[110:113]
	v_mfma_f32_16x16x32_bf16 v[106:109], v[186:189], v[194:197], v[106:109]
	v_mfma_f32_16x16x32_bf16 v[94:97], v[178:181], v[212:215], v[94:97]
	v_mfma_f32_16x16x32_bf16 v[90:93], v[186:189], v[212:215], v[90:93]
	v_mfma_f32_16x16x32_bf16 v[78:81], v[178:181], v[220:223], v[78:81]
	v_mfma_f32_16x16x32_bf16 v[74:77], v[186:189], v[220:223], v[74:77]
	v_mfma_f32_16x16x32_bf16 v[70:73], v[178:181], v[228:231], v[70:73]
	v_mfma_f32_16x16x32_bf16 v[66:69], v[186:189], v[228:231], v[66:69]
	s_setprio 0
	s_setprio 1
	v_mfma_f32_16x16x32_bf16 v[110:113], v[182:185], v[208:211], v[110:113]
	v_mfma_f32_16x16x32_bf16 v[106:109], v[190:193], v[208:211], v[106:109]
	v_mfma_f32_16x16x32_bf16 v[94:97], v[182:185], v[216:219], v[94:97]
	v_mfma_f32_16x16x32_bf16 v[90:93], v[190:193], v[216:219], v[90:93]
	v_mfma_f32_16x16x32_bf16 v[78:81], v[182:185], v[224:227], v[78:81]
	v_mfma_f32_16x16x32_bf16 v[74:77], v[190:193], v[224:227], v[74:77]
	v_mfma_f32_16x16x32_bf16 v[70:73], v[182:185], v[232:235], v[70:73]
	v_mfma_f32_16x16x32_bf16 v[66:69], v[190:193], v[232:235], v[66:69]
	s_setprio 0
	s_barrier
	s_add_i32 s18, s40, s22
	s_add_u32 s44, s16, 0x80
	s_addc_u32 s45, s17, 0
	s_mov_b32 m0, s18
	ds_read_b128 v[194:197], v143 offset:49152
	ds_read_b128 v[208:211], v143 offset:50176
	ds_read_b128 v[212:215], v143 offset:51200
	ds_read_b128 v[216:219], v143 offset:52224
	ds_read_b128 v[220:223], v143 offset:53248
	ds_read_b128 v[224:227], v143 offset:54272
	ds_read_b128 v[228:231], v143 offset:55296
	ds_read_b128 v[232:235], v143 offset:56320
	global_load_lds_dwordx4 v64, s[44:45]
	s_add_i32 m0, s18, 0x2000
	s_add_u32 s16, s16, 0x80080
	s_addc_u32 s17, s17, 0
	s_add_i32 s18, s41, s22
	global_load_lds_dwordx4 v130, s[44:45]
	s_mov_b32 m0, s18
	s_nop 0
	global_load_lds_dwordx4 v64, s[16:17]
	s_add_i32 m0, s18, 0x2000
	s_nop 0
	global_load_lds_dwordx4 v130, s[16:17]
	s_add_u32 s100, s100, 0x80
	s_addc_u32 s101, s101, 0
	s_mov_b32 m0, s27
	s_nop 0
	global_load_lds_dwordx4 v134, s[100:101]
	s_mov_b32 m0, s28
	s_nop 0
	global_load_lds_dwordx4 v132, s[100:101]
	s_waitcnt vmcnt(8)
	s_waitcnt lgkmcnt(0)
	s_setprio 1
	s_barrier
	s_waitcnt lgkmcnt(0)
	v_mfma_f32_16x16x32_bf16 v[60:63], v[144:147], v[194:197], v[60:63]
	v_mfma_f32_16x16x32_bf16 v[56:59], v[152:155], v[194:197], v[56:59]
	v_mfma_f32_16x16x32_bf16 v[52:55], v[144:147], v[212:215], v[52:55]
	v_mfma_f32_16x16x32_bf16 v[48:51], v[152:155], v[212:215], v[48:51]
	v_mfma_f32_16x16x32_bf16 v[36:39], v[144:147], v[220:223], v[36:39]
	v_mfma_f32_16x16x32_bf16 v[32:35], v[152:155], v[220:223], v[32:35]
	v_mfma_f32_16x16x32_bf16 v[20:23], v[144:147], v[228:231], v[20:23]
	v_mfma_f32_16x16x32_bf16 v[16:19], v[152:155], v[228:231], v[16:19]
	s_setprio 0
	s_setprio 1
	v_mfma_f32_16x16x32_bf16 v[60:63], v[148:151], v[208:211], v[60:63]
	v_mfma_f32_16x16x32_bf16 v[56:59], v[156:159], v[208:211], v[56:59]
	v_mfma_f32_16x16x32_bf16 v[52:55], v[148:151], v[216:219], v[52:55]
	v_mfma_f32_16x16x32_bf16 v[48:51], v[156:159], v[216:219], v[48:51]
	v_mfma_f32_16x16x32_bf16 v[36:39], v[148:151], v[224:227], v[36:39]
	v_mfma_f32_16x16x32_bf16 v[32:35], v[156:159], v[224:227], v[32:35]
	v_mfma_f32_16x16x32_bf16 v[20:23], v[148:151], v[232:235], v[20:23]
	v_mfma_f32_16x16x32_bf16 v[16:19], v[156:159], v[232:235], v[16:19]
	s_setprio 0
	s_setprio 1
	v_mfma_f32_16x16x32_bf16 v[44:47], v[178:181], v[194:197], v[44:47]
	v_mfma_f32_16x16x32_bf16 v[40:43], v[186:189], v[194:197], v[40:43]
	v_mfma_f32_16x16x32_bf16 v[28:31], v[178:181], v[212:215], v[28:31]
	v_mfma_f32_16x16x32_bf16 v[24:27], v[186:189], v[212:215], v[24:27]
	v_mfma_f32_16x16x32_bf16 v[12:15], v[178:181], v[220:223], v[12:15]
	v_mfma_f32_16x16x32_bf16 v[8:11], v[186:189], v[220:223], v[8:11]
	v_mfma_f32_16x16x32_bf16 v[4:7], v[178:181], v[228:231], v[4:7]
	v_mfma_f32_16x16x32_bf16 v[0:3], v[186:189], v[228:231], v[0:3]
	s_setprio 0
	s_setprio 1
	v_mfma_f32_16x16x32_bf16 v[44:47], v[182:185], v[208:211], v[44:47]
	v_mfma_f32_16x16x32_bf16 v[40:43], v[190:193], v[208:211], v[40:43]
	v_mfma_f32_16x16x32_bf16 v[28:31], v[182:185], v[216:219], v[28:31]
	v_mfma_f32_16x16x32_bf16 v[24:27], v[190:193], v[216:219], v[24:27]
	v_mfma_f32_16x16x32_bf16 v[12:15], v[182:185], v[224:227], v[12:15]
	v_mfma_f32_16x16x32_bf16 v[8:11], v[190:193], v[224:227], v[8:11]
	v_mfma_f32_16x16x32_bf16 v[4:7], v[182:185], v[232:235], v[4:7]
	v_mfma_f32_16x16x32_bf16 v[0:3], v[190:193], v[232:235], v[0:3]
	s_setprio 0
	s_barrier
	s_add_i32 s37, s37, 2
	s_add_u32 s0, s0, 0x100
	s_addc_u32 s1, s1, 0
	s_add_u32 s35, s35, 0x100
	s_addc_u32 s36, s36, 0
	s_cmp_gt_u32 s37, 29
	s_cbranch_scc0 .LBB0_1341
	s_mov_b64 s[44:45], 0x80
	s_and_b64 vcc, exec, s[6:7]
	s_mov_b64 s[34:35], 0x45000
	s_cbranch_vccz .LBB0_1344
	s_barrier

; #define PG8_STAGE(bufoff, gbase, voff) do { _Pragma("unroll") for (int _i = 0; _i < 2; ++_i) \
;         __builtin_amdgcn_global_load_lds((const unsigned*)((const char*)(gbase) + (voff)[_i]), (PG8_LAS unsigned*)(lds + (bufoff) + ldsw + _i * 8192), 16, 0, 0); } while (0)
; #define PG8_LDA(dst, b, h) do { _Pragma("unroll") for (int m = 0; m < 4; ++m) _Pragma("unroll") for (int k = 0; k < 2; ++k) dst[m][k] = *(const PG8_LAS bf16x8*)(lds + PG8_SA(b, h) + aoff + m * 2048 + k * 1024); } while (0)
; #define PG8_LDB(dst, b, h) do { _Pragma("unroll") for (int n = 0; n < 2; ++n) _Pragma("unroll") for (int k = 0; k < 2; ++k) dst[n][k] = *(const PG8_LAS bf16x8*)(lds + PG8_SB(b, h) + boff + n * 2048 + k * 1024); } while (0)
; #define PG8_MMA(ai, bj, At, Bt) do { __builtin_amdgcn_s_setprio(1); _Pragma("unroll") for (int m = 0; m < 4; ++m) _Pragma("unroll") for (int n = 0; n < 2; ++n) _Pragma("unroll") for (int k = 0; k < 2; ++k) \
;         acc[ai][bj][m][n] = __builtin_amdgcn_mfma_f32_16x16x32_bf16(Bt[n][k], At[m][k], acc[ai][bj][m][n], 0, 0, 0); __builtin_amdgcn_s_setprio(0); } while (0)
; #define PG8_WAIT_V(n) asm volatile("s_waitcnt vmcnt(" #n ")" ::: "memory")
; #define PG8_WAIT_L(n) asm volatile("s_waitcnt lgkmcnt(" #n ")" ::: "memory")
; template <class Epi, class Sched, bool ALIGN_EPI = false, bool SP2 = false>
; __device__ __forceinline__ void gemm_phase(PG8_LAS unsigned char* lds, const Gemm g, const Sched& S, const Epi& E, const int wave0) {
;     ...
;             const bool last = (t == nt - 2);
;             const char* a1 = cA + (size_t)(t + 1) * kstep;
;             const char* a2 = last ? nA : cA + (size_t)(t + 2) * kstep; const char* b2 = last ? nB : cB + (size_t)(t + 2) * kstep;
;             const char* a3 = a2 + kstep; const char* b3 = b2 + kstep;
;             if (last && has_next) S.a_ready(nxt);
;             if constexpr (SP2) {
;             PG8_LDB(B0, 0, 0); PG8_LDB(B1, 0, 1); PG8_SCHED; PG8_LDA(At, 0, 0); PG8_STAGE(PG8_SA(1, 1), a1 + hstepA, voffA);
;             PG8_WAIT_V(8); PG8_WAIT_L(0); PG8_BAR; PG8_MMA(0, 0, At, B0); PG8_MMA(0, 1, At, B1); PG8_BAR; PG8_SCHED;
;             PG8_LDA(At, 0, 1); PG8_STAGE(PG8_SB(0, 0), b2, voffB); PG8_STAGE(PG8_SB(0, 1), b2 + hstepB, voffB); PG8_STAGE(PG8_SA(0, 0), a2, voffA);
;             PG8_WAIT_V(8); PG8_WAIT_L(0); PG8_BAR; PG8_MMA(1, 0, At, B0); PG8_MMA(1, 1, At, B1); PG8_BAR; PG8_SCHED;
.LBB0_1360:
	s_add_u32 s16, s0, 0xfff80080
	s_addc_u32 s17, s1, -1
	s_add_i32 s42, 0, 0x10000
	s_cmp_eq_u32 s41, 12
	s_cselect_b32 s19, s5, s17
	s_cselect_b32 s18, s4, s16
	s_cselect_b32 s17, s11, s27
	s_cselect_b32 s16, s13, s15
	s_add_i32 s44, 0, 0x14000
	ds_read_b128 v[144:147], v252
	ds_read_b128 v[148:151], v252 offset:1024
	ds_read_b128 v[152:155], v252 offset:2048
	ds_read_b128 v[156:159], v252 offset:3072
	ds_read_b128 v[178:181], v253
	ds_read_b128 v[182:185], v253 offset:1024
	ds_read_b128 v[186:189], v253 offset:2048
	ds_read_b128 v[190:193], v253 offset:3072
	s_add_i32 m0, s23, 0xc000
	ds_read_b128 v[194:197], v143
	ds_read_b128 v[208:211], v143 offset:1024
	ds_read_b128 v[212:215], v143 offset:2048
	ds_read_b128 v[216:219], v143 offset:3072
	ds_read_b128 v[220:223], v143 offset:4096
	ds_read_b128 v[224:227], v143 offset:5120
	ds_read_b128 v[228:231], v143 offset:6144
	ds_read_b128 v[232:235], v143 offset:7168
	global_load_lds_dwordx4 v136, s[0:1]
	s_add_i32 m0, s23, 0xe000
	s_nop 0
	global_load_lds_dwordx4 v138, s[0:1]
	s_waitcnt vmcnt(8)
	s_waitcnt lgkmcnt(0)
	s_setprio 1
	s_barrier
	s_waitcnt lgkmcnt(0)
	v_mfma_f32_16x16x32_bf16 v[126:129], v[144:147], v[194:197], v[126:129]
	v_mfma_f32_16x16x32_bf16 v[122:125], v[152:155], v[194:197], v[122:125]
	v_mfma_f32_16x16x32_bf16 v[118:121], v[144:147], v[212:215], v[118:121]
	v_mfma_f32_16x16x32_bf16 v[114:117], v[152:155], v[212:215], v[114:117]
	v_mfma_f32_16x16x32_bf16 v[102:105], v[144:147], v[220:223], v[102:105]
	v_mfma_f32_16x16x32_bf16 v[98:101], v[152:155], v[220:223], v[98:101]
	v_mfma_f32_16x16x32_bf16 v[86:89], v[144:147], v[228:231], v[86:89]
	v_mfma_f32_16x16x32_bf16 v[82:85], v[152:155], v[228:231], v[82:85]
	s_setprio 0
	s_setprio 1
	v_mfma_f32_16x16x32_bf16 v[126:129], v[148:151], v[208:211], v[126:129]
	v_mfma_f32_16x16x32_bf16 v[122:125], v[156:159], v[208:211], v[122:125]
	v_mfma_f32_16x16x32_bf16 v[118:121], v[148:151], v[216:219], v[118:121]
	v_mfma_f32_16x16x32_bf16 v[114:117], v[156:159], v[216:219], v[114:117]
	v_mfma_f32_16x16x32_bf16 v[102:105], v[148:151], v[224:227], v[102:105]
	v_mfma_f32_16x16x32_bf16 v[98:101], v[156:159], v[224:227], v[98:101]
	v_mfma_f32_16x16x32_bf16 v[86:89], v[148:151], v[232:235], v[86:89]
	v_mfma_f32_16x16x32_bf16 v[82:85], v[156:159], v[232:235], v[82:85]
	s_setprio 0
	s_setprio 1
	v_mfma_f32_16x16x32_bf16 v[110:113], v[178:181], v[194:197], v[110:113]
	v_mfma_f32_16x16x32_bf16 v[106:109], v[186:189], v[194:197], v[106:109]
	v_mfma_f32_16x16x32_bf16 v[94:97], v[178:181], v[212:215], v[94:97]
	v_mfma_f32_16x16x32_bf16 v[90:93], v[186:189], v[212:215], v[90:93]
	v_mfma_f32_16x16x32_bf16 v[78:81], v[178:181], v[220:223], v[78:81]
	v_mfma_f32_16x16x32_bf16 v[74:77], v[186:189], v[220:223], v[74:77]
	v_mfma_f32_16x16x32_bf16 v[70:73], v[178:181], v[228:231], v[70:73]
	v_mfma_f32_16x16x32_bf16 v[66:69], v[186:189], v[228:231], v[66:69]
	s_setprio 0
	s_setprio 1
	v_mfma_f32_16x16x32_bf16 v[110:113], v[182:185], v[208:211], v[110:113]
	v_mfma_f32_16x16x32_bf16 v[106:109], v[190:193], v[208:211], v[106:109]
	v_mfma_f32_16x16x32_bf16 v[94:97], v[182:185], v[216:219], v[94:97]
	v_mfma_f32_16x16x32_bf16 v[90:93], v[190:193], v[216:219], v[90:93]
	v_mfma_f32_16x16x32_bf16 v[78:81], v[182:185], v[224:227], v[78:81]
	v_mfma_f32_16x16x32_bf16 v[74:77], v[190:193], v[224:227], v[74:77]
	v_mfma_f32_16x16x32_bf16 v[70:73], v[182:185], v[232:235], v[70:73]
	v_mfma_f32_16x16x32_bf16 v[66:69], v[190:193], v[232:235], v[66:69]
	s_setprio 0
	s_barrier
	s_add_i32 s42, s42, s22
	s_mov_b32 m0, s42
	ds_read_b128 v[194:197], v143 offset:16384
	ds_read_b128 v[208:211], v143 offset:17408
	ds_read_b128 v[212:215], v143 offset:18432
	ds_read_b128 v[216:219], v143 offset:19456
	ds_read_b128 v[220:223], v143 offset:20480
	ds_read_b128 v[224:227], v143 offset:21504
	ds_read_b128 v[228:231], v143 offset:22528
	ds_read_b128 v[232:235], v143 offset:23552
	global_load_lds_dwordx4 v64, s[16:17]
	s_add_i32 m0, s42, 0x2000
	s_add_u32 s42, s16, 0x80000
	s_addc_u32 s43, s17, 0
	s_add_i32 s44, s44, s22
	global_load_lds_dwordx4 v130, s[16:17]
	s_mov_b32 m0, s44
	s_mov_b64 s[100:101], s[18:19]
	global_load_lds_dwordx4 v64, s[42:43]
	s_add_i32 m0, s44, 0x2000
	s_nop 0
	global_load_lds_dwordx4 v130, s[42:43]
	s_mov_b32 m0, s23
	s_nop 0
	global_load_lds_dwordx4 v134, s[18:19]
	s_mov_b32 m0, s24
	s_nop 0
	global_load_lds_dwordx4 v132, s[18:19]
	s_waitcnt vmcnt(8)
	s_waitcnt lgkmcnt(0)
	s_setprio 1
	s_barrier
	s_waitcnt lgkmcnt(0)
	v_mfma_f32_16x16x32_bf16 v[60:63], v[144:147], v[194:197], v[60:63]
	v_mfma_f32_16x16x32_bf16 v[56:59], v[152:155], v[194:197], v[56:59]
	v_mfma_f32_16x16x32_bf16 v[52:55], v[144:147], v[212:215], v[52:55]
	v_mfma_f32_16x16x32_bf16 v[48:51], v[152:155], v[212:215], v[48:51]
	v_mfma_f32_16x16x32_bf16 v[36:39], v[144:147], v[220:223], v[36:39]
	v_mfma_f32_16x16x32_bf16 v[32:35], v[152:155], v[220:223], v[32:35]
	v_mfma_f32_16x16x32_bf16 v[20:23], v[144:147], v[228:231], v[20:23]
	v_mfma_f32_16x16x32_bf16 v[16:19], v[152:155], v[228:231], v[16:19]
	s_setprio 0
	s_setprio 1
	v_mfma_f32_16x16x32_bf16 v[60:63], v[148:151], v[208:211], v[60:63]
	v_mfma_f32_16x16x32_bf16 v[56:59], v[156:159], v[208:211], v[56:59]
	v_mfma_f32_16x16x32_bf16 v[52:55], v[148:151], v[216:219], v[52:55]
	v_mfma_f32_16x16x32_bf16 v[48:51], v[156:159], v[216:219], v[48:51]
	v_mfma_f32_16x16x32_bf16 v[36:39], v[148:151], v[224:227], v[36:39]
	v_mfma_f32_16x16x32_bf16 v[32:35], v[156:159], v[224:227], v[32:35]
	v_mfma_f32_16x16x32_bf16 v[20:23], v[148:151], v[232:235], v[20:23]
	v_mfma_f32_16x16x32_bf16 v[16:19], v[156:159], v[232:235], v[16:19]
	s_setprio 0
	s_setprio 1
	v_mfma_f32_16x16x32_bf16 v[44:47], v[178:181], v[194:197], v[44:47]
	v_mfma_f32_16x16x32_bf16 v[40:43], v[186:189], v[194:197], v[40:43]
	v_mfma_f32_16x16x32_bf16 v[28:31], v[178:181], v[212:215], v[28:31]
	v_mfma_f32_16x16x32_bf16 v[24:27], v[186:189], v[212:215], v[24:27]
	v_mfma_f32_16x16x32_bf16 v[12:15], v[178:181], v[220:223], v[12:15]
	v_mfma_f32_16x16x32_bf16 v[8:11], v[186:189], v[220:223], v[8:11]
	v_mfma_f32_16x16x32_bf16 v[4:7], v[178:181], v[228:231], v[4:7]
	v_mfma_f32_16x16x32_bf16 v[0:3], v[186:189], v[228:231], v[0:3]
	s_setprio 0
	s_setprio 1
	v_mfma_f32_16x16x32_bf16 v[44:47], v[182:185], v[208:211], v[44:47]
	v_mfma_f32_16x16x32_bf16 v[40:43], v[190:193], v[208:211], v[40:43]
	v_mfma_f32_16x16x32_bf16 v[28:31], v[182:185], v[216:219], v[28:31]
	v_mfma_f32_16x16x32_bf16 v[24:27], v[190:193], v[216:219], v[24:27]
	v_mfma_f32_16x16x32_bf16 v[12:15], v[182:185], v[224:227], v[12:15]
	v_mfma_f32_16x16x32_bf16 v[8:11], v[190:193], v[224:227], v[8:11]
	v_mfma_f32_16x16x32_bf16 v[4:7], v[182:185], v[232:235], v[4:7]
	v_mfma_f32_16x16x32_bf16 v[0:3], v[190:193], v[232:235], v[0:3]
	s_setprio 0
	s_barrier
; #define PG8_STAGE(bufoff, gbase, voff) do { _Pragma("unroll") for (int _i = 0; _i < 2; ++_i) \
;         __builtin_amdgcn_global_load_lds((const unsigned*)((const char*)(gbase) + (voff)[_i]), (PG8_LAS unsigned*)(lds + (bufoff) + ldsw + _i * 8192), 16, 0, 0); } while (0)
; #define PG8_LDA(dst, b, h) do { _Pragma("unroll") for (int m = 0; m < 4; ++m) _Pragma("unroll") for (int k = 0; k < 2; ++k) dst[m][k] = *(const PG8_LAS bf16x8*)(lds + PG8_SA(b, h) + aoff + m * 2048 + k * 1024); } while (0)
; #define PG8_LDB(dst, b, h) do { _Pragma("unroll") for (int n = 0; n < 2; ++n) _Pragma("unroll") for (int k = 0; k < 2; ++k) dst[n][k] = *(const PG8_LAS bf16x8*)(lds + PG8_SB(b, h) + boff + n * 2048 + k * 1024); } while (0)
; #define PG8_MMA(ai, bj, At, Bt) do { __builtin_amdgcn_s_setprio(1); _Pragma("unroll") for (int m = 0; m < 4; ++m) _Pragma("unroll") for (int n = 0; n < 2; ++n) _Pragma("unroll") for (int k = 0; k < 2; ++k) \
;         acc[ai][bj][m][n] = __builtin_amdgcn_mfma_f32_16x16x32_bf16(Bt[n][k], At[m][k], acc[ai][bj][m][n], 0, 0, 0); __builtin_amdgcn_s_setprio(0); } while (0)
; #define PG8_WAIT_V(n) asm volatile("s_waitcnt vmcnt(" #n ")" ::: "memory")
; #define PG8_WAIT_L(n) asm volatile("s_waitcnt lgkmcnt(" #n ")" ::: "memory")
; #define PG8_BAR __builtin_amdgcn_s_barrier()
; #define PG8_SCHED __builtin_amdgcn_sched_barrier(0)
; template <class Epi, class Sched, bool ALIGN_EPI = false, bool SP2 = false>
; __device__ __forceinline__ void gemm_phase(PG8_LAS unsigned char* lds, const Gemm g, const Sched& S, const Epi& E, const int wave0) {
;     ...
;             PG8_LDB(B0, 1, 0); PG8_LDB(B1, 1, 1); PG8_SCHED; PG8_LDA(At, 1, 0); PG8_STAGE(PG8_SA(0, 1), a2 + hstepA, voffA);
;             PG8_WAIT_V(8); PG8_WAIT_L(0); PG8_BAR; PG8_MMA(0, 0, At, B0); PG8_MMA(0, 1, At, B1); PG8_BAR; PG8_SCHED;
;             PG8_LDA(At, 1, 1); PG8_STAGE(PG8_SB(1, 0), b3, voffB); PG8_STAGE(PG8_SB(1, 1), b3 + hstepB, voffB); PG8_STAGE(PG8_SA(1, 0), a3, voffA);
;             PG8_WAIT_V(8); PG8_WAIT_L(0); PG8_BAR; PG8_MMA(1, 0, At, B0); PG8_MMA(1, 1, At, B1); PG8_BAR; PG8_SCHED;
	s_add_i32 s42, 0, 0x18000
	s_add_i32 s43, 0, 0x1c000
	ds_read_b128 v[144:147], v254
	ds_read_b128 v[148:151], v254 offset:1024
	ds_read_b128 v[152:155], v254 offset:2048
	ds_read_b128 v[156:159], v254 offset:3072
	ds_read_b128 v[178:181], v255
	ds_read_b128 v[182:185], v255 offset:1024
	ds_read_b128 v[186:189], v255 offset:2048
	ds_read_b128 v[190:193], v255 offset:3072
	s_add_u32 s18, s18, 0x80000
	s_addc_u32 s19, s19, 0
	s_mov_b32 m0, s25
	ds_read_b128 v[194:197], v143 offset:32768
	ds_read_b128 v[208:211], v143 offset:33792
	ds_read_b128 v[212:215], v143 offset:34816
	ds_read_b128 v[216:219], v143 offset:35840
	ds_read_b128 v[220:223], v143 offset:36864
	ds_read_b128 v[224:227], v143 offset:37888
	ds_read_b128 v[228:231], v143 offset:38912
	ds_read_b128 v[232:235], v143 offset:39936
	global_load_lds_dwordx4 v134, s[18:19]
	s_mov_b32 m0, s33
	s_nop 0
	global_load_lds_dwordx4 v132, s[18:19]
	s_waitcnt vmcnt(8)
	s_waitcnt lgkmcnt(0)
	s_setprio 1
	s_barrier
	s_waitcnt lgkmcnt(0)
	v_mfma_f32_16x16x32_bf16 v[126:129], v[144:147], v[194:197], v[126:129]
	v_mfma_f32_16x16x32_bf16 v[122:125], v[152:155], v[194:197], v[122:125]
	v_mfma_f32_16x16x32_bf16 v[118:121], v[144:147], v[212:215], v[118:121]
	v_mfma_f32_16x16x32_bf16 v[114:117], v[152:155], v[212:215], v[114:117]
	v_mfma_f32_16x16x32_bf16 v[102:105], v[144:147], v[220:223], v[102:105]
	v_mfma_f32_16x16x32_bf16 v[98:101], v[152:155], v[220:223], v[98:101]
	v_mfma_f32_16x16x32_bf16 v[86:89], v[144:147], v[228:231], v[86:89]
	v_mfma_f32_16x16x32_bf16 v[82:85], v[152:155], v[228:231], v[82:85]
	s_setprio 0
	s_setprio 1
	v_mfma_f32_16x16x32_bf16 v[126:129], v[148:151], v[208:211], v[126:129]
	v_mfma_f32_16x16x32_bf16 v[122:125], v[156:159], v[208:211], v[122:125]
	v_mfma_f32_16x16x32_bf16 v[118:121], v[148:151], v[216:219], v[118:121]
	v_mfma_f32_16x16x32_bf16 v[114:117], v[156:159], v[216:219], v[114:117]
	v_mfma_f32_16x16x32_bf16 v[102:105], v[148:151], v[224:227], v[102:105]
	v_mfma_f32_16x16x32_bf16 v[98:101], v[156:159], v[224:227], v[98:101]
	v_mfma_f32_16x16x32_bf16 v[86:89], v[148:151], v[232:235], v[86:89]
	v_mfma_f32_16x16x32_bf16 v[82:85], v[156:159], v[232:235], v[82:85]
	s_setprio 0
	s_setprio 1
	v_mfma_f32_16x16x32_bf16 v[110:113], v[178:181], v[194:197], v[110:113]
	v_mfma_f32_16x16x32_bf16 v[106:109], v[186:189], v[194:197], v[106:109]
	v_mfma_f32_16x16x32_bf16 v[94:97], v[178:181], v[212:215], v[94:97]
	v_mfma_f32_16x16x32_bf16 v[90:93], v[186:189], v[212:215], v[90:93]
	v_mfma_f32_16x16x32_bf16 v[78:81], v[178:181], v[220:223], v[78:81]
	v_mfma_f32_16x16x32_bf16 v[74:77], v[186:189], v[220:223], v[74:77]
	v_mfma_f32_16x16x32_bf16 v[70:73], v[178:181], v[228:231], v[70:73]
	v_mfma_f32_16x16x32_bf16 v[66:69], v[186:189], v[228:231], v[66:69]
	s_setprio 0
	s_setprio 1
	v_mfma_f32_16x16x32_bf16 v[110:113], v[182:185], v[208:211], v[110:113]
	v_mfma_f32_16x16x32_bf16 v[106:109], v[190:193], v[208:211], v[106:109]
	v_mfma_f32_16x16x32_bf16 v[94:97], v[182:185], v[216:219], v[94:97]
	v_mfma_f32_16x16x32_bf16 v[90:93], v[190:193], v[216:219], v[90:93]
	v_mfma_f32_16x16x32_bf16 v[78:81], v[182:185], v[224:227], v[78:81]
	v_mfma_f32_16x16x32_bf16 v[74:77], v[190:193], v[224:227], v[74:77]
	v_mfma_f32_16x16x32_bf16 v[70:73], v[182:185], v[232:235], v[70:73]
	v_mfma_f32_16x16x32_bf16 v[66:69], v[190:193], v[232:235], v[66:69]
	s_setprio 0
	s_barrier
	s_add_i32 s18, s42, s22
	s_add_u32 s46, s16, 0x80
	s_addc_u32 s47, s17, 0
	s_mov_b32 m0, s18
	ds_read_b128 v[194:197], v143 offset:49152
	ds_read_b128 v[208:211], v143 offset:50176
	ds_read_b128 v[212:215], v143 offset:51200
	ds_read_b128 v[216:219], v143 offset:52224
	ds_read_b128 v[220:223], v143 offset:53248
	ds_read_b128 v[224:227], v143 offset:54272
	ds_read_b128 v[228:231], v143 offset:55296
	ds_read_b128 v[232:235], v143 offset:56320
	global_load_lds_dwordx4 v64, s[46:47]
	s_add_i32 m0, s18, 0x2000
	s_add_u32 s16, s16, 0x80080
	s_addc_u32 s17, s17, 0
	s_add_i32 s18, s43, s22
	global_load_lds_dwordx4 v130, s[46:47]
	s_mov_b32 m0, s18
	s_nop 0
	global_load_lds_dwordx4 v64, s[16:17]
	s_add_i32 m0, s18, 0x2000
	s_nop 0
	global_load_lds_dwordx4 v130, s[16:17]
	s_add_u32 s100, s100, 0x80
	s_addc_u32 s101, s101, 0
	s_mov_b32 m0, s34
	s_nop 0
	global_load_lds_dwordx4 v134, s[100:101]
	s_mov_b32 m0, s35
	s_nop 0
	global_load_lds_dwordx4 v132, s[100:101]
	s_waitcnt vmcnt(8)
	s_waitcnt lgkmcnt(0)
	s_setprio 1
	s_barrier
	s_waitcnt lgkmcnt(0)
	v_mfma_f32_16x16x32_bf16 v[60:63], v[144:147], v[194:197], v[60:63]
	v_mfma_f32_16x16x32_bf16 v[56:59], v[152:155], v[194:197], v[56:59]
	v_mfma_f32_16x16x32_bf16 v[52:55], v[144:147], v[212:215], v[52:55]
	v_mfma_f32_16x16x32_bf16 v[48:51], v[152:155], v[212:215], v[48:51]
	v_mfma_f32_16x16x32_bf16 v[36:39], v[144:147], v[220:223], v[36:39]
	v_mfma_f32_16x16x32_bf16 v[32:35], v[152:155], v[220:223], v[32:35]
	v_mfma_f32_16x16x32_bf16 v[20:23], v[144:147], v[228:231], v[20:23]
	v_mfma_f32_16x16x32_bf16 v[16:19], v[152:155], v[228:231], v[16:19]
	s_setprio 0
	s_setprio 1
	v_mfma_f32_16x16x32_bf16 v[60:63], v[148:151], v[208:211], v[60:63]
	v_mfma_f32_16x16x32_bf16 v[56:59], v[156:159], v[208:211], v[56:59]
	v_mfma_f32_16x16x32_bf16 v[52:55], v[148:151], v[216:219], v[52:55]
	v_mfma_f32_16x16x32_bf16 v[48:51], v[156:159], v[216:219], v[48:51]
	v_mfma_f32_16x16x32_bf16 v[36:39], v[148:151], v[224:227], v[36:39]
	v_mfma_f32_16x16x32_bf16 v[32:35], v[156:159], v[224:227], v[32:35]
	v_mfma_f32_16x16x32_bf16 v[20:23], v[148:151], v[232:235], v[20:23]
	v_mfma_f32_16x16x32_bf16 v[16:19], v[156:159], v[232:235], v[16:19]
	s_setprio 0
	s_setprio 1
	v_mfma_f32_16x16x32_bf16 v[44:47], v[178:181], v[194:197], v[44:47]
	v_mfma_f32_16x16x32_bf16 v[40:43], v[186:189], v[194:197], v[40:43]
	v_mfma_f32_16x16x32_bf16 v[28:31], v[178:181], v[212:215], v[28:31]
	v_mfma_f32_16x16x32_bf16 v[24:27], v[186:189], v[212:215], v[24:27]
	v_mfma_f32_16x16x32_bf16 v[12:15], v[178:181], v[220:223], v[12:15]
	v_mfma_f32_16x16x32_bf16 v[8:11], v[186:189], v[220:223], v[8:11]
	v_mfma_f32_16x16x32_bf16 v[4:7], v[178:181], v[228:231], v[4:7]
	v_mfma_f32_16x16x32_bf16 v[0:3], v[186:189], v[228:231], v[0:3]
	s_setprio 0
	s_setprio 1
	v_mfma_f32_16x16x32_bf16 v[44:47], v[182:185], v[208:211], v[44:47]
	v_mfma_f32_16x16x32_bf16 v[40:43], v[190:193], v[208:211], v[40:43]
	v_mfma_f32_16x16x32_bf16 v[28:31], v[182:185], v[216:219], v[28:31]
	v_mfma_f32_16x16x32_bf16 v[24:27], v[190:193], v[216:219], v[24:27]
	v_mfma_f32_16x16x32_bf16 v[12:15], v[182:185], v[224:227], v[12:15]
	v_mfma_f32_16x16x32_bf16 v[8:11], v[190:193], v[224:227], v[8:11]
	v_mfma_f32_16x16x32_bf16 v[4:7], v[182:185], v[232:235], v[4:7]
	v_mfma_f32_16x16x32_bf16 v[0:3], v[190:193], v[232:235], v[0:3]
	s_setprio 0
	s_barrier
	s_add_i32 s41, s41, 2
	s_add_u32 s0, s0, 0x100
	s_addc_u32 s1, s1, 0
	s_add_u32 s15, s15, 0x100
	s_addc_u32 s27, s27, 0
	s_cmp_gt_u32 s41, 13
	s_cbranch_scc0 .LBB0_1360
	s_mov_b64 s[46:47], 0x80
	s_and_b64 vcc, exec, s[8:9]
	s_cbranch_vccz .LBB0_1363
	s_barrier

; #define PG8_STAGE(bufoff, gbase, voff) do { _Pragma("unroll") for (int _i = 0; _i < 2; ++_i) \
;         __builtin_amdgcn_global_load_lds((const unsigned*)((const char*)(gbase) + (voff)[_i]), (PG8_LAS unsigned*)(lds + (bufoff) + ldsw + _i * 8192), 16, 0, 0); } while (0)
; #define PG8_LDA(dst, b, h) do { _Pragma("unroll") for (int m = 0; m < 4; ++m) _Pragma("unroll") for (int k = 0; k < 2; ++k) dst[m][k] = *(const PG8_LAS bf16x8*)(lds + PG8_SA(b, h) + aoff + m * 2048 + k * 1024); } while (0)
; #define PG8_LDB(dst, b, h) do { _Pragma("unroll") for (int n = 0; n < 2; ++n) _Pragma("unroll") for (int k = 0; k < 2; ++k) dst[n][k] = *(const PG8_LAS bf16x8*)(lds + PG8_SB(b, h) + boff + n * 2048 + k * 1024); } while (0)
; #define PG8_MMA(ai, bj, At, Bt) do { __builtin_amdgcn_s_setprio(1); _Pragma("unroll") for (int m = 0; m < 4; ++m) _Pragma("unroll") for (int n = 0; n < 2; ++n) _Pragma("unroll") for (int k = 0; k < 2; ++k) \
;         acc[ai][bj][m][n] = __builtin_amdgcn_mfma_f32_16x16x32_bf16(Bt[n][k], At[m][k], acc[ai][bj][m][n], 0, 0, 0); __builtin_amdgcn_s_setprio(0); } while (0)
; #define PG8_WAIT_V(n) asm volatile("s_waitcnt vmcnt(" #n ")" ::: "memory")
; #define PG8_WAIT_L(n) asm volatile("s_waitcnt lgkmcnt(" #n ")" ::: "memory")
; template <class Epi, class Sched, bool ALIGN_EPI = false, bool SP2 = false>
; __device__ __forceinline__ void gemm_phase(PG8_LAS unsigned char* lds, const Gemm g, const Sched& S, const Epi& E, const int wave0) {
;     ...
;             const bool last = (t == nt - 2);
;             const char* a1 = cA + (size_t)(t + 1) * kstep;
;             const char* a2 = last ? nA : cA + (size_t)(t + 2) * kstep; const char* b2 = last ? nB : cB + (size_t)(t + 2) * kstep;
;             const char* a3 = a2 + kstep; const char* b3 = b2 + kstep;
;             if (last && has_next) S.a_ready(nxt);
;             if constexpr (SP2) {
;             PG8_LDB(B0, 0, 0); PG8_LDB(B1, 0, 1); PG8_SCHED; PG8_LDA(At, 0, 0); PG8_STAGE(PG8_SA(1, 1), a1 + hstepA, voffA);
;             PG8_WAIT_V(8); PG8_WAIT_L(0); PG8_BAR; PG8_MMA(0, 0, At, B0); PG8_MMA(0, 1, At, B1); PG8_BAR; PG8_SCHED;
;             PG8_LDA(At, 0, 1); PG8_STAGE(PG8_SB(0, 0), b2, voffB); PG8_STAGE(PG8_SB(0, 1), b2 + hstepB, voffB); PG8_STAGE(PG8_SA(0, 0), a2, voffA);
;             PG8_WAIT_V(8); PG8_WAIT_L(0); PG8_BAR; PG8_MMA(1, 0, At, B0); PG8_MMA(1, 1, At, B1); PG8_BAR; PG8_SCHED;
.LBB0_1571:
	s_add_u32 s16, s0, 0xfff80080
	s_addc_u32 s17, s1, -1
	s_add_i32 s46, 0, 0x10000
	s_cmp_eq_u32 s45, 28
	s_cselect_b32 s19, s9, s17
	s_cselect_b32 s18, s33, s16
	s_cselect_b32 s17, s7, s44
	s_cselect_b32 s16, s36, s37
	s_add_i32 s48, 0, 0x14000
	ds_read_b128 v[140:143], v252
	ds_read_b128 v[148:151], v252 offset:1024
	ds_read_b128 v[152:155], v252 offset:2048
	ds_read_b128 v[156:159], v252 offset:3072
	ds_read_b128 v[178:181], v253
	ds_read_b128 v[182:185], v253 offset:1024
	ds_read_b128 v[186:189], v253 offset:2048
	ds_read_b128 v[190:193], v253 offset:3072
	s_add_i32 m0, s15, 0xc000
	ds_read_b128 v[194:197], v147
	ds_read_b128 v[208:211], v147 offset:1024
	ds_read_b128 v[212:215], v147 offset:2048
	ds_read_b128 v[216:219], v147 offset:3072
	ds_read_b128 v[220:223], v147 offset:4096
	ds_read_b128 v[224:227], v147 offset:5120
	ds_read_b128 v[228:231], v147 offset:6144
	ds_read_b128 v[232:235], v147 offset:7168
	global_load_lds_dwordx4 v136, s[0:1]
	s_add_i32 m0, s15, 0xe000
	s_nop 0
	global_load_lds_dwordx4 v138, s[0:1]
	s_waitcnt vmcnt(8)
	s_waitcnt lgkmcnt(0)
	s_setprio 1
	s_barrier
	s_waitcnt lgkmcnt(0)
	v_mfma_f32_16x16x32_bf16 v[126:129], v[140:143], v[194:197], v[126:129]
	v_mfma_f32_16x16x32_bf16 v[122:125], v[152:155], v[194:197], v[122:125]
	v_mfma_f32_16x16x32_bf16 v[110:113], v[140:143], v[212:215], v[110:113]
	v_mfma_f32_16x16x32_bf16 v[106:109], v[152:155], v[212:215], v[106:109]
	v_mfma_f32_16x16x32_bf16 v[94:97], v[140:143], v[220:223], v[94:97]
	v_mfma_f32_16x16x32_bf16 v[90:93], v[152:155], v[220:223], v[90:93]
	v_mfma_f32_16x16x32_bf16 v[78:81], v[140:143], v[228:231], v[78:81]
	v_mfma_f32_16x16x32_bf16 v[74:77], v[152:155], v[228:231], v[74:77]
	s_setprio 0
	s_setprio 1
	v_mfma_f32_16x16x32_bf16 v[126:129], v[148:151], v[208:211], v[126:129]
	v_mfma_f32_16x16x32_bf16 v[122:125], v[156:159], v[208:211], v[122:125]
	v_mfma_f32_16x16x32_bf16 v[110:113], v[148:151], v[216:219], v[110:113]
	v_mfma_f32_16x16x32_bf16 v[106:109], v[156:159], v[216:219], v[106:109]
	v_mfma_f32_16x16x32_bf16 v[94:97], v[148:151], v[224:227], v[94:97]
	v_mfma_f32_16x16x32_bf16 v[90:93], v[156:159], v[224:227], v[90:93]
	v_mfma_f32_16x16x32_bf16 v[78:81], v[148:151], v[232:235], v[78:81]
	v_mfma_f32_16x16x32_bf16 v[74:77], v[156:159], v[232:235], v[74:77]
	s_setprio 0
	s_setprio 1
	v_mfma_f32_16x16x32_bf16 v[118:121], v[178:181], v[194:197], v[118:121]
	v_mfma_f32_16x16x32_bf16 v[114:117], v[186:189], v[194:197], v[114:117]
	v_mfma_f32_16x16x32_bf16 v[102:105], v[178:181], v[212:215], v[102:105]
	v_mfma_f32_16x16x32_bf16 v[98:101], v[186:189], v[212:215], v[98:101]
	v_mfma_f32_16x16x32_bf16 v[86:89], v[178:181], v[220:223], v[86:89]
	v_mfma_f32_16x16x32_bf16 v[82:85], v[186:189], v[220:223], v[82:85]
	v_mfma_f32_16x16x32_bf16 v[70:73], v[178:181], v[228:231], v[70:73]
	v_mfma_f32_16x16x32_bf16 v[66:69], v[186:189], v[228:231], v[66:69]
	s_setprio 0
	s_setprio 1
	v_mfma_f32_16x16x32_bf16 v[118:121], v[182:185], v[208:211], v[118:121]
	v_mfma_f32_16x16x32_bf16 v[114:117], v[190:193], v[208:211], v[114:117]
	v_mfma_f32_16x16x32_bf16 v[102:105], v[182:185], v[216:219], v[102:105]
	v_mfma_f32_16x16x32_bf16 v[98:101], v[190:193], v[216:219], v[98:101]
	v_mfma_f32_16x16x32_bf16 v[86:89], v[182:185], v[224:227], v[86:89]
	v_mfma_f32_16x16x32_bf16 v[82:85], v[190:193], v[224:227], v[82:85]
	v_mfma_f32_16x16x32_bf16 v[70:73], v[182:185], v[232:235], v[70:73]
	v_mfma_f32_16x16x32_bf16 v[66:69], v[190:193], v[232:235], v[66:69]
	s_setprio 0
	s_barrier
	s_add_i32 s46, s46, s28
	s_mov_b32 m0, s46
	ds_read_b128 v[194:197], v147 offset:16384
	ds_read_b128 v[208:211], v147 offset:17408
	ds_read_b128 v[212:215], v147 offset:18432
	ds_read_b128 v[216:219], v147 offset:19456
	ds_read_b128 v[220:223], v147 offset:20480
	ds_read_b128 v[224:227], v147 offset:21504
	ds_read_b128 v[228:231], v147 offset:22528
	ds_read_b128 v[232:235], v147 offset:23552
	global_load_lds_dwordx4 v64, s[16:17]
	s_add_i32 m0, s46, 0x2000
	s_add_u32 s46, s16, 0x80000
	s_addc_u32 s47, s17, 0
	s_add_i32 s48, s48, s28
	global_load_lds_dwordx4 v130, s[16:17]
	s_mov_b32 m0, s48
	s_mov_b64 s[100:101], s[18:19]
	global_load_lds_dwordx4 v64, s[46:47]
	s_add_i32 m0, s48, 0x2000
	s_nop 0
	global_load_lds_dwordx4 v130, s[46:47]
	s_mov_b32 m0, s15
	s_nop 0
	global_load_lds_dwordx4 v134, s[18:19]
	s_mov_b32 m0, s27
	s_nop 0
	global_load_lds_dwordx4 v132, s[18:19]
	s_waitcnt vmcnt(8)
	s_waitcnt lgkmcnt(0)
	s_setprio 1
	s_barrier
	s_waitcnt lgkmcnt(0)
	v_mfma_f32_16x16x32_bf16 v[60:63], v[140:143], v[194:197], v[60:63]
	v_mfma_f32_16x16x32_bf16 v[56:59], v[152:155], v[194:197], v[56:59]
	v_mfma_f32_16x16x32_bf16 v[44:47], v[140:143], v[212:215], v[44:47]
	v_mfma_f32_16x16x32_bf16 v[40:43], v[152:155], v[212:215], v[40:43]
	v_mfma_f32_16x16x32_bf16 v[28:31], v[140:143], v[220:223], v[28:31]
	v_mfma_f32_16x16x32_bf16 v[24:27], v[152:155], v[220:223], v[24:27]
	v_mfma_f32_16x16x32_bf16 v[12:15], v[140:143], v[228:231], v[12:15]
	v_mfma_f32_16x16x32_bf16 v[8:11], v[152:155], v[228:231], v[8:11]
	s_setprio 0
	s_setprio 1
	v_mfma_f32_16x16x32_bf16 v[60:63], v[148:151], v[208:211], v[60:63]
	v_mfma_f32_16x16x32_bf16 v[56:59], v[156:159], v[208:211], v[56:59]
	v_mfma_f32_16x16x32_bf16 v[44:47], v[148:151], v[216:219], v[44:47]
	v_mfma_f32_16x16x32_bf16 v[40:43], v[156:159], v[216:219], v[40:43]
	v_mfma_f32_16x16x32_bf16 v[28:31], v[148:151], v[224:227], v[28:31]
	v_mfma_f32_16x16x32_bf16 v[24:27], v[156:159], v[224:227], v[24:27]
	v_mfma_f32_16x16x32_bf16 v[12:15], v[148:151], v[232:235], v[12:15]
	v_mfma_f32_16x16x32_bf16 v[8:11], v[156:159], v[232:235], v[8:11]
	s_setprio 0
	s_setprio 1
	v_mfma_f32_16x16x32_bf16 v[52:55], v[178:181], v[194:197], v[52:55]
	v_mfma_f32_16x16x32_bf16 v[48:51], v[186:189], v[194:197], v[48:51]
	v_mfma_f32_16x16x32_bf16 v[36:39], v[178:181], v[212:215], v[36:39]
	v_mfma_f32_16x16x32_bf16 v[32:35], v[186:189], v[212:215], v[32:35]
	v_mfma_f32_16x16x32_bf16 v[20:23], v[178:181], v[220:223], v[20:23]
	v_mfma_f32_16x16x32_bf16 v[16:19], v[186:189], v[220:223], v[16:19]
	v_mfma_f32_16x16x32_bf16 v[4:7], v[178:181], v[228:231], v[4:7]
	v_mfma_f32_16x16x32_bf16 v[0:3], v[186:189], v[228:231], v[0:3]
	s_setprio 0
	s_setprio 1
	v_mfma_f32_16x16x32_bf16 v[52:55], v[182:185], v[208:211], v[52:55]
	v_mfma_f32_16x16x32_bf16 v[48:51], v[190:193], v[208:211], v[48:51]
	v_mfma_f32_16x16x32_bf16 v[36:39], v[182:185], v[216:219], v[36:39]
	v_mfma_f32_16x16x32_bf16 v[32:35], v[190:193], v[216:219], v[32:35]
	v_mfma_f32_16x16x32_bf16 v[20:23], v[182:185], v[224:227], v[20:23]
	v_mfma_f32_16x16x32_bf16 v[16:19], v[190:193], v[224:227], v[16:19]
	v_mfma_f32_16x16x32_bf16 v[4:7], v[182:185], v[232:235], v[4:7]
	v_mfma_f32_16x16x32_bf16 v[0:3], v[190:193], v[232:235], v[0:3]
	s_setprio 0
	s_barrier
; #define PG8_STAGE(bufoff, gbase, voff) do { _Pragma("unroll") for (int _i = 0; _i < 2; ++_i) \
;         __builtin_amdgcn_global_load_lds((const unsigned*)((const char*)(gbase) + (voff)[_i]), (PG8_LAS unsigned*)(lds + (bufoff) + ldsw + _i * 8192), 16, 0, 0); } while (0)
; #define PG8_LDA(dst, b, h) do { _Pragma("unroll") for (int m = 0; m < 4; ++m) _Pragma("unroll") for (int k = 0; k < 2; ++k) dst[m][k] = *(const PG8_LAS bf16x8*)(lds + PG8_SA(b, h) + aoff + m * 2048 + k * 1024); } while (0)
; #define PG8_LDB(dst, b, h) do { _Pragma("unroll") for (int n = 0; n < 2; ++n) _Pragma("unroll") for (int k = 0; k < 2; ++k) dst[n][k] = *(const PG8_LAS bf16x8*)(lds + PG8_SB(b, h) + boff + n * 2048 + k * 1024); } while (0)
; #define PG8_MMA(ai, bj, At, Bt) do { __builtin_amdgcn_s_setprio(1); _Pragma("unroll") for (int m = 0; m < 4; ++m) _Pragma("unroll") for (int n = 0; n < 2; ++n) _Pragma("unroll") for (int k = 0; k < 2; ++k) \
;         acc[ai][bj][m][n] = __builtin_amdgcn_mfma_f32_16x16x32_bf16(Bt[n][k], At[m][k], acc[ai][bj][m][n], 0, 0, 0); __builtin_amdgcn_s_setprio(0); } while (0)
; #define PG8_WAIT_V(n) asm volatile("s_waitcnt vmcnt(" #n ")" ::: "memory")
; #define PG8_WAIT_L(n) asm volatile("s_waitcnt lgkmcnt(" #n ")" ::: "memory")
; #define PG8_BAR __builtin_amdgcn_s_barrier()
; #define PG8_SCHED __builtin_amdgcn_sched_barrier(0)
; template <class Epi, class Sched, bool ALIGN_EPI = false, bool SP2 = false>
; __device__ __forceinline__ void gemm_phase(PG8_LAS unsigned char* lds, const Gemm g, const Sched& S, const Epi& E, const int wave0) {
;     ...
;             PG8_LDB(B0, 1, 0); PG8_LDB(B1, 1, 1); PG8_SCHED; PG8_LDA(At, 1, 0); PG8_STAGE(PG8_SA(0, 1), a2 + hstepA, voffA);
;             PG8_WAIT_V(8); PG8_WAIT_L(0); PG8_BAR; PG8_MMA(0, 0, At, B0); PG8_MMA(0, 1, At, B1); PG8_BAR; PG8_SCHED;
;             PG8_LDA(At, 1, 1); PG8_STAGE(PG8_SB(1, 0), b3, voffB); PG8_STAGE(PG8_SB(1, 1), b3 + hstepB, voffB); PG8_STAGE(PG8_SA(1, 0), a3, voffA);
;             PG8_WAIT_V(8); PG8_WAIT_L(0); PG8_BAR; PG8_MMA(1, 0, At, B0); PG8_MMA(1, 1, At, B1); PG8_BAR; PG8_SCHED;
	s_add_i32 s46, 0, 0x18000
	s_add_i32 s47, 0, 0x1c000
	ds_read_b128 v[140:143], v254
	ds_read_b128 v[148:151], v254 offset:1024
	ds_read_b128 v[152:155], v254 offset:2048
	ds_read_b128 v[156:159], v254 offset:3072
	ds_read_b128 v[178:181], v255
	ds_read_b128 v[182:185], v255 offset:1024
	ds_read_b128 v[186:189], v255 offset:2048
	ds_read_b128 v[190:193], v255 offset:3072
	s_add_u32 s18, s18, 0x80000
	s_addc_u32 s19, s19, 0
	s_mov_b32 m0, s29
	ds_read_b128 v[194:197], v147 offset:32768
	ds_read_b128 v[208:211], v147 offset:33792
	ds_read_b128 v[212:215], v147 offset:34816
	ds_read_b128 v[216:219], v147 offset:35840
	ds_read_b128 v[220:223], v147 offset:36864
	ds_read_b128 v[224:227], v147 offset:37888
	ds_read_b128 v[228:231], v147 offset:38912
	ds_read_b128 v[232:235], v147 offset:39936
	global_load_lds_dwordx4 v134, s[18:19]
	s_mov_b32 m0, s30
	s_nop 0
	global_load_lds_dwordx4 v132, s[18:19]
	s_waitcnt vmcnt(8)
	s_waitcnt lgkmcnt(0)
	s_setprio 1
	s_barrier
	s_waitcnt lgkmcnt(0)
	v_mfma_f32_16x16x32_bf16 v[126:129], v[140:143], v[194:197], v[126:129]
	v_mfma_f32_16x16x32_bf16 v[122:125], v[152:155], v[194:197], v[122:125]
	v_mfma_f32_16x16x32_bf16 v[110:113], v[140:143], v[212:215], v[110:113]
	v_mfma_f32_16x16x32_bf16 v[106:109], v[152:155], v[212:215], v[106:109]
	v_mfma_f32_16x16x32_bf16 v[94:97], v[140:143], v[220:223], v[94:97]
	v_mfma_f32_16x16x32_bf16 v[90:93], v[152:155], v[220:223], v[90:93]
	v_mfma_f32_16x16x32_bf16 v[78:81], v[140:143], v[228:231], v[78:81]
	v_mfma_f32_16x16x32_bf16 v[74:77], v[152:155], v[228:231], v[74:77]
	s_setprio 0
	s_setprio 1
	v_mfma_f32_16x16x32_bf16 v[126:129], v[148:151], v[208:211], v[126:129]
	v_mfma_f32_16x16x32_bf16 v[122:125], v[156:159], v[208:211], v[122:125]
	v_mfma_f32_16x16x32_bf16 v[110:113], v[148:151], v[216:219], v[110:113]
	v_mfma_f32_16x16x32_bf16 v[106:109], v[156:159], v[216:219], v[106:109]
	v_mfma_f32_16x16x32_bf16 v[94:97], v[148:151], v[224:227], v[94:97]
	v_mfma_f32_16x16x32_bf16 v[90:93], v[156:159], v[224:227], v[90:93]
	v_mfma_f32_16x16x32_bf16 v[78:81], v[148:151], v[232:235], v[78:81]
	v_mfma_f32_16x16x32_bf16 v[74:77], v[156:159], v[232:235], v[74:77]
	s_setprio 0
	s_setprio 1
	v_mfma_f32_16x16x32_bf16 v[118:121], v[178:181], v[194:197], v[118:121]
	v_mfma_f32_16x16x32_bf16 v[114:117], v[186:189], v[194:197], v[114:117]
	v_mfma_f32_16x16x32_bf16 v[102:105], v[178:181], v[212:215], v[102:105]
	v_mfma_f32_16x16x32_bf16 v[98:101], v[186:189], v[212:215], v[98:101]
	v_mfma_f32_16x16x32_bf16 v[86:89], v[178:181], v[220:223], v[86:89]
	v_mfma_f32_16x16x32_bf16 v[82:85], v[186:189], v[220:223], v[82:85]
	v_mfma_f32_16x16x32_bf16 v[70:73], v[178:181], v[228:231], v[70:73]
	v_mfma_f32_16x16x32_bf16 v[66:69], v[186:189], v[228:231], v[66:69]
	s_setprio 0
	s_setprio 1
	v_mfma_f32_16x16x32_bf16 v[118:121], v[182:185], v[208:211], v[118:121]
	v_mfma_f32_16x16x32_bf16 v[114:117], v[190:193], v[208:211], v[114:117]
	v_mfma_f32_16x16x32_bf16 v[102:105], v[182:185], v[216:219], v[102:105]
	v_mfma_f32_16x16x32_bf16 v[98:101], v[190:193], v[216:219], v[98:101]
	v_mfma_f32_16x16x32_bf16 v[86:89], v[182:185], v[224:227], v[86:89]
	v_mfma_f32_16x16x32_bf16 v[82:85], v[190:193], v[224:227], v[82:85]
	v_mfma_f32_16x16x32_bf16 v[70:73], v[182:185], v[232:235], v[70:73]
	v_mfma_f32_16x16x32_bf16 v[66:69], v[190:193], v[232:235], v[66:69]
	s_setprio 0
	s_barrier
	s_add_i32 s18, s46, s28
	s_add_u32 s50, s16, 0x80
	s_addc_u32 s51, s17, 0
	s_mov_b32 m0, s18
	ds_read_b128 v[194:197], v147 offset:49152
	ds_read_b128 v[208:211], v147 offset:50176
	ds_read_b128 v[212:215], v147 offset:51200
	ds_read_b128 v[216:219], v147 offset:52224
	ds_read_b128 v[220:223], v147 offset:53248
	ds_read_b128 v[224:227], v147 offset:54272
	ds_read_b128 v[228:231], v147 offset:55296
	ds_read_b128 v[232:235], v147 offset:56320
	global_load_lds_dwordx4 v64, s[50:51]
	s_add_i32 m0, s18, 0x2000
	s_add_u32 s16, s16, 0x80080
	s_addc_u32 s17, s17, 0
	s_add_i32 s18, s47, s28
	global_load_lds_dwordx4 v130, s[50:51]
	s_mov_b32 m0, s18
	s_nop 0
	global_load_lds_dwordx4 v64, s[16:17]
	s_add_i32 m0, s18, 0x2000
	s_nop 0
	global_load_lds_dwordx4 v130, s[16:17]
	s_add_u32 s100, s100, 0x80
	s_addc_u32 s101, s101, 0
	s_mov_b32 m0, s31
	s_nop 0
	global_load_lds_dwordx4 v134, s[100:101]
	s_mov_b32 m0, s34
	s_nop 0
	global_load_lds_dwordx4 v132, s[100:101]
	s_waitcnt vmcnt(8)
	s_waitcnt lgkmcnt(0)
	s_setprio 1
	s_barrier
	s_waitcnt lgkmcnt(0)
	v_mfma_f32_16x16x32_bf16 v[60:63], v[140:143], v[194:197], v[60:63]
	v_mfma_f32_16x16x32_bf16 v[56:59], v[152:155], v[194:197], v[56:59]
	v_mfma_f32_16x16x32_bf16 v[44:47], v[140:143], v[212:215], v[44:47]
	v_mfma_f32_16x16x32_bf16 v[40:43], v[152:155], v[212:215], v[40:43]
	v_mfma_f32_16x16x32_bf16 v[28:31], v[140:143], v[220:223], v[28:31]
	v_mfma_f32_16x16x32_bf16 v[24:27], v[152:155], v[220:223], v[24:27]
	v_mfma_f32_16x16x32_bf16 v[12:15], v[140:143], v[228:231], v[12:15]
	v_mfma_f32_16x16x32_bf16 v[8:11], v[152:155], v[228:231], v[8:11]
	s_setprio 0
	s_setprio 1
	v_mfma_f32_16x16x32_bf16 v[60:63], v[148:151], v[208:211], v[60:63]
	v_mfma_f32_16x16x32_bf16 v[56:59], v[156:159], v[208:211], v[56:59]
	v_mfma_f32_16x16x32_bf16 v[44:47], v[148:151], v[216:219], v[44:47]
	v_mfma_f32_16x16x32_bf16 v[40:43], v[156:159], v[216:219], v[40:43]
	v_mfma_f32_16x16x32_bf16 v[28:31], v[148:151], v[224:227], v[28:31]
	v_mfma_f32_16x16x32_bf16 v[24:27], v[156:159], v[224:227], v[24:27]
	v_mfma_f32_16x16x32_bf16 v[12:15], v[148:151], v[232:235], v[12:15]
	v_mfma_f32_16x16x32_bf16 v[8:11], v[156:159], v[232:235], v[8:11]
	s_setprio 0
	s_setprio 1
	v_mfma_f32_16x16x32_bf16 v[52:55], v[178:181], v[194:197], v[52:55]
	v_mfma_f32_16x16x32_bf16 v[48:51], v[186:189], v[194:197], v[48:51]
	v_mfma_f32_16x16x32_bf16 v[36:39], v[178:181], v[212:215], v[36:39]
	v_mfma_f32_16x16x32_bf16 v[32:35], v[186:189], v[212:215], v[32:35]
	v_mfma_f32_16x16x32_bf16 v[20:23], v[178:181], v[220:223], v[20:23]
	v_mfma_f32_16x16x32_bf16 v[16:19], v[186:189], v[220:223], v[16:19]
	v_mfma_f32_16x16x32_bf16 v[4:7], v[178:181], v[228:231], v[4:7]
	v_mfma_f32_16x16x32_bf16 v[0:3], v[186:189], v[228:231], v[0:3]
	s_setprio 0
	s_setprio 1
	v_mfma_f32_16x16x32_bf16 v[52:55], v[182:185], v[208:211], v[52:55]
	v_mfma_f32_16x16x32_bf16 v[48:51], v[190:193], v[208:211], v[48:51]
	v_mfma_f32_16x16x32_bf16 v[36:39], v[182:185], v[216:219], v[36:39]
	v_mfma_f32_16x16x32_bf16 v[32:35], v[190:193], v[216:219], v[32:35]
	v_mfma_f32_16x16x32_bf16 v[20:23], v[182:185], v[224:227], v[20:23]
	v_mfma_f32_16x16x32_bf16 v[16:19], v[190:193], v[224:227], v[16:19]
	v_mfma_f32_16x16x32_bf16 v[4:7], v[182:185], v[232:235], v[4:7]
	v_mfma_f32_16x16x32_bf16 v[0:3], v[190:193], v[232:235], v[0:3]
	s_setprio 0
	s_barrier
	s_add_i32 s45, s45, 2
	s_add_u32 s0, s0, 0x100
	s_addc_u32 s1, s1, 0
	s_add_u32 s37, s37, 0x100
	s_addc_u32 s44, s44, 0
	s_cmp_gt_u32 s45, 29
	s_cbranch_scc0 .LBB0_1571
	s_mov_b64 s[50:51], 0x80
	s_and_b64 vcc, exec, s[4:5]
	s_cbranch_vccz .LBB0_1574
	s_barrier

; #define PG8_STAGE(bufoff, gbase, voff) do { _Pragma("unroll") for (int _i = 0; _i < 2; ++_i) \
;         __builtin_amdgcn_global_load_lds((const unsigned*)((const char*)(gbase) + (voff)[_i]), (PG8_LAS unsigned*)(lds + (bufoff) + ldsw + _i * 8192), 16, 0, 0); } while (0)
; #define PG8_LDA(dst, b, h) do { _Pragma("unroll") for (int m = 0; m < 4; ++m) _Pragma("unroll") for (int k = 0; k < 2; ++k) dst[m][k] = *(const PG8_LAS bf16x8*)(lds + PG8_SA(b, h) + aoff + m * 2048 + k * 1024); } while (0)
; #define PG8_LDB(dst, b, h) do { _Pragma("unroll") for (int n = 0; n < 2; ++n) _Pragma("unroll") for (int k = 0; k < 2; ++k) dst[n][k] = *(const PG8_LAS bf16x8*)(lds + PG8_SB(b, h) + boff + n * 2048 + k * 1024); } while (0)
; #define PG8_MMA(ai, bj, At, Bt) do { __builtin_amdgcn_s_setprio(1); _Pragma("unroll") for (int m = 0; m < 4; ++m) _Pragma("unroll") for (int n = 0; n < 2; ++n) _Pragma("unroll") for (int k = 0; k < 2; ++k) \
;         acc[ai][bj][m][n] = __builtin_amdgcn_mfma_f32_16x16x32_bf16(Bt[n][k], At[m][k], acc[ai][bj][m][n], 0, 0, 0); __builtin_amdgcn_s_setprio(0); } while (0)
; #define PG8_WAIT_V(n) asm volatile("s_waitcnt vmcnt(" #n ")" ::: "memory")
; #define PG8_WAIT_L(n) asm volatile("s_waitcnt lgkmcnt(" #n ")" ::: "memory")
; template <class Epi, class Sched, bool ALIGN_EPI = false, bool SP2 = false>
; __device__ __forceinline__ void gemm_phase(PG8_LAS unsigned char* lds, const Gemm g, const Sched& S, const Epi& E, const int wave0) {
;     ...
;             const bool last = (t == nt - 2);
;             const char* a1 = cA + (size_t)(t + 1) * kstep;
;             const char* a2 = last ? nA : cA + (size_t)(t + 2) * kstep; const char* b2 = last ? nB : cB + (size_t)(t + 2) * kstep;
;             const char* a3 = a2 + kstep; const char* b3 = b2 + kstep;
;             if (last && has_next) S.a_ready(nxt);
;             if constexpr (SP2) {
;             PG8_LDB(B0, 0, 0); PG8_LDB(B1, 0, 1); PG8_SCHED; PG8_LDA(At, 0, 0); PG8_STAGE(PG8_SA(1, 1), a1 + hstepA, voffA);
;             PG8_WAIT_V(8); PG8_WAIT_L(0); PG8_BAR; PG8_MMA(0, 0, At, B0); PG8_MMA(0, 1, At, B1); PG8_BAR; PG8_SCHED;
;             PG8_LDA(At, 0, 1); PG8_STAGE(PG8_SB(0, 0), b2, voffB); PG8_STAGE(PG8_SB(0, 1), b2 + hstepB, voffB); PG8_STAGE(PG8_SA(0, 0), a2, voffA);
;             PG8_WAIT_V(8); PG8_WAIT_L(0); PG8_BAR; PG8_MMA(1, 0, At, B0); PG8_MMA(1, 1, At, B1); PG8_BAR; PG8_SCHED;
.LBB0_1685:
	s_add_u32 s16, s0, 0xffe00080
	s_addc_u32 s17, s1, -1
	s_add_i32 s43, 0, 0x10000
	s_cmpk_eq_i32 s42, 0x7c
	s_cselect_b32 s19, s11, s17
	s_cselect_b32 s18, s34, s16
	s_cselect_b32 s17, s9, s37
	s_cselect_b32 s16, s35, s36
	s_add_i32 s46, 0, 0x14000
	ds_read_b128 v[144:147], v252
	ds_read_b128 v[148:151], v252 offset:1024
	ds_read_b128 v[152:155], v252 offset:2048
	ds_read_b128 v[156:159], v252 offset:3072
	ds_read_b128 v[178:181], v253
	ds_read_b128 v[182:185], v253 offset:1024
	ds_read_b128 v[186:189], v253 offset:2048
	ds_read_b128 v[190:193], v253 offset:3072
	s_add_i32 m0, s21, 0xc000
	ds_read_b128 v[194:197], v143
	ds_read_b128 v[208:211], v143 offset:1024
	ds_read_b128 v[212:215], v143 offset:2048
	ds_read_b128 v[216:219], v143 offset:3072
	ds_read_b128 v[220:223], v143 offset:4096
	ds_read_b128 v[224:227], v143 offset:5120
	ds_read_b128 v[228:231], v143 offset:6144
	ds_read_b128 v[232:235], v143 offset:7168
	global_load_lds_dwordx4 v136, s[0:1]
	s_add_i32 m0, s21, 0xe000
	s_nop 0
	global_load_lds_dwordx4 v138, s[0:1]
	s_waitcnt vmcnt(8)
	s_waitcnt lgkmcnt(0)
	s_setprio 1
	s_barrier
	s_waitcnt lgkmcnt(0)
	v_mfma_f32_16x16x32_bf16 v[126:129], v[144:147], v[194:197], v[126:129]
	v_mfma_f32_16x16x32_bf16 v[122:125], v[152:155], v[194:197], v[122:125]
	v_mfma_f32_16x16x32_bf16 v[118:121], v[144:147], v[212:215], v[118:121]
	v_mfma_f32_16x16x32_bf16 v[114:117], v[152:155], v[212:215], v[114:117]
	v_mfma_f32_16x16x32_bf16 v[102:105], v[144:147], v[220:223], v[102:105]
	v_mfma_f32_16x16x32_bf16 v[98:101], v[152:155], v[220:223], v[98:101]
	v_mfma_f32_16x16x32_bf16 v[86:89], v[144:147], v[228:231], v[86:89]
	v_mfma_f32_16x16x32_bf16 v[82:85], v[152:155], v[228:231], v[82:85]
	s_setprio 0
	s_setprio 1
	v_mfma_f32_16x16x32_bf16 v[126:129], v[148:151], v[208:211], v[126:129]
	v_mfma_f32_16x16x32_bf16 v[122:125], v[156:159], v[208:211], v[122:125]
	v_mfma_f32_16x16x32_bf16 v[118:121], v[148:151], v[216:219], v[118:121]
	v_mfma_f32_16x16x32_bf16 v[114:117], v[156:159], v[216:219], v[114:117]
	v_mfma_f32_16x16x32_bf16 v[102:105], v[148:151], v[224:227], v[102:105]
	v_mfma_f32_16x16x32_bf16 v[98:101], v[156:159], v[224:227], v[98:101]
	v_mfma_f32_16x16x32_bf16 v[86:89], v[148:151], v[232:235], v[86:89]
	v_mfma_f32_16x16x32_bf16 v[82:85], v[156:159], v[232:235], v[82:85]
	s_setprio 0
	s_setprio 1
	v_mfma_f32_16x16x32_bf16 v[110:113], v[178:181], v[194:197], v[110:113]
	v_mfma_f32_16x16x32_bf16 v[106:109], v[186:189], v[194:197], v[106:109]
	v_mfma_f32_16x16x32_bf16 v[94:97], v[178:181], v[212:215], v[94:97]
	v_mfma_f32_16x16x32_bf16 v[90:93], v[186:189], v[212:215], v[90:93]
	v_mfma_f32_16x16x32_bf16 v[78:81], v[178:181], v[220:223], v[78:81]
	v_mfma_f32_16x16x32_bf16 v[74:77], v[186:189], v[220:223], v[74:77]
	v_mfma_f32_16x16x32_bf16 v[70:73], v[178:181], v[228:231], v[70:73]
	v_mfma_f32_16x16x32_bf16 v[66:69], v[186:189], v[228:231], v[66:69]
	s_setprio 0
	s_setprio 1
	v_mfma_f32_16x16x32_bf16 v[110:113], v[182:185], v[208:211], v[110:113]
	v_mfma_f32_16x16x32_bf16 v[106:109], v[190:193], v[208:211], v[106:109]
	v_mfma_f32_16x16x32_bf16 v[94:97], v[182:185], v[216:219], v[94:97]
	v_mfma_f32_16x16x32_bf16 v[90:93], v[190:193], v[216:219], v[90:93]
	v_mfma_f32_16x16x32_bf16 v[78:81], v[182:185], v[224:227], v[78:81]
	v_mfma_f32_16x16x32_bf16 v[74:77], v[190:193], v[224:227], v[74:77]
	v_mfma_f32_16x16x32_bf16 v[70:73], v[182:185], v[232:235], v[70:73]
	v_mfma_f32_16x16x32_bf16 v[66:69], v[190:193], v[232:235], v[66:69]
	s_setprio 0
	s_barrier
	s_add_i32 s43, s43, s20
	s_mov_b32 m0, s43
	ds_read_b128 v[194:197], v143 offset:16384
	ds_read_b128 v[208:211], v143 offset:17408
	ds_read_b128 v[212:215], v143 offset:18432
	ds_read_b128 v[216:219], v143 offset:19456
	ds_read_b128 v[220:223], v143 offset:20480
	ds_read_b128 v[224:227], v143 offset:21504
	ds_read_b128 v[228:231], v143 offset:22528
	ds_read_b128 v[232:235], v143 offset:23552
	global_load_lds_dwordx4 v64, s[16:17]
	s_add_i32 m0, s43, 0x2000
	s_add_u32 s44, s16, 0x200000
	s_addc_u32 s45, s17, 0
	s_add_i32 s43, s46, s20
	global_load_lds_dwordx4 v130, s[16:17]
	s_mov_b32 m0, s43
	s_mov_b64 s[100:101], s[18:19]
	global_load_lds_dwordx4 v64, s[44:45]
	s_add_i32 m0, s43, 0x2000
	s_nop 0
	global_load_lds_dwordx4 v130, s[44:45]
	s_mov_b32 m0, s21
	s_nop 0
	global_load_lds_dwordx4 v134, s[18:19]
	s_mov_b32 m0, s25
	s_nop 0
	global_load_lds_dwordx4 v132, s[18:19]
	s_waitcnt vmcnt(8)
	s_waitcnt lgkmcnt(0)
	s_setprio 1
	s_barrier
	s_waitcnt lgkmcnt(0)
	v_mfma_f32_16x16x32_bf16 v[60:63], v[144:147], v[194:197], v[60:63]
	v_mfma_f32_16x16x32_bf16 v[56:59], v[152:155], v[194:197], v[56:59]
	v_mfma_f32_16x16x32_bf16 v[52:55], v[144:147], v[212:215], v[52:55]
	v_mfma_f32_16x16x32_bf16 v[48:51], v[152:155], v[212:215], v[48:51]
	v_mfma_f32_16x16x32_bf16 v[36:39], v[144:147], v[220:223], v[36:39]
	v_mfma_f32_16x16x32_bf16 v[32:35], v[152:155], v[220:223], v[32:35]
	v_mfma_f32_16x16x32_bf16 v[20:23], v[144:147], v[228:231], v[20:23]
	v_mfma_f32_16x16x32_bf16 v[16:19], v[152:155], v[228:231], v[16:19]
	s_setprio 0
	s_setprio 1
	v_mfma_f32_16x16x32_bf16 v[60:63], v[148:151], v[208:211], v[60:63]
	v_mfma_f32_16x16x32_bf16 v[56:59], v[156:159], v[208:211], v[56:59]
	v_mfma_f32_16x16x32_bf16 v[52:55], v[148:151], v[216:219], v[52:55]
	v_mfma_f32_16x16x32_bf16 v[48:51], v[156:159], v[216:219], v[48:51]
	v_mfma_f32_16x16x32_bf16 v[36:39], v[148:151], v[224:227], v[36:39]
	v_mfma_f32_16x16x32_bf16 v[32:35], v[156:159], v[224:227], v[32:35]
	v_mfma_f32_16x16x32_bf16 v[20:23], v[148:151], v[232:235], v[20:23]
	v_mfma_f32_16x16x32_bf16 v[16:19], v[156:159], v[232:235], v[16:19]
	s_setprio 0
	s_setprio 1
	v_mfma_f32_16x16x32_bf16 v[44:47], v[178:181], v[194:197], v[44:47]
	v_mfma_f32_16x16x32_bf16 v[40:43], v[186:189], v[194:197], v[40:43]
	v_mfma_f32_16x16x32_bf16 v[28:31], v[178:181], v[212:215], v[28:31]
	v_mfma_f32_16x16x32_bf16 v[24:27], v[186:189], v[212:215], v[24:27]
	v_mfma_f32_16x16x32_bf16 v[12:15], v[178:181], v[220:223], v[12:15]
	v_mfma_f32_16x16x32_bf16 v[8:11], v[186:189], v[220:223], v[8:11]
	v_mfma_f32_16x16x32_bf16 v[4:7], v[178:181], v[228:231], v[4:7]
	v_mfma_f32_16x16x32_bf16 v[0:3], v[186:189], v[228:231], v[0:3]
	s_setprio 0
	s_setprio 1
	v_mfma_f32_16x16x32_bf16 v[44:47], v[182:185], v[208:211], v[44:47]
	v_mfma_f32_16x16x32_bf16 v[40:43], v[190:193], v[208:211], v[40:43]
	v_mfma_f32_16x16x32_bf16 v[28:31], v[182:185], v[216:219], v[28:31]
	v_mfma_f32_16x16x32_bf16 v[24:27], v[190:193], v[216:219], v[24:27]
	v_mfma_f32_16x16x32_bf16 v[12:15], v[182:185], v[224:227], v[12:15]
	v_mfma_f32_16x16x32_bf16 v[8:11], v[190:193], v[224:227], v[8:11]
	v_mfma_f32_16x16x32_bf16 v[4:7], v[182:185], v[232:235], v[4:7]
	v_mfma_f32_16x16x32_bf16 v[0:3], v[190:193], v[232:235], v[0:3]
	s_setprio 0
	s_barrier
; #define PG8_STAGE(bufoff, gbase, voff) do { _Pragma("unroll") for (int _i = 0; _i < 2; ++_i) \
;         __builtin_amdgcn_global_load_lds((const unsigned*)((const char*)(gbase) + (voff)[_i]), (PG8_LAS unsigned*)(lds + (bufoff) + ldsw + _i * 8192), 16, 0, 0); } while (0)
; #define PG8_LDA(dst, b, h) do { _Pragma("unroll") for (int m = 0; m < 4; ++m) _Pragma("unroll") for (int k = 0; k < 2; ++k) dst[m][k] = *(const PG8_LAS bf16x8*)(lds + PG8_SA(b, h) + aoff + m * 2048 + k * 1024); } while (0)
; #define PG8_LDB(dst, b, h) do { _Pragma("unroll") for (int n = 0; n < 2; ++n) _Pragma("unroll") for (int k = 0; k < 2; ++k) dst[n][k] = *(const PG8_LAS bf16x8*)(lds + PG8_SB(b, h) + boff + n * 2048 + k * 1024); } while (0)
; #define PG8_MMA(ai, bj, At, Bt) do { __builtin_amdgcn_s_setprio(1); _Pragma("unroll") for (int m = 0; m < 4; ++m) _Pragma("unroll") for (int n = 0; n < 2; ++n) _Pragma("unroll") for (int k = 0; k < 2; ++k) \
;         acc[ai][bj][m][n] = __builtin_amdgcn_mfma_f32_16x16x32_bf16(Bt[n][k], At[m][k], acc[ai][bj][m][n], 0, 0, 0); __builtin_amdgcn_s_setprio(0); } while (0)
; #define PG8_WAIT_V(n) asm volatile("s_waitcnt vmcnt(" #n ")" ::: "memory")
; #define PG8_WAIT_L(n) asm volatile("s_waitcnt lgkmcnt(" #n ")" ::: "memory")
; #define PG8_BAR __builtin_amdgcn_s_barrier()
; #define PG8_SCHED __builtin_amdgcn_sched_barrier(0)
; template <class Epi, class Sched, bool ALIGN_EPI = false, bool SP2 = false>
; __device__ __forceinline__ void gemm_phase(PG8_LAS unsigned char* lds, const Gemm g, const Sched& S, const Epi& E, const int wave0) {
;     ...
;             PG8_LDB(B0, 1, 0); PG8_LDB(B1, 1, 1); PG8_SCHED; PG8_LDA(At, 1, 0); PG8_STAGE(PG8_SA(0, 1), a2 + hstepA, voffA);
;             PG8_WAIT_V(8); PG8_WAIT_L(0); PG8_BAR; PG8_MMA(0, 0, At, B0); PG8_MMA(0, 1, At, B1); PG8_BAR; PG8_SCHED;
;             PG8_LDA(At, 1, 1); PG8_STAGE(PG8_SB(1, 0), b3, voffB); PG8_STAGE(PG8_SB(1, 1), b3 + hstepB, voffB); PG8_STAGE(PG8_SA(1, 0), a3, voffA);
;             PG8_WAIT_V(8); PG8_WAIT_L(0); PG8_BAR; PG8_MMA(1, 0, At, B0); PG8_MMA(1, 1, At, B1); PG8_BAR; PG8_SCHED;
	s_add_i32 s43, 0, 0x18000
	s_add_i32 s44, 0, 0x1c000
	ds_read_b128 v[144:147], v254
	ds_read_b128 v[148:151], v254 offset:1024
	ds_read_b128 v[152:155], v254 offset:2048
	ds_read_b128 v[156:159], v254 offset:3072
	ds_read_b128 v[178:181], v255
	ds_read_b128 v[182:185], v255 offset:1024
	ds_read_b128 v[186:189], v255 offset:2048
	ds_read_b128 v[190:193], v255 offset:3072
	s_add_u32 s18, s18, 0x200000
	s_addc_u32 s19, s19, 0
	s_mov_b32 m0, s26
	ds_read_b128 v[194:197], v143 offset:32768
	ds_read_b128 v[208:211], v143 offset:33792
	ds_read_b128 v[212:215], v143 offset:34816
	ds_read_b128 v[216:219], v143 offset:35840
	ds_read_b128 v[220:223], v143 offset:36864
	ds_read_b128 v[224:227], v143 offset:37888
	ds_read_b128 v[228:231], v143 offset:38912
	ds_read_b128 v[232:235], v143 offset:39936
	global_load_lds_dwordx4 v134, s[18:19]
	s_mov_b32 m0, s27
	s_nop 0
	global_load_lds_dwordx4 v132, s[18:19]
	s_waitcnt vmcnt(8)
	s_waitcnt lgkmcnt(0)
	s_setprio 1
	s_barrier
	s_waitcnt lgkmcnt(0)
	v_mfma_f32_16x16x32_bf16 v[126:129], v[144:147], v[194:197], v[126:129]
	v_mfma_f32_16x16x32_bf16 v[122:125], v[152:155], v[194:197], v[122:125]
	v_mfma_f32_16x16x32_bf16 v[118:121], v[144:147], v[212:215], v[118:121]
	v_mfma_f32_16x16x32_bf16 v[114:117], v[152:155], v[212:215], v[114:117]
	v_mfma_f32_16x16x32_bf16 v[102:105], v[144:147], v[220:223], v[102:105]
	v_mfma_f32_16x16x32_bf16 v[98:101], v[152:155], v[220:223], v[98:101]
	v_mfma_f32_16x16x32_bf16 v[86:89], v[144:147], v[228:231], v[86:89]
	v_mfma_f32_16x16x32_bf16 v[82:85], v[152:155], v[228:231], v[82:85]
	s_setprio 0
	s_setprio 1
	v_mfma_f32_16x16x32_bf16 v[126:129], v[148:151], v[208:211], v[126:129]
	v_mfma_f32_16x16x32_bf16 v[122:125], v[156:159], v[208:211], v[122:125]
	v_mfma_f32_16x16x32_bf16 v[118:121], v[148:151], v[216:219], v[118:121]
	v_mfma_f32_16x16x32_bf16 v[114:117], v[156:159], v[216:219], v[114:117]
	v_mfma_f32_16x16x32_bf16 v[102:105], v[148:151], v[224:227], v[102:105]
	v_mfma_f32_16x16x32_bf16 v[98:101], v[156:159], v[224:227], v[98:101]
	v_mfma_f32_16x16x32_bf16 v[86:89], v[148:151], v[232:235], v[86:89]
	v_mfma_f32_16x16x32_bf16 v[82:85], v[156:159], v[232:235], v[82:85]
	s_setprio 0
	s_setprio 1
	v_mfma_f32_16x16x32_bf16 v[110:113], v[178:181], v[194:197], v[110:113]
	v_mfma_f32_16x16x32_bf16 v[106:109], v[186:189], v[194:197], v[106:109]
	v_mfma_f32_16x16x32_bf16 v[94:97], v[178:181], v[212:215], v[94:97]
	v_mfma_f32_16x16x32_bf16 v[90:93], v[186:189], v[212:215], v[90:93]
	v_mfma_f32_16x16x32_bf16 v[78:81], v[178:181], v[220:223], v[78:81]
	v_mfma_f32_16x16x32_bf16 v[74:77], v[186:189], v[220:223], v[74:77]
	v_mfma_f32_16x16x32_bf16 v[70:73], v[178:181], v[228:231], v[70:73]
	v_mfma_f32_16x16x32_bf16 v[66:69], v[186:189], v[228:231], v[66:69]
	s_setprio 0
	s_setprio 1
	v_mfma_f32_16x16x32_bf16 v[110:113], v[182:185], v[208:211], v[110:113]
	v_mfma_f32_16x16x32_bf16 v[106:109], v[190:193], v[208:211], v[106:109]
	v_mfma_f32_16x16x32_bf16 v[94:97], v[182:185], v[216:219], v[94:97]
	v_mfma_f32_16x16x32_bf16 v[90:93], v[190:193], v[216:219], v[90:93]
	v_mfma_f32_16x16x32_bf16 v[78:81], v[182:185], v[224:227], v[78:81]
	v_mfma_f32_16x16x32_bf16 v[74:77], v[190:193], v[224:227], v[74:77]
	v_mfma_f32_16x16x32_bf16 v[70:73], v[182:185], v[232:235], v[70:73]
	v_mfma_f32_16x16x32_bf16 v[66:69], v[190:193], v[232:235], v[66:69]
	s_setprio 0
	s_barrier
	s_add_i32 s18, s43, s20
	s_add_u32 s48, s16, 0x80
	s_addc_u32 s49, s17, 0
	s_mov_b32 m0, s18
	ds_read_b128 v[194:197], v143 offset:49152
	ds_read_b128 v[208:211], v143 offset:50176
	ds_read_b128 v[212:215], v143 offset:51200
	ds_read_b128 v[216:219], v143 offset:52224
	ds_read_b128 v[220:223], v143 offset:53248
	ds_read_b128 v[224:227], v143 offset:54272
	ds_read_b128 v[228:231], v143 offset:55296
	ds_read_b128 v[232:235], v143 offset:56320
	global_load_lds_dwordx4 v64, s[48:49]
	s_add_i32 m0, s18, 0x2000
	s_add_u32 s16, s16, 0x200080
	s_addc_u32 s17, s17, 0
	s_add_i32 s18, s44, s20
	global_load_lds_dwordx4 v130, s[48:49]
	s_mov_b32 m0, s18
	s_nop 0
	global_load_lds_dwordx4 v64, s[16:17]
	s_add_i32 m0, s18, 0x2000
	s_nop 0
	global_load_lds_dwordx4 v130, s[16:17]
	s_add_u32 s100, s100, 0x80
	s_addc_u32 s101, s101, 0
	s_mov_b32 m0, s28
	s_nop 0
	global_load_lds_dwordx4 v134, s[100:101]
	s_mov_b32 m0, s29
	s_nop 0
	global_load_lds_dwordx4 v132, s[100:101]
	s_waitcnt vmcnt(8)
	s_waitcnt lgkmcnt(0)
	s_setprio 1
	s_barrier
	s_waitcnt lgkmcnt(0)
	v_mfma_f32_16x16x32_bf16 v[60:63], v[144:147], v[194:197], v[60:63]
	v_mfma_f32_16x16x32_bf16 v[56:59], v[152:155], v[194:197], v[56:59]
	v_mfma_f32_16x16x32_bf16 v[52:55], v[144:147], v[212:215], v[52:55]
	v_mfma_f32_16x16x32_bf16 v[48:51], v[152:155], v[212:215], v[48:51]
	v_mfma_f32_16x16x32_bf16 v[36:39], v[144:147], v[220:223], v[36:39]
	v_mfma_f32_16x16x32_bf16 v[32:35], v[152:155], v[220:223], v[32:35]
	v_mfma_f32_16x16x32_bf16 v[20:23], v[144:147], v[228:231], v[20:23]
	v_mfma_f32_16x16x32_bf16 v[16:19], v[152:155], v[228:231], v[16:19]
	s_setprio 0
	s_setprio 1
	v_mfma_f32_16x16x32_bf16 v[60:63], v[148:151], v[208:211], v[60:63]
	v_mfma_f32_16x16x32_bf16 v[56:59], v[156:159], v[208:211], v[56:59]
	v_mfma_f32_16x16x32_bf16 v[52:55], v[148:151], v[216:219], v[52:55]
	v_mfma_f32_16x16x32_bf16 v[48:51], v[156:159], v[216:219], v[48:51]
	v_mfma_f32_16x16x32_bf16 v[36:39], v[148:151], v[224:227], v[36:39]
	v_mfma_f32_16x16x32_bf16 v[32:35], v[156:159], v[224:227], v[32:35]
	v_mfma_f32_16x16x32_bf16 v[20:23], v[148:151], v[232:235], v[20:23]
	v_mfma_f32_16x16x32_bf16 v[16:19], v[156:159], v[232:235], v[16:19]
	s_setprio 0
	s_setprio 1
	v_mfma_f32_16x16x32_bf16 v[44:47], v[178:181], v[194:197], v[44:47]
	v_mfma_f32_16x16x32_bf16 v[40:43], v[186:189], v[194:197], v[40:43]
	v_mfma_f32_16x16x32_bf16 v[28:31], v[178:181], v[212:215], v[28:31]
	v_mfma_f32_16x16x32_bf16 v[24:27], v[186:189], v[212:215], v[24:27]
	v_mfma_f32_16x16x32_bf16 v[12:15], v[178:181], v[220:223], v[12:15]
	v_mfma_f32_16x16x32_bf16 v[8:11], v[186:189], v[220:223], v[8:11]
	v_mfma_f32_16x16x32_bf16 v[4:7], v[178:181], v[228:231], v[4:7]
	v_mfma_f32_16x16x32_bf16 v[0:3], v[186:189], v[228:231], v[0:3]
	s_setprio 0
	s_setprio 1
	v_mfma_f32_16x16x32_bf16 v[44:47], v[182:185], v[208:211], v[44:47]
	v_mfma_f32_16x16x32_bf16 v[40:43], v[190:193], v[208:211], v[40:43]
	v_mfma_f32_16x16x32_bf16 v[28:31], v[182:185], v[216:219], v[28:31]
	v_mfma_f32_16x16x32_bf16 v[24:27], v[190:193], v[216:219], v[24:27]
	v_mfma_f32_16x16x32_bf16 v[12:15], v[182:185], v[224:227], v[12:15]
	v_mfma_f32_16x16x32_bf16 v[8:11], v[190:193], v[224:227], v[8:11]
	v_mfma_f32_16x16x32_bf16 v[4:7], v[182:185], v[232:235], v[4:7]
	v_mfma_f32_16x16x32_bf16 v[0:3], v[190:193], v[232:235], v[0:3]
	s_setprio 0
	s_barrier
	s_add_i32 s42, s42, 2
	s_add_u32 s0, s0, 0x100
	s_addc_u32 s1, s1, 0
	s_add_u32 s36, s36, 0x100
	s_addc_u32 s37, s37, 0
	s_cmpk_gt_u32 s42, 0x7d
	s_cbranch_scc0 .LBB0_1685
	s_mov_b64 s[48:49], 0x80
	s_and_b64 vcc, exec, s[6:7]
	s_mov_b64 s[34:35], 0x45000
	s_cbranch_vccz .LBB0_1688
	s_barrier

; #define PG8_STAGE(bufoff, gbase, voff) do { _Pragma("unroll") for (int _i = 0; _i < 2; ++_i) \
;         __builtin_amdgcn_global_load_lds((const unsigned*)((const char*)(gbase) + (voff)[_i]), (PG8_LAS unsigned*)(lds + (bufoff) + ldsw + _i * 8192), 16, 0, 0); } while (0)
; #define PG8_LDA(dst, b, h) do { _Pragma("unroll") for (int m = 0; m < 4; ++m) _Pragma("unroll") for (int k = 0; k < 2; ++k) dst[m][k] = *(const PG8_LAS bf16x8*)(lds + PG8_SA(b, h) + aoff + m * 2048 + k * 1024); } while (0)
; #define PG8_LDB(dst, b, h) do { _Pragma("unroll") for (int n = 0; n < 2; ++n) _Pragma("unroll") for (int k = 0; k < 2; ++k) dst[n][k] = *(const PG8_LAS bf16x8*)(lds + PG8_SB(b, h) + boff + n * 2048 + k * 1024); } while (0)
; #define PG8_MMA(ai, bj, At, Bt) do { __builtin_amdgcn_s_setprio(1); _Pragma("unroll") for (int m = 0; m < 4; ++m) _Pragma("unroll") for (int n = 0; n < 2; ++n) _Pragma("unroll") for (int k = 0; k < 2; ++k) \
;         acc[ai][bj][m][n] = __builtin_amdgcn_mfma_f32_16x16x32_bf16(Bt[n][k], At[m][k], acc[ai][bj][m][n], 0, 0, 0); __builtin_amdgcn_s_setprio(0); } while (0)
; #define PG8_WAIT_V(n) asm volatile("s_waitcnt vmcnt(" #n ")" ::: "memory")
; #define PG8_WAIT_L(n) asm volatile("s_waitcnt lgkmcnt(" #n ")" ::: "memory")
; template <class Epi, class Sched, bool ALIGN_EPI = false, bool SP2 = false>
; __device__ __forceinline__ void gemm_phase(PG8_LAS unsigned char* lds, const Gemm g, const Sched& S, const Epi& E, const int wave0) {
;     ...
;             const bool last = (t == nt - 2);
;             const char* a1 = cA + (size_t)(t + 1) * kstep;
;             const char* a2 = last ? nA : cA + (size_t)(t + 2) * kstep; const char* b2 = last ? nB : cB + (size_t)(t + 2) * kstep;
;             const char* a3 = a2 + kstep; const char* b3 = b2 + kstep;
;             if (last && has_next) S.a_ready(nxt);
;             if constexpr (SP2) {
;             PG8_LDB(B0, 0, 0); PG8_LDB(B1, 0, 1); PG8_SCHED; PG8_LDA(At, 0, 0); PG8_STAGE(PG8_SA(1, 1), a1 + hstepA, voffA);
;             PG8_WAIT_V(8); PG8_WAIT_L(0); PG8_BAR; PG8_MMA(0, 0, At, B0); PG8_MMA(0, 1, At, B1); PG8_BAR; PG8_SCHED;
;             PG8_LDA(At, 0, 1); PG8_STAGE(PG8_SB(0, 0), b2, voffB); PG8_STAGE(PG8_SB(0, 1), b2 + hstepB, voffB); PG8_STAGE(PG8_SA(0, 0), a2, voffA);
;             PG8_WAIT_V(8); PG8_WAIT_L(0); PG8_BAR; PG8_MMA(1, 0, At, B0); PG8_MMA(1, 1, At, B1); PG8_BAR; PG8_SCHED;
.LBB0_1702:
	s_add_u32 s18, s16, 0xffe00080
	s_addc_u32 s19, s17, -1
	s_add_i32 s44, 0, 0x10000
	s_cmp_eq_u32 s43, 12
	s_cselect_b32 s21, s9, s19
	s_cselect_b32 s20, s11, s18
	s_cselect_b32 s19, s13, s42
	s_cselect_b32 s18, s38, s39
	s_add_i32 s46, 0, 0x14000
	ds_read_b128 v[144:147], v252
	ds_read_b128 v[148:151], v252 offset:1024
	ds_read_b128 v[152:155], v252 offset:2048
	ds_read_b128 v[156:159], v252 offset:3072
	ds_read_b128 v[178:181], v253
	ds_read_b128 v[182:185], v253 offset:1024
	ds_read_b128 v[186:189], v253 offset:2048
	ds_read_b128 v[190:193], v253 offset:3072
	s_add_i32 m0, s28, 0xc000
	ds_read_b128 v[194:197], v143
	ds_read_b128 v[208:211], v143 offset:1024
	ds_read_b128 v[212:215], v143 offset:2048
	ds_read_b128 v[216:219], v143 offset:3072
	ds_read_b128 v[220:223], v143 offset:4096
	ds_read_b128 v[224:227], v143 offset:5120
	ds_read_b128 v[228:231], v143 offset:6144
	ds_read_b128 v[232:235], v143 offset:7168
	global_load_lds_dwordx4 v136, s[16:17]
	s_add_i32 m0, s28, 0xe000
	s_nop 0
	global_load_lds_dwordx4 v138, s[16:17]
	s_waitcnt vmcnt(8)
	s_waitcnt lgkmcnt(0)
	s_setprio 1
	s_barrier
	s_waitcnt lgkmcnt(0)
	v_mfma_f32_16x16x32_bf16 v[126:129], v[144:147], v[194:197], v[126:129]
	v_mfma_f32_16x16x32_bf16 v[122:125], v[152:155], v[194:197], v[122:125]
	v_mfma_f32_16x16x32_bf16 v[118:121], v[144:147], v[212:215], v[118:121]
	v_mfma_f32_16x16x32_bf16 v[114:117], v[152:155], v[212:215], v[114:117]
	v_mfma_f32_16x16x32_bf16 v[102:105], v[144:147], v[220:223], v[102:105]
	v_mfma_f32_16x16x32_bf16 v[98:101], v[152:155], v[220:223], v[98:101]
	v_mfma_f32_16x16x32_bf16 v[86:89], v[144:147], v[228:231], v[86:89]
	v_mfma_f32_16x16x32_bf16 v[82:85], v[152:155], v[228:231], v[82:85]
	s_setprio 0
	s_setprio 1
	v_mfma_f32_16x16x32_bf16 v[126:129], v[148:151], v[208:211], v[126:129]
	v_mfma_f32_16x16x32_bf16 v[122:125], v[156:159], v[208:211], v[122:125]
	v_mfma_f32_16x16x32_bf16 v[118:121], v[148:151], v[216:219], v[118:121]
	v_mfma_f32_16x16x32_bf16 v[114:117], v[156:159], v[216:219], v[114:117]
	v_mfma_f32_16x16x32_bf16 v[102:105], v[148:151], v[224:227], v[102:105]
	v_mfma_f32_16x16x32_bf16 v[98:101], v[156:159], v[224:227], v[98:101]
	v_mfma_f32_16x16x32_bf16 v[86:89], v[148:151], v[232:235], v[86:89]
	v_mfma_f32_16x16x32_bf16 v[82:85], v[156:159], v[232:235], v[82:85]
	s_setprio 0
	s_setprio 1
	v_mfma_f32_16x16x32_bf16 v[110:113], v[178:181], v[194:197], v[110:113]
	v_mfma_f32_16x16x32_bf16 v[106:109], v[186:189], v[194:197], v[106:109]
	v_mfma_f32_16x16x32_bf16 v[94:97], v[178:181], v[212:215], v[94:97]
	v_mfma_f32_16x16x32_bf16 v[90:93], v[186:189], v[212:215], v[90:93]
	v_mfma_f32_16x16x32_bf16 v[78:81], v[178:181], v[220:223], v[78:81]
	v_mfma_f32_16x16x32_bf16 v[74:77], v[186:189], v[220:223], v[74:77]
	v_mfma_f32_16x16x32_bf16 v[70:73], v[178:181], v[228:231], v[70:73]
	v_mfma_f32_16x16x32_bf16 v[66:69], v[186:189], v[228:231], v[66:69]
	s_setprio 0
	s_setprio 1
	v_mfma_f32_16x16x32_bf16 v[110:113], v[182:185], v[208:211], v[110:113]
	v_mfma_f32_16x16x32_bf16 v[106:109], v[190:193], v[208:211], v[106:109]
	v_mfma_f32_16x16x32_bf16 v[94:97], v[182:185], v[216:219], v[94:97]
	v_mfma_f32_16x16x32_bf16 v[90:93], v[190:193], v[216:219], v[90:93]
	v_mfma_f32_16x16x32_bf16 v[78:81], v[182:185], v[224:227], v[78:81]
	v_mfma_f32_16x16x32_bf16 v[74:77], v[190:193], v[224:227], v[74:77]
	v_mfma_f32_16x16x32_bf16 v[70:73], v[182:185], v[232:235], v[70:73]
	v_mfma_f32_16x16x32_bf16 v[66:69], v[190:193], v[232:235], v[66:69]
	s_setprio 0
	s_barrier
	s_add_i32 s44, s44, s25
	s_mov_b32 m0, s44
	ds_read_b128 v[194:197], v143 offset:16384
	ds_read_b128 v[208:211], v143 offset:17408
	ds_read_b128 v[212:215], v143 offset:18432
	ds_read_b128 v[216:219], v143 offset:19456
	ds_read_b128 v[220:223], v143 offset:20480
	ds_read_b128 v[224:227], v143 offset:21504
	ds_read_b128 v[228:231], v143 offset:22528
	ds_read_b128 v[232:235], v143 offset:23552
	global_load_lds_dwordx4 v64, s[18:19]
	s_add_i32 m0, s44, 0x2000
	s_add_u32 s44, s18, 0x200000
	s_addc_u32 s45, s19, 0
	s_add_i32 s46, s46, s25
	global_load_lds_dwordx4 v130, s[18:19]
	s_mov_b32 m0, s46
	s_mov_b64 s[100:101], s[20:21]
	global_load_lds_dwordx4 v64, s[44:45]
	s_add_i32 m0, s46, 0x2000
	s_nop 0
	global_load_lds_dwordx4 v130, s[44:45]
	s_mov_b32 m0, s28
	s_nop 0
	global_load_lds_dwordx4 v134, s[20:21]
	s_mov_b32 m0, s29
	s_nop 0
	global_load_lds_dwordx4 v132, s[20:21]
	s_waitcnt vmcnt(8)
	s_waitcnt lgkmcnt(0)
	s_setprio 1
	s_barrier
	s_waitcnt lgkmcnt(0)
	v_mfma_f32_16x16x32_bf16 v[60:63], v[144:147], v[194:197], v[60:63]
	v_mfma_f32_16x16x32_bf16 v[56:59], v[152:155], v[194:197], v[56:59]
	v_mfma_f32_16x16x32_bf16 v[52:55], v[144:147], v[212:215], v[52:55]
	v_mfma_f32_16x16x32_bf16 v[48:51], v[152:155], v[212:215], v[48:51]
	v_mfma_f32_16x16x32_bf16 v[36:39], v[144:147], v[220:223], v[36:39]
	v_mfma_f32_16x16x32_bf16 v[32:35], v[152:155], v[220:223], v[32:35]
	v_mfma_f32_16x16x32_bf16 v[20:23], v[144:147], v[228:231], v[20:23]
	v_mfma_f32_16x16x32_bf16 v[16:19], v[152:155], v[228:231], v[16:19]
	s_setprio 0
	s_setprio 1
	v_mfma_f32_16x16x32_bf16 v[60:63], v[148:151], v[208:211], v[60:63]
	v_mfma_f32_16x16x32_bf16 v[56:59], v[156:159], v[208:211], v[56:59]
	v_mfma_f32_16x16x32_bf16 v[52:55], v[148:151], v[216:219], v[52:55]
	v_mfma_f32_16x16x32_bf16 v[48:51], v[156:159], v[216:219], v[48:51]
	v_mfma_f32_16x16x32_bf16 v[36:39], v[148:151], v[224:227], v[36:39]
	v_mfma_f32_16x16x32_bf16 v[32:35], v[156:159], v[224:227], v[32:35]
	v_mfma_f32_16x16x32_bf16 v[20:23], v[148:151], v[232:235], v[20:23]
	v_mfma_f32_16x16x32_bf16 v[16:19], v[156:159], v[232:235], v[16:19]
	s_setprio 0
	s_setprio 1
	v_mfma_f32_16x16x32_bf16 v[44:47], v[178:181], v[194:197], v[44:47]
	v_mfma_f32_16x16x32_bf16 v[40:43], v[186:189], v[194:197], v[40:43]
	v_mfma_f32_16x16x32_bf16 v[28:31], v[178:181], v[212:215], v[28:31]
	v_mfma_f32_16x16x32_bf16 v[24:27], v[186:189], v[212:215], v[24:27]
	v_mfma_f32_16x16x32_bf16 v[12:15], v[178:181], v[220:223], v[12:15]
	v_mfma_f32_16x16x32_bf16 v[8:11], v[186:189], v[220:223], v[8:11]
	v_mfma_f32_16x16x32_bf16 v[4:7], v[178:181], v[228:231], v[4:7]
	v_mfma_f32_16x16x32_bf16 v[0:3], v[186:189], v[228:231], v[0:3]
	s_setprio 0
	s_setprio 1
	v_mfma_f32_16x16x32_bf16 v[44:47], v[182:185], v[208:211], v[44:47]
	v_mfma_f32_16x16x32_bf16 v[40:43], v[190:193], v[208:211], v[40:43]
	v_mfma_f32_16x16x32_bf16 v[28:31], v[182:185], v[216:219], v[28:31]
	v_mfma_f32_16x16x32_bf16 v[24:27], v[190:193], v[216:219], v[24:27]
	v_mfma_f32_16x16x32_bf16 v[12:15], v[182:185], v[224:227], v[12:15]
	v_mfma_f32_16x16x32_bf16 v[8:11], v[190:193], v[224:227], v[8:11]
	v_mfma_f32_16x16x32_bf16 v[4:7], v[182:185], v[232:235], v[4:7]
	v_mfma_f32_16x16x32_bf16 v[0:3], v[190:193], v[232:235], v[0:3]
	s_setprio 0
	s_barrier
; #define PG8_STAGE(bufoff, gbase, voff) do { _Pragma("unroll") for (int _i = 0; _i < 2; ++_i) \
;         __builtin_amdgcn_global_load_lds((const unsigned*)((const char*)(gbase) + (voff)[_i]), (PG8_LAS unsigned*)(lds + (bufoff) + ldsw + _i * 8192), 16, 0, 0); } while (0)
; #define PG8_LDA(dst, b, h) do { _Pragma("unroll") for (int m = 0; m < 4; ++m) _Pragma("unroll") for (int k = 0; k < 2; ++k) dst[m][k] = *(const PG8_LAS bf16x8*)(lds + PG8_SA(b, h) + aoff + m * 2048 + k * 1024); } while (0)
; #define PG8_LDB(dst, b, h) do { _Pragma("unroll") for (int n = 0; n < 2; ++n) _Pragma("unroll") for (int k = 0; k < 2; ++k) dst[n][k] = *(const PG8_LAS bf16x8*)(lds + PG8_SB(b, h) + boff + n * 2048 + k * 1024); } while (0)
; #define PG8_MMA(ai, bj, At, Bt) do { __builtin_amdgcn_s_setprio(1); _Pragma("unroll") for (int m = 0; m < 4; ++m) _Pragma("unroll") for (int n = 0; n < 2; ++n) _Pragma("unroll") for (int k = 0; k < 2; ++k) \
;         acc[ai][bj][m][n] = __builtin_amdgcn_mfma_f32_16x16x32_bf16(Bt[n][k], At[m][k], acc[ai][bj][m][n], 0, 0, 0); __builtin_amdgcn_s_setprio(0); } while (0)
; #define PG8_WAIT_V(n) asm volatile("s_waitcnt vmcnt(" #n ")" ::: "memory")
; #define PG8_WAIT_L(n) asm volatile("s_waitcnt lgkmcnt(" #n ")" ::: "memory")
; #define PG8_BAR __builtin_amdgcn_s_barrier()
; #define PG8_SCHED __builtin_amdgcn_sched_barrier(0)
; template <class Epi, class Sched, bool ALIGN_EPI = false, bool SP2 = false>
; __device__ __forceinline__ void gemm_phase(PG8_LAS unsigned char* lds, const Gemm g, const Sched& S, const Epi& E, const int wave0) {
;     ...
;             PG8_LDB(B0, 1, 0); PG8_LDB(B1, 1, 1); PG8_SCHED; PG8_LDA(At, 1, 0); PG8_STAGE(PG8_SA(0, 1), a2 + hstepA, voffA);
;             PG8_WAIT_V(8); PG8_WAIT_L(0); PG8_BAR; PG8_MMA(0, 0, At, B0); PG8_MMA(0, 1, At, B1); PG8_BAR; PG8_SCHED;
;             PG8_LDA(At, 1, 1); PG8_STAGE(PG8_SB(1, 0), b3, voffB); PG8_STAGE(PG8_SB(1, 1), b3 + hstepB, voffB); PG8_STAGE(PG8_SA(1, 0), a3, voffA);
;             PG8_WAIT_V(8); PG8_WAIT_L(0); PG8_BAR; PG8_MMA(1, 0, At, B0); PG8_MMA(1, 1, At, B1); PG8_BAR; PG8_SCHED;
	s_add_i32 s44, 0, 0x18000
	s_add_i32 s45, 0, 0x1c000
	ds_read_b128 v[144:147], v254
	ds_read_b128 v[148:151], v254 offset:1024
	ds_read_b128 v[152:155], v254 offset:2048
	ds_read_b128 v[156:159], v254 offset:3072
	ds_read_b128 v[178:181], v255
	ds_read_b128 v[182:185], v255 offset:1024
	ds_read_b128 v[186:189], v255 offset:2048
	ds_read_b128 v[190:193], v255 offset:3072
	s_add_u32 s20, s20, 0x200000
	s_addc_u32 s21, s21, 0
	s_mov_b32 m0, s30
	ds_read_b128 v[194:197], v143 offset:32768
	ds_read_b128 v[208:211], v143 offset:33792
	ds_read_b128 v[212:215], v143 offset:34816
	ds_read_b128 v[216:219], v143 offset:35840
	ds_read_b128 v[220:223], v143 offset:36864
	ds_read_b128 v[224:227], v143 offset:37888
	ds_read_b128 v[228:231], v143 offset:38912
	ds_read_b128 v[232:235], v143 offset:39936
	global_load_lds_dwordx4 v134, s[20:21]
	s_mov_b32 m0, s31
	s_nop 0
	global_load_lds_dwordx4 v132, s[20:21]
	s_waitcnt vmcnt(8)
	s_waitcnt lgkmcnt(0)
	s_setprio 1
	s_barrier
	s_waitcnt lgkmcnt(0)
	v_mfma_f32_16x16x32_bf16 v[126:129], v[144:147], v[194:197], v[126:129]
	v_mfma_f32_16x16x32_bf16 v[122:125], v[152:155], v[194:197], v[122:125]
	v_mfma_f32_16x16x32_bf16 v[118:121], v[144:147], v[212:215], v[118:121]
	v_mfma_f32_16x16x32_bf16 v[114:117], v[152:155], v[212:215], v[114:117]
	v_mfma_f32_16x16x32_bf16 v[102:105], v[144:147], v[220:223], v[102:105]
	v_mfma_f32_16x16x32_bf16 v[98:101], v[152:155], v[220:223], v[98:101]
	v_mfma_f32_16x16x32_bf16 v[86:89], v[144:147], v[228:231], v[86:89]
	v_mfma_f32_16x16x32_bf16 v[82:85], v[152:155], v[228:231], v[82:85]
	s_setprio 0
	s_setprio 1
	v_mfma_f32_16x16x32_bf16 v[126:129], v[148:151], v[208:211], v[126:129]
	v_mfma_f32_16x16x32_bf16 v[122:125], v[156:159], v[208:211], v[122:125]
	v_mfma_f32_16x16x32_bf16 v[118:121], v[148:151], v[216:219], v[118:121]
	v_mfma_f32_16x16x32_bf16 v[114:117], v[156:159], v[216:219], v[114:117]
	v_mfma_f32_16x16x32_bf16 v[102:105], v[148:151], v[224:227], v[102:105]
	v_mfma_f32_16x16x32_bf16 v[98:101], v[156:159], v[224:227], v[98:101]
	v_mfma_f32_16x16x32_bf16 v[86:89], v[148:151], v[232:235], v[86:89]
	v_mfma_f32_16x16x32_bf16 v[82:85], v[156:159], v[232:235], v[82:85]
	s_setprio 0
	s_setprio 1
	v_mfma_f32_16x16x32_bf16 v[110:113], v[178:181], v[194:197], v[110:113]
	v_mfma_f32_16x16x32_bf16 v[106:109], v[186:189], v[194:197], v[106:109]
	v_mfma_f32_16x16x32_bf16 v[94:97], v[178:181], v[212:215], v[94:97]
	v_mfma_f32_16x16x32_bf16 v[90:93], v[186:189], v[212:215], v[90:93]
	v_mfma_f32_16x16x32_bf16 v[78:81], v[178:181], v[220:223], v[78:81]
	v_mfma_f32_16x16x32_bf16 v[74:77], v[186:189], v[220:223], v[74:77]
	v_mfma_f32_16x16x32_bf16 v[70:73], v[178:181], v[228:231], v[70:73]
	v_mfma_f32_16x16x32_bf16 v[66:69], v[186:189], v[228:231], v[66:69]
	s_setprio 0
	s_setprio 1
	v_mfma_f32_16x16x32_bf16 v[110:113], v[182:185], v[208:211], v[110:113]
	v_mfma_f32_16x16x32_bf16 v[106:109], v[190:193], v[208:211], v[106:109]
	v_mfma_f32_16x16x32_bf16 v[94:97], v[182:185], v[216:219], v[94:97]
	v_mfma_f32_16x16x32_bf16 v[90:93], v[190:193], v[216:219], v[90:93]
	v_mfma_f32_16x16x32_bf16 v[78:81], v[182:185], v[224:227], v[78:81]
	v_mfma_f32_16x16x32_bf16 v[74:77], v[190:193], v[224:227], v[74:77]
	v_mfma_f32_16x16x32_bf16 v[70:73], v[182:185], v[232:235], v[70:73]
	v_mfma_f32_16x16x32_bf16 v[66:69], v[190:193], v[232:235], v[66:69]
	s_setprio 0
	s_barrier
	s_add_i32 s20, s44, s25
	s_add_u32 s48, s18, 0x80
	s_addc_u32 s49, s19, 0
	s_mov_b32 m0, s20
	ds_read_b128 v[194:197], v143 offset:49152
	ds_read_b128 v[208:211], v143 offset:50176
	ds_read_b128 v[212:215], v143 offset:51200
	ds_read_b128 v[216:219], v143 offset:52224
	ds_read_b128 v[220:223], v143 offset:53248
	ds_read_b128 v[224:227], v143 offset:54272
	ds_read_b128 v[228:231], v143 offset:55296
	ds_read_b128 v[232:235], v143 offset:56320
	global_load_lds_dwordx4 v64, s[48:49]
	s_add_i32 m0, s20, 0x2000
	s_add_u32 s18, s18, 0x200080
	s_addc_u32 s19, s19, 0
	s_add_i32 s20, s45, s25
	global_load_lds_dwordx4 v130, s[48:49]
	s_mov_b32 m0, s20
	s_nop 0
	global_load_lds_dwordx4 v64, s[18:19]
	s_add_i32 m0, s20, 0x2000
	s_nop 0
	global_load_lds_dwordx4 v130, s[18:19]
	s_add_u32 s100, s100, 0x80
	s_addc_u32 s101, s101, 0
	s_mov_b32 m0, s33
	s_nop 0
	global_load_lds_dwordx4 v134, s[100:101]
	s_mov_b32 m0, s34
	s_nop 0
	global_load_lds_dwordx4 v132, s[100:101]
	s_waitcnt vmcnt(8)
	s_waitcnt lgkmcnt(0)
	s_setprio 1
	s_barrier
	s_waitcnt lgkmcnt(0)
	v_mfma_f32_16x16x32_bf16 v[60:63], v[144:147], v[194:197], v[60:63]
	v_mfma_f32_16x16x32_bf16 v[56:59], v[152:155], v[194:197], v[56:59]
	v_mfma_f32_16x16x32_bf16 v[52:55], v[144:147], v[212:215], v[52:55]
	v_mfma_f32_16x16x32_bf16 v[48:51], v[152:155], v[212:215], v[48:51]
	v_mfma_f32_16x16x32_bf16 v[36:39], v[144:147], v[220:223], v[36:39]
	v_mfma_f32_16x16x32_bf16 v[32:35], v[152:155], v[220:223], v[32:35]
	v_mfma_f32_16x16x32_bf16 v[20:23], v[144:147], v[228:231], v[20:23]
	v_mfma_f32_16x16x32_bf16 v[16:19], v[152:155], v[228:231], v[16:19]
	s_setprio 0
	s_setprio 1
	v_mfma_f32_16x16x32_bf16 v[60:63], v[148:151], v[208:211], v[60:63]
	v_mfma_f32_16x16x32_bf16 v[56:59], v[156:159], v[208:211], v[56:59]
	v_mfma_f32_16x16x32_bf16 v[52:55], v[148:151], v[216:219], v[52:55]
	v_mfma_f32_16x16x32_bf16 v[48:51], v[156:159], v[216:219], v[48:51]
	v_mfma_f32_16x16x32_bf16 v[36:39], v[148:151], v[224:227], v[36:39]
	v_mfma_f32_16x16x32_bf16 v[32:35], v[156:159], v[224:227], v[32:35]
	v_mfma_f32_16x16x32_bf16 v[20:23], v[148:151], v[232:235], v[20:23]
	v_mfma_f32_16x16x32_bf16 v[16:19], v[156:159], v[232:235], v[16:19]
	s_setprio 0
	s_setprio 1
	v_mfma_f32_16x16x32_bf16 v[44:47], v[178:181], v[194:197], v[44:47]
	v_mfma_f32_16x16x32_bf16 v[40:43], v[186:189], v[194:197], v[40:43]
	v_mfma_f32_16x16x32_bf16 v[28:31], v[178:181], v[212:215], v[28:31]
	v_mfma_f32_16x16x32_bf16 v[24:27], v[186:189], v[212:215], v[24:27]
	v_mfma_f32_16x16x32_bf16 v[12:15], v[178:181], v[220:223], v[12:15]
	v_mfma_f32_16x16x32_bf16 v[8:11], v[186:189], v[220:223], v[8:11]
	v_mfma_f32_16x16x32_bf16 v[4:7], v[178:181], v[228:231], v[4:7]
	v_mfma_f32_16x16x32_bf16 v[0:3], v[186:189], v[228:231], v[0:3]
	s_setprio 0
	s_setprio 1
	v_mfma_f32_16x16x32_bf16 v[44:47], v[182:185], v[208:211], v[44:47]
	v_mfma_f32_16x16x32_bf16 v[40:43], v[190:193], v[208:211], v[40:43]
	v_mfma_f32_16x16x32_bf16 v[28:31], v[182:185], v[216:219], v[28:31]
	v_mfma_f32_16x16x32_bf16 v[24:27], v[190:193], v[216:219], v[24:27]
	v_mfma_f32_16x16x32_bf16 v[12:15], v[182:185], v[224:227], v[12:15]
	v_mfma_f32_16x16x32_bf16 v[8:11], v[190:193], v[224:227], v[8:11]
	v_mfma_f32_16x16x32_bf16 v[4:7], v[182:185], v[232:235], v[4:7]
	v_mfma_f32_16x16x32_bf16 v[0:3], v[190:193], v[232:235], v[0:3]
	s_setprio 0
	s_barrier
	s_add_i32 s43, s43, 2
	s_add_u32 s16, s16, 0x100
	s_addc_u32 s17, s17, 0
	s_add_u32 s39, s39, 0x100
	s_addc_u32 s42, s42, 0
	s_cmp_gt_u32 s43, 13
	s_cbranch_scc0 .LBB0_1702
	s_mov_b64 s[48:49], 0x80
	s_and_b64 vcc, exec, s[6:7]
	s_cbranch_vccz .LBB0_1705
	s_barrier
